# A/B: per-phase s_setprio flips removed from the five GEMM K-loops (replaced by s_nop 0)
# speedup vs baseline: 1.0108x; 1.0012x over previous
; #define G8_STAGE(bufoff, gbase) do { _Pragma("unroll") for (int _i = 0; _i < 2; ++_i) \
;     __builtin_amdgcn_global_load_lds((const unsigned*)((const char*)(gbase) + voffA[_i]), (LAS unsigned*)(lds + (bufoff) + ldsw + _i * 8192), 16, 0, 0); } while (0)
; #define G8_LDA(dst, b, h) do { _Pragma("unroll") for (int m = 0; m < 4; ++m) _Pragma("unroll") for (int k = 0; k < 2; ++k) dst[m][k] = *(const LAS h16x8*)(lds + G8_SA(b, h) + aoff + m * 2048 + k * 1024); } while (0)
; #define G8_LDB(dst, b, h) do { _Pragma("unroll") for (int n = 0; n < 2; ++n) _Pragma("unroll") for (int k = 0; k < 2; ++k) dst[n][k] = *(const LAS h16x8*)(lds + G8_SB(b, h) + boff + n * 2048 + k * 1024); } while (0)
; #define G8_MMA(ai, bj, At, Bt_) do { __builtin_amdgcn_s_setprio(1); _Pragma("unroll") for (int m = 0; m < 4; ++m) _Pragma("unroll") for (int n = 0; n < 2; ++n) _Pragma("unroll") for (int k = 0; k < 2; ++k) \
;     acc[ai][bj][m][n] = __builtin_amdgcn_mfma_f32_16x16x32_f16(Bt_[n][k], At[m][k], acc[ai][bj][m][n], 0, 0, 0); __builtin_amdgcn_s_setprio(0); } while (0)
; #define G8_WAIT_V(n) asm volatile("s_waitcnt vmcnt(" #n ")" ::: "memory")
; #define G8_WAIT_L(n) asm volatile("s_waitcnt lgkmcnt(" #n ")" ::: "memory")
; #define G8_BAR __builtin_amdgcn_s_barrier()
; #define G8_SCHED __builtin_amdgcn_sched_barrier(0)
; template <class Epi>
; __device__ __forceinline__ void gemm_phase(LAS unsigned char* lds, const h16* A, const h16* Bt, int K, const Order& S, const Epi& E) {
;     ...
;       G8_LDB(B0, 0, 0); G8_SCHED; G8_LDA(At, 0, 0); G8_STAGE(G8_SA(1, 1), a1 + hstep);
;       G8_WAIT_L(8); G8_BAR; G8_WAIT_L(0); G8_MMA(0, 0, At, B0); G8_BAR; G8_SCHED;
;       G8_LDB(B1, 0, 1); G8_STAGE(G8_SB(0, 0), b2);
;       G8_BAR; G8_WAIT_L(0); G8_MMA(0, 1, At, B1); G8_BAR;
;       G8_LDA(At, 0, 1); G8_STAGE(G8_SA(0, 0), a2);
;       G8_BAR; G8_WAIT_L(0); G8_MMA(1, 0, At, B0); G8_BAR; G8_SCHED;
;       G8_STAGE(G8_SB(0, 1), b2 + hstep);
;       G8_WAIT_V(6); G8_BAR; G8_MMA(1, 1, At, B1); G8_BAR;
;       G8_LDB(B0, 1, 0); G8_SCHED; G8_LDA(At, 1, 0); G8_STAGE(G8_SA(0, 1), a2 + hstep);
;       G8_WAIT_L(8); G8_BAR; G8_WAIT_L(0); G8_MMA(0, 0, At, B0); G8_BAR; G8_SCHED;
.LBB0_195:
	s_add_u32 s12, s10, 0xfffc0080
	s_addc_u32 s13, s11, -1
	s_cmp_eq_u32 s54, 12
	s_cselect_b32 s15, s19, s13
	s_cselect_b32 s14, s25, s12
	s_cselect_b32 s13, s17, s53
	s_cselect_b32 s12, s26, s27
	s_mov_b32 m0, s50
	v_lshl_add_u64 v[140:141], s[10:11], 0, v[136:137]
	ds_read_b128 v[202:205], v159
	ds_read_b128 v[206:209], v159 offset:1024
	ds_read_b128 v[210:213], v159 offset:2048
	ds_read_b128 v[214:217], v159 offset:3072
	ds_read_b128 v[218:221], v159 offset:4096
	ds_read_b128 v[222:225], v159 offset:5120
	ds_read_b128 v[226:229], v159 offset:6144
	ds_read_b128 v[230:233], v159 offset:7168
	global_load_lds_dwordx4 v[140:141], off
	v_lshl_add_u64 v[140:141], s[10:11], 0, v[138:139]
	s_mov_b32 m0, s51
	s_nop 0
	global_load_lds_dwordx4 v[140:141], off
	s_waitcnt lgkmcnt(8)
	s_barrier
	s_waitcnt lgkmcnt(0)
	s_nop 0
	s_waitcnt lgkmcnt(0)
	v_mfma_f32_16x16x32_f16 v[126:129], v[152:155], v[202:205], v[126:129]
	v_mfma_f32_16x16x32_f16 v[122:125], v[182:185], v[202:205], v[122:125]
	v_mfma_f32_16x16x32_f16 v[110:113], v[152:155], v[210:213], v[110:113]
	v_mfma_f32_16x16x32_f16 v[106:109], v[182:185], v[210:213], v[106:109]
	v_mfma_f32_16x16x32_f16 v[94:97], v[152:155], v[218:221], v[94:97]
	v_mfma_f32_16x16x32_f16 v[90:93], v[182:185], v[218:221], v[90:93]
	v_mfma_f32_16x16x32_f16 v[78:81], v[152:155], v[226:229], v[78:81]
	v_mfma_f32_16x16x32_f16 v[74:77], v[182:185], v[226:229], v[74:77]
	v_mfma_f32_16x16x32_f16 v[126:129], v[178:181], v[206:209], v[126:129]
	v_mfma_f32_16x16x32_f16 v[122:125], v[186:189], v[206:209], v[122:125]
	v_mfma_f32_16x16x32_f16 v[110:113], v[178:181], v[214:217], v[110:113]
	v_mfma_f32_16x16x32_f16 v[106:109], v[186:189], v[214:217], v[106:109]
	v_mfma_f32_16x16x32_f16 v[94:97], v[178:181], v[222:225], v[94:97]
	v_mfma_f32_16x16x32_f16 v[90:93], v[186:189], v[222:225], v[90:93]
	v_mfma_f32_16x16x32_f16 v[78:81], v[178:181], v[230:233], v[78:81]
	v_mfma_f32_16x16x32_f16 v[74:77], v[186:189], v[230:233], v[74:77]
	s_nop 0
	s_barrier
	s_mov_b32 m0, s36
	v_lshl_add_u64 v[140:141], s[12:13], 0, v[132:133]
	ds_read_b128 v[234:237], v165
	ds_read_b128 v[238:241], v166
	ds_read_b128 v[242:245], v167
	ds_read_b128 v[246:249], v168
	global_load_lds_dwordx4 v[140:141], off
	v_lshl_add_u64 v[156:157], s[12:13], 0, v[130:131]
	s_mov_b32 m0, s37
	s_nop 0
	global_load_lds_dwordx4 v[156:157], off
	s_barrier
	s_waitcnt lgkmcnt(0)
	s_nop 0
	s_waitcnt lgkmcnt(0)
	v_mfma_f32_16x16x32_f16 v[118:121], v[234:237], v[202:205], v[118:121]
	v_mfma_f32_16x16x32_f16 v[114:117], v[242:245], v[202:205], v[114:117]
	v_mfma_f32_16x16x32_f16 v[102:105], v[234:237], v[210:213], v[102:105]
	v_mfma_f32_16x16x32_f16 v[98:101], v[242:245], v[210:213], v[98:101]
	v_mfma_f32_16x16x32_f16 v[86:89], v[234:237], v[218:221], v[86:89]
	v_mfma_f32_16x16x32_f16 v[82:85], v[242:245], v[218:221], v[82:85]
	v_mfma_f32_16x16x32_f16 v[70:73], v[234:237], v[226:229], v[70:73]
	v_mfma_f32_16x16x32_f16 v[66:69], v[242:245], v[226:229], v[66:69]
	v_mfma_f32_16x16x32_f16 v[118:121], v[238:241], v[206:209], v[118:121]
	v_mfma_f32_16x16x32_f16 v[114:117], v[246:249], v[206:209], v[114:117]
	v_mfma_f32_16x16x32_f16 v[102:105], v[238:241], v[214:217], v[102:105]
	v_mfma_f32_16x16x32_f16 v[98:101], v[246:249], v[214:217], v[98:101]
	v_mfma_f32_16x16x32_f16 v[86:89], v[238:241], v[222:225], v[86:89]
	v_mfma_f32_16x16x32_f16 v[82:85], v[246:249], v[222:225], v[82:85]
	v_mfma_f32_16x16x32_f16 v[70:73], v[238:241], v[230:233], v[70:73]
	v_mfma_f32_16x16x32_f16 v[66:69], v[246:249], v[230:233], v[66:69]
	s_nop 0
	s_mov_b32 m0, s35
	v_lshl_add_u64 v[250:251], s[14:15], 0, v[132:133]
	s_barrier
	ds_read_b128 v[202:205], v159 offset:16384
	ds_read_b128 v[206:209], v159 offset:17408
	ds_read_b128 v[210:213], v159 offset:18432
	ds_read_b128 v[214:217], v159 offset:19456
	ds_read_b128 v[218:221], v159 offset:20480
	ds_read_b128 v[222:225], v159 offset:21504
	ds_read_b128 v[226:229], v159 offset:22528
	ds_read_b128 v[230:233], v159 offset:23552
	global_load_lds_dwordx4 v[250:251], off
	v_lshl_add_u64 v[252:253], s[14:15], 0, v[130:131]
	s_mov_b32 m0, s38
	s_nop 0
	global_load_lds_dwordx4 v[252:253], off
	s_waitcnt vmcnt(10)
	s_barrier
	s_waitcnt lgkmcnt(0)
	s_nop 0
	s_waitcnt lgkmcnt(0)
	v_mfma_f32_16x16x32_f16 v[62:65], v[152:155], v[202:205], v[62:65]
	v_mfma_f32_16x16x32_f16 v[58:61], v[182:185], v[202:205], v[58:61]
	v_mfma_f32_16x16x32_f16 v[46:49], v[152:155], v[210:213], v[46:49]
	v_mfma_f32_16x16x32_f16 v[42:45], v[182:185], v[210:213], v[42:45]
	v_mfma_f32_16x16x32_f16 v[30:33], v[152:155], v[218:221], v[30:33]
	v_mfma_f32_16x16x32_f16 v[26:29], v[182:185], v[218:221], v[26:29]
	v_mfma_f32_16x16x32_f16 v[14:17], v[152:155], v[226:229], v[14:17]
	v_mfma_f32_16x16x32_f16 v[10:13], v[182:185], v[226:229], v[10:13]
	v_mfma_f32_16x16x32_f16 v[62:65], v[178:181], v[206:209], v[62:65]
	v_mfma_f32_16x16x32_f16 v[58:61], v[186:189], v[206:209], v[58:61]
	v_mfma_f32_16x16x32_f16 v[46:49], v[178:181], v[214:217], v[46:49]
	v_mfma_f32_16x16x32_f16 v[42:45], v[186:189], v[214:217], v[42:45]
	v_mfma_f32_16x16x32_f16 v[30:33], v[178:181], v[222:225], v[30:33]
	v_mfma_f32_16x16x32_f16 v[26:29], v[186:189], v[222:225], v[26:29]
	v_mfma_f32_16x16x32_f16 v[14:17], v[178:181], v[230:233], v[14:17]
	v_mfma_f32_16x16x32_f16 v[10:13], v[186:189], v[230:233], v[10:13]
	s_nop 0
	s_barrier
	s_add_u32 s56, s12, 0x40000
	s_addc_u32 s57, s13, 0
	s_mov_b32 m0, s39
	v_lshl_add_u64 v[152:153], s[56:57], 0, v[132:133]
	global_load_lds_dwordx4 v[152:153], off
	v_lshl_add_u64 v[152:153], s[56:57], 0, v[130:131]
	s_mov_b32 m0, s40
	s_nop 0
	global_load_lds_dwordx4 v[152:153], off
	ds_read_b128 v[152:155], v169
	ds_read_b128 v[178:181], v170
	ds_read_b128 v[182:185], v171
	ds_read_b128 v[186:189], v172
	s_waitcnt vmcnt(6)
	s_barrier
; #define G8_STAGE(bufoff, gbase) do { _Pragma("unroll") for (int _i = 0; _i < 2; ++_i) \
;     __builtin_amdgcn_global_load_lds((const unsigned*)((const char*)(gbase) + voffA[_i]), (LAS unsigned*)(lds + (bufoff) + ldsw + _i * 8192), 16, 0, 0); } while (0)
; #define G8_LDA(dst, b, h) do { _Pragma("unroll") for (int m = 0; m < 4; ++m) _Pragma("unroll") for (int k = 0; k < 2; ++k) dst[m][k] = *(const LAS h16x8*)(lds + G8_SA(b, h) + aoff + m * 2048 + k * 1024); } while (0)
; #define G8_LDB(dst, b, h) do { _Pragma("unroll") for (int n = 0; n < 2; ++n) _Pragma("unroll") for (int k = 0; k < 2; ++k) dst[n][k] = *(const LAS h16x8*)(lds + G8_SB(b, h) + boff + n * 2048 + k * 1024); } while (0)
; #define G8_MMA(ai, bj, At, Bt_) do { __builtin_amdgcn_s_setprio(1); _Pragma("unroll") for (int m = 0; m < 4; ++m) _Pragma("unroll") for (int n = 0; n < 2; ++n) _Pragma("unroll") for (int k = 0; k < 2; ++k) \
;     acc[ai][bj][m][n] = __builtin_amdgcn_mfma_f32_16x16x32_f16(Bt_[n][k], At[m][k], acc[ai][bj][m][n], 0, 0, 0); __builtin_amdgcn_s_setprio(0); } while (0)
; #define G8_WAIT_V(n) asm volatile("s_waitcnt vmcnt(" #n ")" ::: "memory")
; #define G8_WAIT_L(n) asm volatile("s_waitcnt lgkmcnt(" #n ")" ::: "memory")
; #define G8_BAR __builtin_amdgcn_s_barrier()
; #define G8_SCHED __builtin_amdgcn_sched_barrier(0)
; template <class Epi>
; __device__ __forceinline__ void gemm_phase(LAS unsigned char* lds, const h16* A, const h16* Bt, int K, const Order& S, const Epi& E) {
;     ...
;       G8_LDA(At, 0, 1); G8_STAGE(G8_SA(0, 0), a2);
;       G8_BAR; G8_WAIT_L(0); G8_MMA(1, 0, At, B0); G8_BAR; G8_SCHED;
;       G8_STAGE(G8_SB(0, 1), b2 + hstep);
;       G8_WAIT_V(6); G8_BAR; G8_MMA(1, 1, At, B1); G8_BAR;
;       G8_LDB(B0, 1, 0); G8_SCHED; G8_LDA(At, 1, 0); G8_STAGE(G8_SA(0, 1), a2 + hstep);
;       G8_WAIT_L(8); G8_BAR; G8_WAIT_L(0); G8_MMA(0, 0, At, B0); G8_BAR; G8_SCHED;
;       G8_LDB(B1, 1, 1); G8_STAGE(G8_SB(1, 0), b3);
;       G8_BAR; G8_WAIT_L(0); G8_MMA(0, 1, At, B1); G8_BAR;
	s_nop 0
	v_mfma_f32_16x16x32_f16 v[54:57], v[234:237], v[202:205], v[54:57]
	v_mfma_f32_16x16x32_f16 v[50:53], v[242:245], v[202:205], v[50:53]
	v_mfma_f32_16x16x32_f16 v[38:41], v[234:237], v[210:213], v[38:41]
	v_mfma_f32_16x16x32_f16 v[34:37], v[242:245], v[210:213], v[34:37]
	v_mfma_f32_16x16x32_f16 v[22:25], v[234:237], v[218:221], v[22:25]
	v_mfma_f32_16x16x32_f16 v[18:21], v[242:245], v[218:221], v[18:21]
	v_mfma_f32_16x16x32_f16 v[6:9], v[234:237], v[226:229], v[6:9]
	v_mfma_f32_16x16x32_f16 v[2:5], v[242:245], v[226:229], v[2:5]
	v_mfma_f32_16x16x32_f16 v[54:57], v[238:241], v[206:209], v[54:57]
	v_mfma_f32_16x16x32_f16 v[50:53], v[246:249], v[206:209], v[50:53]
	v_mfma_f32_16x16x32_f16 v[38:41], v[238:241], v[214:217], v[38:41]
	v_mfma_f32_16x16x32_f16 v[34:37], v[246:249], v[214:217], v[34:37]
	v_mfma_f32_16x16x32_f16 v[22:25], v[238:241], v[222:225], v[22:25]
	v_mfma_f32_16x16x32_f16 v[18:21], v[246:249], v[222:225], v[18:21]
	v_mfma_f32_16x16x32_f16 v[6:9], v[238:241], v[230:233], v[6:9]
	v_mfma_f32_16x16x32_f16 v[2:5], v[246:249], v[230:233], v[2:5]
	s_nop 0
	s_barrier
	s_add_u32 s14, s14, 0x40000
	s_addc_u32 s15, s15, 0
	s_mov_b32 m0, s41
	v_lshl_add_u64 v[234:235], s[14:15], 0, v[132:133]
	ds_read_b128 v[202:205], v159 offset:32768
	ds_read_b128 v[206:209], v159 offset:33792
	ds_read_b128 v[210:213], v159 offset:34816
	ds_read_b128 v[214:217], v159 offset:35840
	ds_read_b128 v[218:221], v159 offset:36864
	ds_read_b128 v[222:225], v159 offset:37888
	ds_read_b128 v[226:229], v159 offset:38912
	ds_read_b128 v[230:233], v159 offset:39936
	global_load_lds_dwordx4 v[234:235], off
	v_lshl_add_u64 v[234:235], s[14:15], 0, v[130:131]
	s_mov_b32 m0, s42
	s_nop 0
	global_load_lds_dwordx4 v[234:235], off
	s_waitcnt lgkmcnt(8)
	s_barrier
	s_waitcnt lgkmcnt(0)
	s_nop 0
	s_waitcnt lgkmcnt(0)
	v_mfma_f32_16x16x32_f16 v[126:129], v[152:155], v[202:205], v[126:129]
	v_mfma_f32_16x16x32_f16 v[122:125], v[182:185], v[202:205], v[122:125]
	v_mfma_f32_16x16x32_f16 v[110:113], v[152:155], v[210:213], v[110:113]
	v_mfma_f32_16x16x32_f16 v[106:109], v[182:185], v[210:213], v[106:109]
	v_mfma_f32_16x16x32_f16 v[94:97], v[152:155], v[218:221], v[94:97]
	v_mfma_f32_16x16x32_f16 v[90:93], v[182:185], v[218:221], v[90:93]
	v_mfma_f32_16x16x32_f16 v[78:81], v[152:155], v[226:229], v[78:81]
	v_mfma_f32_16x16x32_f16 v[74:77], v[182:185], v[226:229], v[74:77]
	v_mfma_f32_16x16x32_f16 v[126:129], v[178:181], v[206:209], v[126:129]
	v_mfma_f32_16x16x32_f16 v[122:125], v[186:189], v[206:209], v[122:125]
	v_mfma_f32_16x16x32_f16 v[110:113], v[178:181], v[214:217], v[110:113]
	v_mfma_f32_16x16x32_f16 v[106:109], v[186:189], v[214:217], v[106:109]
	v_mfma_f32_16x16x32_f16 v[94:97], v[178:181], v[222:225], v[94:97]
	v_mfma_f32_16x16x32_f16 v[90:93], v[186:189], v[222:225], v[90:93]
	v_mfma_f32_16x16x32_f16 v[78:81], v[178:181], v[230:233], v[78:81]
	v_mfma_f32_16x16x32_f16 v[74:77], v[186:189], v[230:233], v[74:77]
	s_nop 0
	s_barrier
	s_mov_b32 m0, s44
	v_lshl_add_u64 v[140:141], v[140:141], 0, s[94:95]
	ds_read_b128 v[234:237], v173
	ds_read_b128 v[238:241], v174
	ds_read_b128 v[242:245], v175
	ds_read_b128 v[246:249], v176
	global_load_lds_dwordx4 v[140:141], off
	v_lshl_add_u64 v[140:141], v[156:157], 0, s[94:95]
	s_mov_b32 m0, s45
	s_nop 0
	global_load_lds_dwordx4 v[140:141], off
	s_barrier
	s_waitcnt lgkmcnt(0)
	s_nop 0
	s_waitcnt lgkmcnt(0)
	v_mfma_f32_16x16x32_f16 v[118:121], v[234:237], v[202:205], v[118:121]
	v_mfma_f32_16x16x32_f16 v[114:117], v[242:245], v[202:205], v[114:117]
	v_mfma_f32_16x16x32_f16 v[102:105], v[234:237], v[210:213], v[102:105]
	v_mfma_f32_16x16x32_f16 v[98:101], v[242:245], v[210:213], v[98:101]
	v_mfma_f32_16x16x32_f16 v[86:89], v[234:237], v[218:221], v[86:89]
	v_mfma_f32_16x16x32_f16 v[82:85], v[242:245], v[218:221], v[82:85]
	v_mfma_f32_16x16x32_f16 v[70:73], v[234:237], v[226:229], v[70:73]
	v_mfma_f32_16x16x32_f16 v[66:69], v[242:245], v[226:229], v[66:69]
	v_mfma_f32_16x16x32_f16 v[118:121], v[238:241], v[206:209], v[118:121]
	v_mfma_f32_16x16x32_f16 v[114:117], v[246:249], v[206:209], v[114:117]
	v_mfma_f32_16x16x32_f16 v[102:105], v[238:241], v[214:217], v[102:105]
	v_mfma_f32_16x16x32_f16 v[98:101], v[246:249], v[214:217], v[98:101]
	v_mfma_f32_16x16x32_f16 v[86:89], v[238:241], v[222:225], v[86:89]
	v_mfma_f32_16x16x32_f16 v[82:85], v[246:249], v[222:225], v[82:85]
	v_mfma_f32_16x16x32_f16 v[70:73], v[238:241], v[230:233], v[70:73]
	v_mfma_f32_16x16x32_f16 v[66:69], v[246:249], v[230:233], v[66:69]
	s_nop 0
	s_mov_b32 m0, s46
	v_lshl_add_u64 v[140:141], v[250:251], 0, s[94:95]
	s_barrier
; #define G8_STAGE(bufoff, gbase) do { _Pragma("unroll") for (int _i = 0; _i < 2; ++_i) \
;     __builtin_amdgcn_global_load_lds((const unsigned*)((const char*)(gbase) + voffA[_i]), (LAS unsigned*)(lds + (bufoff) + ldsw + _i * 8192), 16, 0, 0); } while (0)
; #define G8_LDA(dst, b, h) do { _Pragma("unroll") for (int m = 0; m < 4; ++m) _Pragma("unroll") for (int k = 0; k < 2; ++k) dst[m][k] = *(const LAS h16x8*)(lds + G8_SA(b, h) + aoff + m * 2048 + k * 1024); } while (0)
; #define G8_LDB(dst, b, h) do { _Pragma("unroll") for (int n = 0; n < 2; ++n) _Pragma("unroll") for (int k = 0; k < 2; ++k) dst[n][k] = *(const LAS h16x8*)(lds + G8_SB(b, h) + boff + n * 2048 + k * 1024); } while (0)
; #define G8_MMA(ai, bj, At, Bt_) do { __builtin_amdgcn_s_setprio(1); _Pragma("unroll") for (int m = 0; m < 4; ++m) _Pragma("unroll") for (int n = 0; n < 2; ++n) _Pragma("unroll") for (int k = 0; k < 2; ++k) \
;     acc[ai][bj][m][n] = __builtin_amdgcn_mfma_f32_16x16x32_f16(Bt_[n][k], At[m][k], acc[ai][bj][m][n], 0, 0, 0); __builtin_amdgcn_s_setprio(0); } while (0)
; #define G8_WAIT_V(n) asm volatile("s_waitcnt vmcnt(" #n ")" ::: "memory")
; #define G8_WAIT_L(n) asm volatile("s_waitcnt lgkmcnt(" #n ")" ::: "memory")
; #define G8_BAR __builtin_amdgcn_s_barrier()
; template <class Epi>
; __device__ __forceinline__ void gemm_phase(LAS unsigned char* lds, const h16* A, const h16* Bt, int K, const Order& S, const Epi& E) {
;     ...
;       G8_LDB(B0, 1, 0); G8_SCHED; G8_LDA(At, 1, 0); G8_STAGE(G8_SA(0, 1), a2 + hstep);
;       G8_WAIT_L(8); G8_BAR; G8_WAIT_L(0); G8_MMA(0, 0, At, B0); G8_BAR; G8_SCHED;
;       G8_LDB(B1, 1, 1); G8_STAGE(G8_SB(1, 0), b3);
;       G8_BAR; G8_WAIT_L(0); G8_MMA(0, 1, At, B1); G8_BAR;
;       G8_LDA(At, 1, 1); G8_STAGE(G8_SA(1, 0), a3);
;       G8_BAR; G8_WAIT_L(0); G8_MMA(1, 0, At, B0); G8_BAR; G8_SCHED;
;       G8_STAGE(G8_SB(1, 1), b3 + hstep);
;       G8_WAIT_V(6); G8_BAR; G8_MMA(1, 1, At, B1); G8_BAR;
;     }
;     E(acc, cur, ui, wr, wc, fr, fq);
;   __device__ __forceinline__ void operator()(const f32x4 (&acc)[2][2][4][2], const g8::Unit& u, int ui, int wr, int wc, int fr, int fq) const {
;     const int hs = u.pn * 4 + wc;
;     int gi = -1;
;     if (hs < 4) gi = 0; else if (hs < 6) gi = 1; else if (hs >= 16 && hs < 20) gi = 2; else if (hs == 22) gi = 4; else if (hs == 24) gi = 5;
;     const bool gate = (hs == 26);
	ds_read_b128 v[202:205], v159 offset:49152
	ds_read_b128 v[206:209], v159 offset:50176
	ds_read_b128 v[210:213], v159 offset:51200
	ds_read_b128 v[214:217], v159 offset:52224
	ds_read_b128 v[218:221], v159 offset:53248
	ds_read_b128 v[222:225], v159 offset:54272
	ds_read_b128 v[226:229], v159 offset:55296
	ds_read_b128 v[230:233], v159 offset:56320
	global_load_lds_dwordx4 v[140:141], off
	v_lshl_add_u64 v[140:141], v[252:253], 0, s[94:95]
	s_mov_b32 m0, s47
	s_nop 0
	global_load_lds_dwordx4 v[140:141], off
	s_waitcnt vmcnt(10)
	s_barrier
	s_waitcnt lgkmcnt(0)
	s_nop 0
	s_waitcnt lgkmcnt(0)
	v_mfma_f32_16x16x32_f16 v[62:65], v[152:155], v[202:205], v[62:65]
	v_mfma_f32_16x16x32_f16 v[58:61], v[182:185], v[202:205], v[58:61]
	v_mfma_f32_16x16x32_f16 v[46:49], v[152:155], v[210:213], v[46:49]
	v_mfma_f32_16x16x32_f16 v[42:45], v[182:185], v[210:213], v[42:45]
	v_mfma_f32_16x16x32_f16 v[30:33], v[152:155], v[218:221], v[30:33]
	v_mfma_f32_16x16x32_f16 v[26:29], v[182:185], v[218:221], v[26:29]
	v_mfma_f32_16x16x32_f16 v[14:17], v[152:155], v[226:229], v[14:17]
	v_mfma_f32_16x16x32_f16 v[10:13], v[182:185], v[226:229], v[10:13]
	v_mfma_f32_16x16x32_f16 v[62:65], v[178:181], v[206:209], v[62:65]
	v_mfma_f32_16x16x32_f16 v[58:61], v[186:189], v[206:209], v[58:61]
	v_mfma_f32_16x16x32_f16 v[46:49], v[178:181], v[214:217], v[46:49]
	v_mfma_f32_16x16x32_f16 v[42:45], v[186:189], v[214:217], v[42:45]
	v_mfma_f32_16x16x32_f16 v[30:33], v[178:181], v[222:225], v[30:33]
	v_mfma_f32_16x16x32_f16 v[26:29], v[186:189], v[222:225], v[26:29]
	v_mfma_f32_16x16x32_f16 v[14:17], v[178:181], v[230:233], v[14:17]
	v_mfma_f32_16x16x32_f16 v[10:13], v[186:189], v[230:233], v[10:13]
	s_nop 0
	s_barrier
	s_add_u32 s12, s12, 0x40080
	s_addc_u32 s13, s13, 0
	s_mov_b32 m0, s48
	v_lshl_add_u64 v[140:141], s[12:13], 0, v[132:133]
	global_load_lds_dwordx4 v[140:141], off
	v_lshl_add_u64 v[140:141], s[12:13], 0, v[130:131]
	s_mov_b32 m0, s49
	s_nop 0
	global_load_lds_dwordx4 v[140:141], off
	ds_read_b128 v[152:155], v161
	ds_read_b128 v[178:181], v162
	ds_read_b128 v[182:185], v163
	ds_read_b128 v[186:189], v164
	s_waitcnt vmcnt(6)
	s_barrier
	s_nop 0
	v_mfma_f32_16x16x32_f16 v[54:57], v[234:237], v[202:205], v[54:57]
	v_mfma_f32_16x16x32_f16 v[50:53], v[242:245], v[202:205], v[50:53]
	v_mfma_f32_16x16x32_f16 v[38:41], v[234:237], v[210:213], v[38:41]
	v_mfma_f32_16x16x32_f16 v[34:37], v[242:245], v[210:213], v[34:37]
	v_mfma_f32_16x16x32_f16 v[22:25], v[234:237], v[218:221], v[22:25]
	v_mfma_f32_16x16x32_f16 v[18:21], v[242:245], v[218:221], v[18:21]
	v_mfma_f32_16x16x32_f16 v[6:9], v[234:237], v[226:229], v[6:9]
	v_mfma_f32_16x16x32_f16 v[2:5], v[242:245], v[226:229], v[2:5]
	v_mfma_f32_16x16x32_f16 v[54:57], v[238:241], v[206:209], v[54:57]
	v_mfma_f32_16x16x32_f16 v[50:53], v[246:249], v[206:209], v[50:53]
	v_mfma_f32_16x16x32_f16 v[38:41], v[238:241], v[214:217], v[38:41]
	v_mfma_f32_16x16x32_f16 v[34:37], v[246:249], v[214:217], v[34:37]
	v_mfma_f32_16x16x32_f16 v[22:25], v[238:241], v[222:225], v[22:25]
	v_mfma_f32_16x16x32_f16 v[18:21], v[246:249], v[222:225], v[18:21]
	v_mfma_f32_16x16x32_f16 v[6:9], v[238:241], v[230:233], v[6:9]
	v_mfma_f32_16x16x32_f16 v[2:5], v[246:249], v[230:233], v[2:5]
	s_nop 0
	s_add_i32 s54, s54, 2
	s_add_u32 s10, s10, 0x100
	s_addc_u32 s11, s11, 0
	s_add_u32 s27, s27, 0x100
	s_addc_u32 s53, s53, 0
	s_cmp_gt_u32 s54, 13
	s_barrier
	s_cbranch_scc0 .LBB0_195
	s_waitcnt lgkmcnt(0)
	s_lshl_b32 s10, s24, 2
	s_or_b32 s19, s10, s43
	s_cmp_lt_i32 s19, 4
	s_cbranch_scc1 .LBB0_203
	s_cmp_lt_u32 s19, 6
	s_cbranch_scc1 .LBB0_204
	s_cmp_eq_u32 s24, 4
	s_cbranch_scc1 .LBB0_205
	s_cmp_lt_i32 s19, 24
	s_cbranch_scc1 .LBB0_206
	s_cmp_eq_u32 s19, 24
	s_mov_b64 s[10:11], -1
	s_cbranch_scc0 .LBB0_202
	s_mov_b64 s[10:11], 0

; #define G8_STAGE(bufoff, gbase) do { _Pragma("unroll") for (int _i = 0; _i < 2; ++_i) \
;     __builtin_amdgcn_global_load_lds((const unsigned*)((const char*)(gbase) + voffA[_i]), (LAS unsigned*)(lds + (bufoff) + ldsw + _i * 8192), 16, 0, 0); } while (0)
; #define G8_LDA(dst, b, h) do { _Pragma("unroll") for (int m = 0; m < 4; ++m) _Pragma("unroll") for (int k = 0; k < 2; ++k) dst[m][k] = *(const LAS h16x8*)(lds + G8_SA(b, h) + aoff + m * 2048 + k * 1024); } while (0)
; #define G8_LDB(dst, b, h) do { _Pragma("unroll") for (int n = 0; n < 2; ++n) _Pragma("unroll") for (int k = 0; k < 2; ++k) dst[n][k] = *(const LAS h16x8*)(lds + G8_SB(b, h) + boff + n * 2048 + k * 1024); } while (0)
; #define G8_MMA(ai, bj, At, Bt_) do { __builtin_amdgcn_s_setprio(1); _Pragma("unroll") for (int m = 0; m < 4; ++m) _Pragma("unroll") for (int n = 0; n < 2; ++n) _Pragma("unroll") for (int k = 0; k < 2; ++k) \
;     acc[ai][bj][m][n] = __builtin_amdgcn_mfma_f32_16x16x32_f16(Bt_[n][k], At[m][k], acc[ai][bj][m][n], 0, 0, 0); __builtin_amdgcn_s_setprio(0); } while (0)
; #define G8_WAIT_V(n) asm volatile("s_waitcnt vmcnt(" #n ")" ::: "memory")
; #define G8_WAIT_L(n) asm volatile("s_waitcnt lgkmcnt(" #n ")" ::: "memory")
; #define G8_BAR __builtin_amdgcn_s_barrier()
; #define G8_SCHED __builtin_amdgcn_sched_barrier(0)
; template <class Epi>
; __device__ __forceinline__ void gemm_phase(LAS unsigned char* lds, const h16* A, const h16* Bt, int K, const Order& S, const Epi& E) {
;     ...
;       G8_LDB(B0, 0, 0); G8_SCHED; G8_LDA(At, 0, 0); G8_STAGE(G8_SA(1, 1), a1 + hstep);
;       G8_WAIT_L(8); G8_BAR; G8_WAIT_L(0); G8_MMA(0, 0, At, B0); G8_BAR; G8_SCHED;
;       G8_LDB(B1, 0, 1); G8_STAGE(G8_SB(0, 0), b2);
;       G8_BAR; G8_WAIT_L(0); G8_MMA(0, 1, At, B1); G8_BAR;
;       G8_LDA(At, 0, 1); G8_STAGE(G8_SA(0, 0), a2);
;       G8_BAR; G8_WAIT_L(0); G8_MMA(1, 0, At, B0); G8_BAR; G8_SCHED;
;       G8_STAGE(G8_SB(0, 1), b2 + hstep);
;       G8_WAIT_V(6); G8_BAR; G8_MMA(1, 1, At, B1); G8_BAR;
.LBB0_2284:
	v_or_b32_e32 v34, 0x10000, v171
	v_add_u32_e32 v46, 0x10400, v171
	v_add_u32_e32 v50, 0x10800, v171
	v_add_u32_e32 v160, 0x10c00, v171
	ds_read_b128 v[34:37], v34
	ds_read_b128 v[46:49], v46
	ds_read_b128 v[50:53], v50
	ds_read_b128 v[160:163], v160
	s_add_u32 s26, s24, 0xfffe0080
	s_addc_u32 s27, s25, -1
	s_cmp_eq_u32 s55, 4
	s_cselect_b32 s29, s3, s27
	s_cselect_b32 s28, s17, s26
	s_cselect_b32 s27, s15, s54
	s_cselect_b32 s26, s23, s53
	v_lshl_add_u64 v[168:169], s[24:25], 0, v[156:157]
	s_add_i32 m0, s37, 0xc000
	ds_read_b128 v[164:167], v170
	ds_read_b128 v[174:177], v170 offset:1024
	ds_read_b128 v[178:181], v170 offset:2048
	ds_read_b128 v[182:185], v170 offset:3072
	ds_read_b128 v[186:189], v170 offset:4096
	ds_read_b128 v[202:205], v170 offset:5120
	ds_read_b128 v[206:209], v170 offset:6144
	ds_read_b128 v[210:213], v170 offset:7168
	global_load_lds_dwordx4 v[168:169], off
	v_lshl_add_u64 v[168:169], s[24:25], 0, v[158:159]
	s_add_i32 m0, s37, 0xe000
	s_nop 0
	global_load_lds_dwordx4 v[168:169], off
	s_waitcnt lgkmcnt(8)
	s_barrier
	s_waitcnt lgkmcnt(0)
	s_nop 0
	s_waitcnt lgkmcnt(0)
	v_mfma_f32_16x16x32_f16 v[62:65], v[34:37], v[164:167], v[62:65]
	v_mfma_f32_16x16x32_f16 v[138:141], v[50:53], v[164:167], v[138:141]
	v_mfma_f32_16x16x32_f16 v[122:125], v[34:37], v[178:181], v[122:125]
	v_mfma_f32_16x16x32_f16 v[126:129], v[50:53], v[178:181], v[126:129]
	v_mfma_f32_16x16x32_f16 v[106:109], v[34:37], v[186:189], v[106:109]
	v_mfma_f32_16x16x32_f16 v[110:113], v[50:53], v[186:189], v[110:113]
	v_mfma_f32_16x16x32_f16 v[90:93], v[34:37], v[206:209], v[90:93]
	v_mfma_f32_16x16x32_f16 v[94:97], v[50:53], v[206:209], v[94:97]
	v_mfma_f32_16x16x32_f16 v[62:65], v[46:49], v[174:177], v[62:65]
	v_mfma_f32_16x16x32_f16 v[138:141], v[160:163], v[174:177], v[138:141]
	v_mfma_f32_16x16x32_f16 v[122:125], v[46:49], v[182:185], v[122:125]
	v_mfma_f32_16x16x32_f16 v[126:129], v[160:163], v[182:185], v[126:129]
	v_mfma_f32_16x16x32_f16 v[106:109], v[46:49], v[202:205], v[106:109]
	v_mfma_f32_16x16x32_f16 v[110:113], v[160:163], v[202:205], v[110:113]
	v_mfma_f32_16x16x32_f16 v[90:93], v[46:49], v[210:213], v[90:93]
	v_mfma_f32_16x16x32_f16 v[94:97], v[160:163], v[210:213], v[94:97]
	s_nop 0
	s_barrier
	v_or_b32_e32 v168, 0x14000, v171
	v_add_u32_e32 v169, 0x14400, v171
	ds_read_b128 v[214:217], v168
	ds_read_b128 v[218:221], v169
	v_add_u32_e32 v168, 0x14800, v171
	v_add_u32_e32 v169, 0x14c00, v171
	s_mov_b32 m0, s38
	ds_read_b128 v[222:225], v168
	ds_read_b128 v[226:229], v169
	v_lshl_add_u64 v[168:169], s[26:27], 0, v[0:1]
	global_load_lds_dwordx4 v[168:169], off
	v_lshl_add_u64 v[230:231], s[26:27], 0, v[152:153]
	s_mov_b32 m0, s39
	s_nop 0
	global_load_lds_dwordx4 v[230:231], off
	s_barrier
	s_waitcnt lgkmcnt(0)
	s_nop 0
	s_waitcnt lgkmcnt(0)
	v_mfma_f32_16x16x32_f16 v[130:133], v[214:217], v[164:167], v[130:133]
	v_mfma_f32_16x16x32_f16 v[134:137], v[222:225], v[164:167], v[134:137]
	v_mfma_f32_16x16x32_f16 v[114:117], v[214:217], v[178:181], v[114:117]
	v_mfma_f32_16x16x32_f16 v[118:121], v[222:225], v[178:181], v[118:121]
	v_mfma_f32_16x16x32_f16 v[98:101], v[214:217], v[186:189], v[98:101]
	v_mfma_f32_16x16x32_f16 v[102:105], v[222:225], v[186:189], v[102:105]
	v_mfma_f32_16x16x32_f16 v[82:85], v[214:217], v[206:209], v[82:85]
	v_mfma_f32_16x16x32_f16 v[86:89], v[222:225], v[206:209], v[86:89]
	v_mfma_f32_16x16x32_f16 v[130:133], v[218:221], v[174:177], v[130:133]
	v_mfma_f32_16x16x32_f16 v[134:137], v[226:229], v[174:177], v[134:137]
	v_mfma_f32_16x16x32_f16 v[114:117], v[218:221], v[182:185], v[114:117]
	v_mfma_f32_16x16x32_f16 v[118:121], v[226:229], v[182:185], v[118:121]
	v_mfma_f32_16x16x32_f16 v[98:101], v[218:221], v[202:205], v[98:101]
	v_mfma_f32_16x16x32_f16 v[102:105], v[226:229], v[202:205], v[102:105]
	v_mfma_f32_16x16x32_f16 v[82:85], v[218:221], v[210:213], v[82:85]
	v_mfma_f32_16x16x32_f16 v[86:89], v[226:229], v[210:213], v[86:89]
	s_nop 0
	s_mov_b32 m0, s37
	v_lshl_add_u64 v[232:233], s[28:29], 0, v[0:1]
	s_barrier
	ds_read_b128 v[164:167], v170 offset:16384
	ds_read_b128 v[174:177], v170 offset:17408
	ds_read_b128 v[178:181], v170 offset:18432
	ds_read_b128 v[182:185], v170 offset:19456
	ds_read_b128 v[186:189], v170 offset:20480
	ds_read_b128 v[202:205], v170 offset:21504
	ds_read_b128 v[206:209], v170 offset:22528
	ds_read_b128 v[210:213], v170 offset:23552
	global_load_lds_dwordx4 v[232:233], off
	v_lshl_add_u64 v[234:235], s[28:29], 0, v[152:153]
	s_mov_b32 m0, s40
	s_nop 0
	global_load_lds_dwordx4 v[234:235], off
	s_barrier
	s_waitcnt lgkmcnt(0)
	s_nop 0
	s_waitcnt lgkmcnt(0)
	v_mfma_f32_16x16x32_f16 v[74:77], v[34:37], v[164:167], v[74:77]
	v_mfma_f32_16x16x32_f16 v[78:81], v[50:53], v[164:167], v[78:81]
	v_mfma_f32_16x16x32_f16 v[54:57], v[34:37], v[178:181], v[54:57]
	v_mfma_f32_16x16x32_f16 v[58:61], v[50:53], v[178:181], v[58:61]
	v_mfma_f32_16x16x32_f16 v[26:29], v[34:37], v[186:189], v[26:29]
	v_mfma_f32_16x16x32_f16 v[30:33], v[50:53], v[186:189], v[30:33]
	v_mfma_f32_16x16x32_f16 v[10:13], v[34:37], v[206:209], v[10:13]
	v_mfma_f32_16x16x32_f16 v[14:17], v[50:53], v[206:209], v[14:17]
	v_mfma_f32_16x16x32_f16 v[74:77], v[46:49], v[174:177], v[74:77]
	v_mfma_f32_16x16x32_f16 v[78:81], v[160:163], v[174:177], v[78:81]
	v_mfma_f32_16x16x32_f16 v[54:57], v[46:49], v[182:185], v[54:57]
	v_mfma_f32_16x16x32_f16 v[58:61], v[160:163], v[182:185], v[58:61]
	v_mfma_f32_16x16x32_f16 v[26:29], v[46:49], v[202:205], v[26:29]
	v_mfma_f32_16x16x32_f16 v[30:33], v[160:163], v[202:205], v[30:33]
	v_mfma_f32_16x16x32_f16 v[10:13], v[46:49], v[210:213], v[10:13]
	v_mfma_f32_16x16x32_f16 v[14:17], v[160:163], v[210:213], v[14:17]
	s_nop 0
	s_barrier
; #define G8_STAGE(bufoff, gbase) do { _Pragma("unroll") for (int _i = 0; _i < 2; ++_i) \
;     __builtin_amdgcn_global_load_lds((const unsigned*)((const char*)(gbase) + voffA[_i]), (LAS unsigned*)(lds + (bufoff) + ldsw + _i * 8192), 16, 0, 0); } while (0)
; #define G8_LDA(dst, b, h) do { _Pragma("unroll") for (int m = 0; m < 4; ++m) _Pragma("unroll") for (int k = 0; k < 2; ++k) dst[m][k] = *(const LAS h16x8*)(lds + G8_SA(b, h) + aoff + m * 2048 + k * 1024); } while (0)
; #define G8_LDB(dst, b, h) do { _Pragma("unroll") for (int n = 0; n < 2; ++n) _Pragma("unroll") for (int k = 0; k < 2; ++k) dst[n][k] = *(const LAS h16x8*)(lds + G8_SB(b, h) + boff + n * 2048 + k * 1024); } while (0)
; #define G8_MMA(ai, bj, At, Bt_) do { __builtin_amdgcn_s_setprio(1); _Pragma("unroll") for (int m = 0; m < 4; ++m) _Pragma("unroll") for (int n = 0; n < 2; ++n) _Pragma("unroll") for (int k = 0; k < 2; ++k) \
;     acc[ai][bj][m][n] = __builtin_amdgcn_mfma_f32_16x16x32_f16(Bt_[n][k], At[m][k], acc[ai][bj][m][n], 0, 0, 0); __builtin_amdgcn_s_setprio(0); } while (0)
; #define G8_WAIT_V(n) asm volatile("s_waitcnt vmcnt(" #n ")" ::: "memory")
; #define G8_WAIT_L(n) asm volatile("s_waitcnt lgkmcnt(" #n ")" ::: "memory")
; #define G8_BAR __builtin_amdgcn_s_barrier()
; #define G8_SCHED __builtin_amdgcn_sched_barrier(0)
; template <class Epi>
; __device__ __forceinline__ void gemm_phase(LAS unsigned char* lds, const h16* A, const h16* Bt, int K, const Order& S, const Epi& E) {
;     ...
;       G8_LDA(At, 0, 1); G8_STAGE(G8_SA(0, 0), a2);
;       G8_BAR; G8_WAIT_L(0); G8_MMA(1, 0, At, B0); G8_BAR; G8_SCHED;
;       G8_STAGE(G8_SB(0, 1), b2 + hstep);
;       G8_WAIT_V(6); G8_BAR; G8_MMA(1, 1, At, B1); G8_BAR;
;       G8_LDB(B0, 1, 0); G8_SCHED; G8_LDA(At, 1, 0); G8_STAGE(G8_SA(0, 1), a2 + hstep);
;       G8_WAIT_L(8); G8_BAR; G8_WAIT_L(0); G8_MMA(0, 0, At, B0); G8_BAR; G8_SCHED;
;       G8_LDB(B1, 1, 1); G8_STAGE(G8_SB(1, 0), b3);
;       G8_BAR; G8_WAIT_L(0); G8_MMA(0, 1, At, B1); G8_BAR;
;       G8_LDA(At, 1, 1); G8_STAGE(G8_SA(1, 0), a3);
;       G8_BAR; G8_WAIT_L(0); G8_MMA(1, 0, At, B0); G8_BAR; G8_SCHED;
	s_add_u32 s56, s26, 0x20000
	s_addc_u32 s57, s27, 0
	s_mov_b32 m0, s41
	v_lshl_add_u64 v[34:35], s[56:57], 0, v[0:1]
	global_load_lds_dwordx4 v[34:35], off
	v_lshl_add_u64 v[34:35], s[56:57], 0, v[152:153]
	s_mov_b32 m0, s42
	s_nop 0
	global_load_lds_dwordx4 v[34:35], off
	s_waitcnt vmcnt(6)
	s_barrier
	s_nop 0
	v_mfma_f32_16x16x32_f16 v[38:41], v[214:217], v[178:181], v[38:41]
	v_mfma_f32_16x16x32_f16 v[42:45], v[222:225], v[178:181], v[42:45]
	v_mfma_f32_16x16x32_f16 v[18:21], v[214:217], v[186:189], v[18:21]
	v_mfma_f32_16x16x32_f16 v[22:25], v[222:225], v[186:189], v[22:25]
	v_mfma_f32_16x16x32_f16 v[2:5], v[214:217], v[206:209], v[2:5]
	v_mfma_f32_16x16x32_f16 v[6:9], v[222:225], v[206:209], v[6:9]
	v_mfma_f32_16x16x32_f16 v[34:37], v[214:217], v[164:167], v[66:69]
	v_mfma_f32_16x16x32_f16 v[46:49], v[222:225], v[164:167], v[70:73]
	v_mfma_f32_16x16x32_f16 v[38:41], v[218:221], v[182:185], v[38:41]
	v_mfma_f32_16x16x32_f16 v[42:45], v[226:229], v[182:185], v[42:45]
	v_mfma_f32_16x16x32_f16 v[18:21], v[218:221], v[202:205], v[18:21]
	v_mfma_f32_16x16x32_f16 v[22:25], v[226:229], v[202:205], v[22:25]
	v_mfma_f32_16x16x32_f16 v[2:5], v[218:221], v[210:213], v[2:5]
	v_mfma_f32_16x16x32_f16 v[6:9], v[226:229], v[210:213], v[6:9]
	v_mfma_f32_16x16x32_f16 v[34:37], v[218:221], v[174:177], v[34:37]
	v_mfma_f32_16x16x32_f16 v[46:49], v[226:229], v[174:177], v[46:49]
	s_nop 0
	v_or_b32_e32 v50, 0x18000, v171
	v_add_u32_e32 v66, 0x18400, v171
	v_add_u32_e32 v70, 0x18800, v171
	v_add_u32_e32 v160, 0x18c00, v171
	s_barrier
	ds_read_b128 v[50:53], v50
	ds_read_b128 v[66:69], v66
	ds_read_b128 v[70:73], v70
	ds_read_b128 v[160:163], v160
	s_add_u32 s28, s28, 0x20000
	s_addc_u32 s29, s29, 0
	s_mov_b32 m0, s43
	v_lshl_add_u64 v[214:215], s[28:29], 0, v[0:1]
	ds_read_b128 v[164:167], v170 offset:32768
	ds_read_b128 v[174:177], v170 offset:33792
	ds_read_b128 v[178:181], v170 offset:34816
	ds_read_b128 v[182:185], v170 offset:35840
	ds_read_b128 v[186:189], v170 offset:36864
	ds_read_b128 v[202:205], v170 offset:37888
	ds_read_b128 v[206:209], v170 offset:38912
	ds_read_b128 v[210:213], v170 offset:39936
	global_load_lds_dwordx4 v[214:215], off
	v_lshl_add_u64 v[214:215], s[28:29], 0, v[152:153]
	s_mov_b32 m0, s44
	s_nop 0
	global_load_lds_dwordx4 v[214:215], off
	s_waitcnt lgkmcnt(8)
	s_barrier
	s_waitcnt lgkmcnt(0)
	s_nop 0
	s_waitcnt lgkmcnt(0)
	v_mfma_f32_16x16x32_f16 v[62:65], v[50:53], v[164:167], v[62:65]
	v_mfma_f32_16x16x32_f16 v[138:141], v[70:73], v[164:167], v[138:141]
	v_mfma_f32_16x16x32_f16 v[122:125], v[50:53], v[178:181], v[122:125]
	v_mfma_f32_16x16x32_f16 v[126:129], v[70:73], v[178:181], v[126:129]
	v_mfma_f32_16x16x32_f16 v[106:109], v[50:53], v[186:189], v[106:109]
	v_mfma_f32_16x16x32_f16 v[110:113], v[70:73], v[186:189], v[110:113]
	v_mfma_f32_16x16x32_f16 v[90:93], v[50:53], v[206:209], v[90:93]
	v_mfma_f32_16x16x32_f16 v[94:97], v[70:73], v[206:209], v[94:97]
	v_mfma_f32_16x16x32_f16 v[62:65], v[66:69], v[174:177], v[62:65]
	v_mfma_f32_16x16x32_f16 v[138:141], v[160:163], v[174:177], v[138:141]
	v_mfma_f32_16x16x32_f16 v[122:125], v[66:69], v[182:185], v[122:125]
	v_mfma_f32_16x16x32_f16 v[126:129], v[160:163], v[182:185], v[126:129]
	v_mfma_f32_16x16x32_f16 v[106:109], v[66:69], v[202:205], v[106:109]
	v_mfma_f32_16x16x32_f16 v[110:113], v[160:163], v[202:205], v[110:113]
	v_mfma_f32_16x16x32_f16 v[90:93], v[66:69], v[210:213], v[90:93]
	v_mfma_f32_16x16x32_f16 v[94:97], v[160:163], v[210:213], v[94:97]
	s_nop 0
	s_barrier
	v_or_b32_e32 v173, 0x1c000, v171
	s_mov_b32 m0, s46
	v_add_u32_e32 v195, 0x1c400, v171
	ds_read_b128 v[214:217], v173
	ds_read_b128 v[218:221], v195
	v_add_u32_e32 v173, 0x1c800, v171
	v_lshl_add_u64 v[168:169], v[168:169], 0, s[94:95]
	v_add_u32_e32 v195, 0x1cc00, v171
	ds_read_b128 v[222:225], v173
	ds_read_b128 v[226:229], v195
	global_load_lds_dwordx4 v[168:169], off
	v_lshl_add_u64 v[168:169], v[230:231], 0, s[94:95]
	s_mov_b32 m0, s47
	s_nop 0
	global_load_lds_dwordx4 v[168:169], off
	s_barrier
	s_waitcnt lgkmcnt(0)
	s_nop 0
	s_waitcnt lgkmcnt(0)
	v_mfma_f32_16x16x32_f16 v[130:133], v[214:217], v[164:167], v[130:133]
	v_mfma_f32_16x16x32_f16 v[134:137], v[222:225], v[164:167], v[134:137]
	v_mfma_f32_16x16x32_f16 v[114:117], v[214:217], v[178:181], v[114:117]
	v_mfma_f32_16x16x32_f16 v[118:121], v[222:225], v[178:181], v[118:121]
	v_mfma_f32_16x16x32_f16 v[98:101], v[214:217], v[186:189], v[98:101]
	v_mfma_f32_16x16x32_f16 v[102:105], v[222:225], v[186:189], v[102:105]
	v_mfma_f32_16x16x32_f16 v[82:85], v[214:217], v[206:209], v[82:85]
	v_mfma_f32_16x16x32_f16 v[86:89], v[222:225], v[206:209], v[86:89]
	v_mfma_f32_16x16x32_f16 v[130:133], v[218:221], v[174:177], v[130:133]
	v_mfma_f32_16x16x32_f16 v[134:137], v[226:229], v[174:177], v[134:137]
	v_mfma_f32_16x16x32_f16 v[114:117], v[218:221], v[182:185], v[114:117]
	v_mfma_f32_16x16x32_f16 v[118:121], v[226:229], v[182:185], v[118:121]
	v_mfma_f32_16x16x32_f16 v[98:101], v[218:221], v[202:205], v[98:101]
	v_mfma_f32_16x16x32_f16 v[102:105], v[226:229], v[202:205], v[102:105]
	v_mfma_f32_16x16x32_f16 v[82:85], v[218:221], v[210:213], v[82:85]
	v_mfma_f32_16x16x32_f16 v[86:89], v[226:229], v[210:213], v[86:89]
	s_nop 0
	s_mov_b32 m0, s48
	v_lshl_add_u64 v[168:169], v[232:233], 0, s[94:95]
	s_barrier
	ds_read_b128 v[164:167], v170 offset:49152
	ds_read_b128 v[174:177], v170 offset:50176
	ds_read_b128 v[178:181], v170 offset:51200
	ds_read_b128 v[182:185], v170 offset:52224
	ds_read_b128 v[186:189], v170 offset:53248
	ds_read_b128 v[202:205], v170 offset:54272
	ds_read_b128 v[206:209], v170 offset:55296
	ds_read_b128 v[210:213], v170 offset:56320
	global_load_lds_dwordx4 v[168:169], off
	v_lshl_add_u64 v[168:169], v[234:235], 0, s[94:95]
	s_mov_b32 m0, s49
	s_nop 0
	global_load_lds_dwordx4 v[168:169], off
	s_barrier
; #define G8_STAGE(bufoff, gbase) do { _Pragma("unroll") for (int _i = 0; _i < 2; ++_i) \
;     __builtin_amdgcn_global_load_lds((const unsigned*)((const char*)(gbase) + voffA[_i]), (LAS unsigned*)(lds + (bufoff) + ldsw + _i * 8192), 16, 0, 0); } while (0)
; #define G8_LDA(dst, b, h) do { _Pragma("unroll") for (int m = 0; m < 4; ++m) _Pragma("unroll") for (int k = 0; k < 2; ++k) dst[m][k] = *(const LAS h16x8*)(lds + G8_SA(b, h) + aoff + m * 2048 + k * 1024); } while (0)
; #define G8_LDB(dst, b, h) do { _Pragma("unroll") for (int n = 0; n < 2; ++n) _Pragma("unroll") for (int k = 0; k < 2; ++k) dst[n][k] = *(const LAS h16x8*)(lds + G8_SB(b, h) + boff + n * 2048 + k * 1024); } while (0)
; #define G8_MMA(ai, bj, At, Bt_) do { __builtin_amdgcn_s_setprio(1); _Pragma("unroll") for (int m = 0; m < 4; ++m) _Pragma("unroll") for (int n = 0; n < 2; ++n) _Pragma("unroll") for (int k = 0; k < 2; ++k) \
;     acc[ai][bj][m][n] = __builtin_amdgcn_mfma_f32_16x16x32_f16(Bt_[n][k], At[m][k], acc[ai][bj][m][n], 0, 0, 0); __builtin_amdgcn_s_setprio(0); } while (0)
; #define G8_WAIT_V(n) asm volatile("s_waitcnt vmcnt(" #n ")" ::: "memory")
; #define G8_WAIT_L(n) asm volatile("s_waitcnt lgkmcnt(" #n ")" ::: "memory")
; #define G8_BAR __builtin_amdgcn_s_barrier()
; #define G8_SCHED __builtin_amdgcn_sched_barrier(0)
; template <class Epi>
; __device__ __forceinline__ void gemm_phase(LAS unsigned char* lds, const h16* A, const h16* Bt, int K, const Order& S, const Epi& E) {
;     ...
;       G8_WAIT_L(8); G8_BAR; G8_WAIT_L(0); G8_MMA(0, 0, At, B0); G8_BAR; G8_SCHED;
;       G8_LDB(B1, 1, 1); G8_STAGE(G8_SB(1, 0), b3);
;       G8_BAR; G8_WAIT_L(0); G8_MMA(0, 1, At, B1); G8_BAR;
;       G8_LDA(At, 1, 1); G8_STAGE(G8_SA(1, 0), a3);
;       G8_BAR; G8_WAIT_L(0); G8_MMA(1, 0, At, B0); G8_BAR; G8_SCHED;
;       G8_STAGE(G8_SB(1, 1), b3 + hstep);
;       G8_WAIT_V(6); G8_BAR; G8_MMA(1, 1, At, B1); G8_BAR;
	s_waitcnt lgkmcnt(0)
	s_nop 0
	s_waitcnt lgkmcnt(0)
	v_mfma_f32_16x16x32_f16 v[74:77], v[50:53], v[164:167], v[74:77]
	v_mfma_f32_16x16x32_f16 v[78:81], v[70:73], v[164:167], v[78:81]
	v_mfma_f32_16x16x32_f16 v[54:57], v[50:53], v[178:181], v[54:57]
	v_mfma_f32_16x16x32_f16 v[58:61], v[70:73], v[178:181], v[58:61]
	v_mfma_f32_16x16x32_f16 v[26:29], v[50:53], v[186:189], v[26:29]
	v_mfma_f32_16x16x32_f16 v[30:33], v[70:73], v[186:189], v[30:33]
	v_mfma_f32_16x16x32_f16 v[10:13], v[50:53], v[206:209], v[10:13]
	v_mfma_f32_16x16x32_f16 v[14:17], v[70:73], v[206:209], v[14:17]
	v_mfma_f32_16x16x32_f16 v[74:77], v[66:69], v[174:177], v[74:77]
	v_mfma_f32_16x16x32_f16 v[78:81], v[160:163], v[174:177], v[78:81]
	v_mfma_f32_16x16x32_f16 v[54:57], v[66:69], v[182:185], v[54:57]
	v_mfma_f32_16x16x32_f16 v[58:61], v[160:163], v[182:185], v[58:61]
	v_mfma_f32_16x16x32_f16 v[26:29], v[66:69], v[202:205], v[26:29]
	v_mfma_f32_16x16x32_f16 v[30:33], v[160:163], v[202:205], v[30:33]
	v_mfma_f32_16x16x32_f16 v[10:13], v[66:69], v[210:213], v[10:13]
	v_mfma_f32_16x16x32_f16 v[14:17], v[160:163], v[210:213], v[14:17]
	s_nop 0
	s_barrier
	s_add_u32 s26, s26, 0x20080
	s_addc_u32 s27, s27, 0
	s_mov_b32 m0, s50
	v_lshl_add_u64 v[50:51], s[26:27], 0, v[0:1]
	global_load_lds_dwordx4 v[50:51], off
	v_lshl_add_u64 v[50:51], s[26:27], 0, v[152:153]
	s_mov_b32 m0, s51
	s_nop 0
	global_load_lds_dwordx4 v[50:51], off
	s_waitcnt vmcnt(6)
	s_barrier
	s_nop 0
	v_mfma_f32_16x16x32_f16 v[34:37], v[214:217], v[164:167], v[34:37]
	v_mfma_f32_16x16x32_f16 v[66:69], v[218:221], v[174:177], v[34:37]
	v_mfma_f32_16x16x32_f16 v[34:37], v[222:225], v[164:167], v[46:49]
	v_mfma_f32_16x16x32_f16 v[70:73], v[226:229], v[174:177], v[34:37]
	v_mfma_f32_16x16x32_f16 v[34:37], v[214:217], v[178:181], v[38:41]
	v_mfma_f32_16x16x32_f16 v[38:41], v[218:221], v[182:185], v[34:37]
	v_mfma_f32_16x16x32_f16 v[34:37], v[222:225], v[178:181], v[42:45]
	v_mfma_f32_16x16x32_f16 v[18:21], v[214:217], v[186:189], v[18:21]
	v_mfma_f32_16x16x32_f16 v[22:25], v[222:225], v[186:189], v[22:25]
	v_mfma_f32_16x16x32_f16 v[2:5], v[214:217], v[206:209], v[2:5]
	v_mfma_f32_16x16x32_f16 v[6:9], v[222:225], v[206:209], v[6:9]
	v_mfma_f32_16x16x32_f16 v[42:45], v[226:229], v[182:185], v[34:37]
	v_mfma_f32_16x16x32_f16 v[18:21], v[218:221], v[202:205], v[18:21]
	v_mfma_f32_16x16x32_f16 v[22:25], v[226:229], v[202:205], v[22:25]
	v_mfma_f32_16x16x32_f16 v[2:5], v[218:221], v[210:213], v[2:5]
	v_mfma_f32_16x16x32_f16 v[6:9], v[226:229], v[210:213], v[6:9]
	s_nop 0
	s_add_i32 s55, s55, 2
	s_add_u32 s24, s24, 0x100
	s_addc_u32 s25, s25, 0
	s_add_u32 s53, s53, 0x100
	s_addc_u32 s54, s54, 0
	s_cmp_gt_u32 s55, 5
	s_barrier
	s_cbranch_scc0 .LBB0_2284
; __device__ __forceinline__ float xor16(float v) { return __int_as_float(__builtin_amdgcn_ds_swizzle(__float_as_int(v), 0x401F)); }
; __device__ __forceinline__ float sigmoidf(float x) { return 1.f / (1.f + __expf(-x)); }
;   __device__ __forceinline__ void operator()(const f32x4 (&acc)[2][2][4][2], const g8::Unit& u, int ui, int wr, int wc, int fr, int fq) const {
;     const int ocb = 128 * u.pn + 16 * wc + 4 * fq;
;     float4 ba[2], bb[2];
; #pragma unroll
;     for (int bj = 0; bj < 2; ++bj) { ba[bj] = *(const float4*)(gb + ocb + 64 * bj); bb[bj] = *(const float4*)(gb + 512 + ocb + 64 * bj); }
; #pragma unroll
;     for (int ai = 0; ai < 2; ++ai)
; #pragma unroll
;       for (int m = 0; m < 4; ++m) {
;         const size_t row = (size_t)u.pm * 256 + 128 * ai + 64 * wr + 16 * m + fr;
;         float ss = 0.f;
; #pragma unroll
;         for (int bj = 0; bj < 2; ++bj) {
;           const f32x4 a = acc[ai][bj][m][0], b = acc[ai][bj][m][1];
;           float o0 = (a[0] + ba[bj].x) * sigmoidf(b[0] + bb[bj].x);
;           float o1 = (a[1] + ba[bj].y) * sigmoidf(b[1] + bb[bj].y);
;           float o2 = (a[2] + ba[bj].z) * sigmoidf(b[2] + bb[bj].z);
;           float o3 = (a[3] + ba[bj].w) * sigmoidf(b[3] + bb[bj].w);
;           *(h16x4*)(OB + row * 1024 + ocb + 64 * bj) = pack4(o0, o1, o2, o3);
;           ss += o0 * o0 + o1 * o1 + o2 * o2 + o3 * o3;
;         }
;         ss += xor16(ss);
;         ss += __shfl_xor(ss, 32);
;         if (fq == 0) ssqb[row * 16 + u.pn * 4 + wc] = ss;
;       }
	v_lshl_or_b32 v160, s2, 7, v172
	v_ashrrev_i32_e32 v161, 31, v160
	v_lshl_add_u64 v[166:167], v[160:161], 2, s[12:13]
	global_load_dwordx4 v[46:49], v[166:167], off offset:2048
	global_load_dwordx4 v[34:37], v[166:167], off offset:2304
	v_and_b32_e32 v51, 64, v199
	v_xor_b32_e32 v50, 32, v199
	v_add_u32_e32 v51, 64, v51
	v_cmp_lt_i32_e32 vcc, v50, v51
	s_ashr_i32 s23, s22, 31
	s_lshl_b64 s[22:23], s[22:23], 8
	v_cndmask_b32_e32 v50, v199, v50, vcc
	v_lshlrev_b32_e32 v173, 2, v50
	v_lshl_add_u64 v[162:163], s[22:23], 0, v[154:155]
	s_lshl_b32 s22, s2, 2
	v_lshlrev_b64 v[164:165], 11, v[162:163]
	s_ashr_i32 s23, s22, 31
	s_waitcnt vmcnt(0)
	v_add_f32_e32 v50, v138, v46
	v_mul_f32_e32 v50, 0xbfb8aa3b, v50
	v_exp_f32_e32 v138, v50
	global_load_dwordx4 v[50:53], v[166:167], off
	v_add_f32_e32 v139, v139, v47
	v_mul_f32_e32 v139, 0xbfb8aa3b, v139
	v_exp_f32_e32 v139, v139
	v_add_f32_e32 v140, v140, v48
	v_add_f32_e32 v141, v141, v49
	v_mul_f32_e32 v140, 0xbfb8aa3b, v140
	v_pk_add_f32 v[138:139], v[138:139], 1.0 op_sel_hi:[1,0]
	v_mul_f32_e32 v141, 0xbfb8aa3b, v141
	v_div_scale_f32 v168, s[2:3], v139, v139, 1.0
	v_rcp_f32_e32 v169, v168
	v_exp_f32_e32 v140, v140
	v_exp_f32_e32 v141, v141
	v_add_f32_e32 v135, v135, v35
	v_fma_f32 v174, -v168, v169, 1.0
	v_fmac_f32_e32 v169, v174, v169
	v_div_scale_f32 v174, vcc, 1.0, v139, 1.0
	v_mul_f32_e32 v175, v174, v169
	v_fma_f32 v176, -v168, v175, v174
	v_fmac_f32_e32 v175, v176, v169
	v_fma_f32 v168, -v168, v175, v174
	v_div_fmas_f32 v168, v168, v169, v175
	v_div_fixup_f32 v139, v168, v139, 1.0
	v_div_scale_f32 v168, s[2:3], v138, v138, 1.0
	v_rcp_f32_e32 v169, v168
	v_mul_f32_e32 v135, 0xbfb8aa3b, v135
	v_exp_f32_e32 v135, v135
	v_add_f32_e32 v136, v136, v36
	v_fma_f32 v174, -v168, v169, 1.0
	v_fmac_f32_e32 v169, v174, v169
	v_div_scale_f32 v174, vcc, 1.0, v138, 1.0
	v_mul_f32_e32 v175, v174, v169
	v_fma_f32 v176, -v168, v175, v174
	v_fmac_f32_e32 v175, v176, v169
	v_fma_f32 v168, -v168, v175, v174
	v_div_fmas_f32 v168, v168, v169, v175
	v_div_fixup_f32 v138, v168, v138, 1.0
	v_add_f32_e32 v137, v137, v37
	v_mul_f32_e32 v136, 0xbfb8aa3b, v136
	v_mul_f32_e32 v137, 0xbfb8aa3b, v137
	v_exp_f32_e32 v136, v136
	v_exp_f32_e32 v137, v137
	s_waitcnt vmcnt(0)
	v_pk_add_f32 v[62:63], v[62:63], v[50:51]
	s_nop 0
	v_pk_mul_f32 v[62:63], v[62:63], v[138:139]
	v_pk_add_f32 v[138:139], v[140:141], 1.0 op_sel_hi:[1,0]
	v_cvt_pk_f16_f32 v168, v62, v63
	v_div_scale_f32 v140, s[2:3], v139, v139, 1.0
	v_rcp_f32_e32 v141, v140
	v_pk_add_f32 v[64:65], v[64:65], v[52:53]
	v_pk_add_f32 v[136:137], v[136:137], 1.0 op_sel_hi:[1,0]
	v_fma_f32 v169, -v140, v141, 1.0
	v_fmac_f32_e32 v141, v169, v141
	v_div_scale_f32 v169, vcc, 1.0, v139, 1.0
	v_mul_f32_e32 v174, v169, v141
	v_fma_f32 v175, -v140, v174, v169
	v_fmac_f32_e32 v174, v175, v141
	v_fma_f32 v140, -v140, v174, v169
	v_div_fmas_f32 v140, v140, v141, v174
	v_div_fixup_f32 v139, v140, v139, 1.0
	v_div_scale_f32 v140, s[2:3], v138, v138, 1.0
	v_rcp_f32_e32 v141, v140
	s_nop 0
	v_fma_f32 v169, -v140, v141, 1.0
	v_fmac_f32_e32 v141, v169, v141
	v_div_scale_f32 v169, vcc, 1.0, v138, 1.0
	v_mul_f32_e32 v174, v169, v141
	v_fma_f32 v175, -v140, v174, v169
	v_fmac_f32_e32 v174, v175, v141
	v_fma_f32 v140, -v140, v174, v169
	v_div_fmas_f32 v140, v140, v141, v174
	v_div_fixup_f32 v138, v140, v138, 1.0
	v_pk_mul_f32 v[140:141], v[62:63], v[62:63]
	v_add_f32_e32 v62, v134, v34
	v_pk_mul_f32 v[64:65], v[64:65], v[138:139]
	v_lshl_add_u64 v[138:139], s[0:1], 0, v[164:165]
	v_mul_f32_e32 v62, 0xbfb8aa3b, v62
	v_cvt_pk_f16_f32 v169, v64, v65
	v_lshl_add_u64 v[164:165], v[160:161], 1, v[138:139]
	v_pk_mul_f32 v[138:139], v[64:65], v[64:65]
	v_exp_f32_e32 v134, v62
	global_load_dwordx4 v[62:65], v[166:167], off offset:256
	v_pk_add_f32 v[134:135], v[134:135], 1.0 op_sel_hi:[1,0]
	s_nop 0
	v_div_scale_f32 v166, s[2:3], v135, v135, 1.0
	v_rcp_f32_e32 v167, v166
	global_store_dwordx2 v[164:165], v[168:169], off
	v_fma_f32 v168, -v166, v167, 1.0
	v_fmac_f32_e32 v167, v168, v167
	v_div_scale_f32 v168, vcc, 1.0, v135, 1.0
	v_mul_f32_e32 v169, v168, v167
	v_fma_f32 v174, -v166, v169, v168
	v_fmac_f32_e32 v169, v174, v167
	v_fma_f32 v166, -v166, v169, v168
	v_div_fmas_f32 v166, v166, v167, v169
	v_div_fixup_f32 v135, v166, v135, 1.0
	v_div_scale_f32 v166, s[2:3], v134, v134, 1.0
	v_rcp_f32_e32 v167, v166
	s_waitcnt vmcnt(0)
	v_pk_add_f32 v[130:131], v[130:131], v[62:63]
	v_fma_f32 v168, -v166, v167, 1.0
	v_fmac_f32_e32 v167, v168, v167
	v_div_scale_f32 v168, vcc, 1.0, v134, 1.0
	v_mul_f32_e32 v169, v168, v167
	v_fma_f32 v174, -v166, v169, v168
	v_fmac_f32_e32 v169, v174, v167
	v_fma_f32 v166, -v166, v169, v168
	v_div_fmas_f32 v166, v166, v167, v169
	v_div_fixup_f32 v134, v166, v134, 1.0
	v_pk_mul_f32 v[130:131], v[130:131], v[134:135]
	v_div_scale_f32 v135, s[2:3], v137, v137, 1.0
	v_rcp_f32_e32 v166, v135
	v_pk_add_f32 v[132:133], v[132:133], v[64:65]
	v_cvt_pk_f16_f32 v134, v130, v131
	v_pk_mul_f32 v[130:131], v[130:131], v[130:131]
	v_fma_f32 v167, -v135, v166, 1.0
	v_fmac_f32_e32 v166, v167, v166
	v_div_scale_f32 v167, vcc, 1.0, v137, 1.0
	v_mul_f32_e32 v168, v167, v166
	v_fma_f32 v169, -v135, v168, v167
	v_fmac_f32_e32 v168, v169, v166
	v_fma_f32 v135, -v135, v168, v167
	v_div_fmas_f32 v135, v135, v166, v168
	v_div_fixup_f32 v137, v135, v137, 1.0
	v_div_scale_f32 v135, s[2:3], v136, v136, 1.0
	v_rcp_f32_e32 v166, v135
	v_add_f32_e32 v130, v130, v131
	v_add_f32_e32 v131, v140, v141
	v_add_f32_e32 v131, v138, v131
	v_fma_f32 v167, -v135, v166, 1.0
	v_fmac_f32_e32 v166, v167, v166
	v_div_scale_f32 v167, vcc, 1.0, v136, 1.0
	v_mul_f32_e32 v168, v167, v166
	v_fma_f32 v169, -v135, v168, v167
	v_fmac_f32_e32 v168, v169, v166
	v_fma_f32 v135, -v135, v168, v167
	v_div_fmas_f32 v135, v135, v166, v168
	v_div_fixup_f32 v136, v135, v136, 1.0
	v_pk_mul_f32 v[132:133], v[132:133], v[136:137]
	v_add_f32_e32 v131, v139, v131
	v_cvt_pk_f16_f32 v135, v132, v133
	v_pk_mul_f32 v[132:133], v[132:133], v[132:133]
	global_store_dwordx2 v[164:165], v[134:135], off offset:128
	v_add_f32_e32 v130, v132, v130
	v_add_f32_e32 v130, v133, v130
	v_add_f32_e32 v130, v131, v130
	v_mov_b32_e32 v131, v130
	s_nop 1
	v_permlane16_swap_b32_e32 v131, v130
	s_waitcnt lgkmcnt(0)
	v_add_f32_e32 v130, v130, v131
	v_mov_b32_e32 v131, v130
	s_nop 1
	v_permlane32_swap_b32_e32 v131, v130
	s_and_saveexec_b64 s[24:25], s[6:7]
	s_cbranch_execz .LBB0_2287
	s_waitcnt lgkmcnt(0)
	v_add_f32_e32 v132, v130, v131
	v_lshlrev_b64 v[130:131], 6, v[162:163]
	v_lshl_add_u64 v[130:131], s[10:11], 0, v[130:131]
	v_lshl_add_u64 v[130:131], s[22:23], 2, v[130:131]
	s_lshl_b32 s92, s45, 2
	v_lshl_add_u64 v[130:131], v[130:131], 0, s[92:93]
	global_store_dword v[130:131], v132, off

; #define G8_STAGE(bufoff, gbase) do { _Pragma("unroll") for (int _i = 0; _i < 2; ++_i) \
;     __builtin_amdgcn_global_load_lds((const unsigned*)((const char*)(gbase) + voffA[_i]), (LAS unsigned*)(lds + (bufoff) + ldsw + _i * 8192), 16, 0, 0); } while (0)
; #define G8_LDA(dst, b, h) do { _Pragma("unroll") for (int m = 0; m < 4; ++m) _Pragma("unroll") for (int k = 0; k < 2; ++k) dst[m][k] = *(const LAS h16x8*)(lds + G8_SA(b, h) + aoff + m * 2048 + k * 1024); } while (0)
; #define G8_LDB(dst, b, h) do { _Pragma("unroll") for (int n = 0; n < 2; ++n) _Pragma("unroll") for (int k = 0; k < 2; ++k) dst[n][k] = *(const LAS h16x8*)(lds + G8_SB(b, h) + boff + n * 2048 + k * 1024); } while (0)
; #define G8_MMA(ai, bj, At, Bt_) do { __builtin_amdgcn_s_setprio(1); _Pragma("unroll") for (int m = 0; m < 4; ++m) _Pragma("unroll") for (int n = 0; n < 2; ++n) _Pragma("unroll") for (int k = 0; k < 2; ++k) \
;     acc[ai][bj][m][n] = __builtin_amdgcn_mfma_f32_16x16x32_f16(Bt_[n][k], At[m][k], acc[ai][bj][m][n], 0, 0, 0); __builtin_amdgcn_s_setprio(0); } while (0)
; #define G8_WAIT_V(n) asm volatile("s_waitcnt vmcnt(" #n ")" ::: "memory")
; #define G8_WAIT_L(n) asm volatile("s_waitcnt lgkmcnt(" #n ")" ::: "memory")
; #define G8_BAR __builtin_amdgcn_s_barrier()
; #define G8_SCHED __builtin_amdgcn_sched_barrier(0)
; template <class Epi>
; __device__ __forceinline__ void gemm_phase(LAS unsigned char* lds, const h16* A, const h16* Bt, int K, const Order& S, const Epi& E) {
;     ...
;       G8_LDB(B0, 0, 0); G8_SCHED; G8_LDA(At, 0, 0); G8_STAGE(G8_SA(1, 1), a1 + hstep);
;       G8_WAIT_L(8); G8_BAR; G8_WAIT_L(0); G8_MMA(0, 0, At, B0); G8_BAR; G8_SCHED;
;       G8_LDB(B1, 0, 1); G8_STAGE(G8_SB(0, 0), b2);
;       G8_BAR; G8_WAIT_L(0); G8_MMA(0, 1, At, B1); G8_BAR;
;       G8_LDA(At, 0, 1); G8_STAGE(G8_SA(0, 0), a2);
;       G8_BAR; G8_WAIT_L(0); G8_MMA(1, 0, At, B0); G8_BAR; G8_SCHED;
;       G8_STAGE(G8_SB(0, 1), b2 + hstep);
;       G8_WAIT_V(6); G8_BAR; G8_MMA(1, 1, At, B1); G8_BAR;
.LBB0_2378:
	s_add_u32 s26, s20, s24
	v_or_b32_e32 v0, 0x10000, v158
	s_addc_u32 s27, s21, s25
	v_add_u32_e32 v2, 0x10400, v158
	ds_read_b128 v[162:165], v0
	ds_read_b128 v[166:169], v2
	v_add_u32_e32 v0, 0x10800, v158
	s_add_u32 s26, s26, 0x100
	v_add_u32_e32 v2, 0x10c00, v158
	ds_read_b128 v[170:173], v0
	ds_read_b128 v[174:177], v2
	s_addc_u32 s27, s27, 0
	s_add_u32 s56, s53, s24
	s_addc_u32 s57, s54, s25
	s_cmpk_eq_i32 s24, 0x700
	s_cselect_b32 s29, s3, s27
	s_cselect_b32 s28, s15, s26
	s_cselect_b32 s27, s13, s57
	s_cselect_b32 s26, s23, s56
	v_lshl_add_u64 v[2:3], v[154:155], 0, s[24:25]
	s_add_i32 m0, s37, 0xc000
	ds_read_b128 v[178:181], v139
	ds_read_b128 v[182:185], v139 offset:1024
	ds_read_b128 v[186:189], v139 offset:2048
	ds_read_b128 v[202:205], v139 offset:3072
	ds_read_b128 v[206:209], v139 offset:4096
	ds_read_b128 v[210:213], v139 offset:5120
	ds_read_b128 v[214:217], v139 offset:6144
	ds_read_b128 v[218:221], v139 offset:7168
	global_load_lds_dwordx4 v[2:3], off
	v_lshl_add_u64 v[2:3], v[156:157], 0, s[24:25]
	s_add_i32 m0, s37, 0xe000
	s_nop 0
	global_load_lds_dwordx4 v[2:3], off
	s_waitcnt lgkmcnt(8)
	s_barrier
	s_waitcnt lgkmcnt(0)
	s_nop 0
	s_waitcnt lgkmcnt(0)
	v_mfma_f32_16x16x32_f16 v[128:131], v[162:165], v[178:181], v[128:131]
	v_mfma_f32_16x16x32_f16 v[124:127], v[170:173], v[178:181], v[124:127]
	v_mfma_f32_16x16x32_f16 v[112:115], v[162:165], v[186:189], v[112:115]
	v_mfma_f32_16x16x32_f16 v[108:111], v[170:173], v[186:189], v[108:111]
	v_mfma_f32_16x16x32_f16 v[96:99], v[162:165], v[206:209], v[96:99]
	v_mfma_f32_16x16x32_f16 v[92:95], v[170:173], v[206:209], v[92:95]
	v_mfma_f32_16x16x32_f16 v[80:83], v[162:165], v[214:217], v[80:83]
	v_mfma_f32_16x16x32_f16 v[76:79], v[170:173], v[214:217], v[76:79]
	v_mfma_f32_16x16x32_f16 v[128:131], v[166:169], v[182:185], v[128:131]
	v_mfma_f32_16x16x32_f16 v[124:127], v[174:177], v[182:185], v[124:127]
	v_mfma_f32_16x16x32_f16 v[112:115], v[166:169], v[202:205], v[112:115]
	v_mfma_f32_16x16x32_f16 v[108:111], v[174:177], v[202:205], v[108:111]
	v_mfma_f32_16x16x32_f16 v[96:99], v[166:169], v[210:213], v[96:99]
	v_mfma_f32_16x16x32_f16 v[92:95], v[174:177], v[210:213], v[92:95]
	v_mfma_f32_16x16x32_f16 v[80:83], v[166:169], v[218:221], v[80:83]
	v_mfma_f32_16x16x32_f16 v[76:79], v[174:177], v[218:221], v[76:79]
	s_nop 0
	s_barrier
	v_or_b32_e32 v0, 0x14000, v158
	s_mov_b32 m0, s38
	v_add_u32_e32 v2, 0x14400, v158
	ds_read_b128 v[222:225], v0
	ds_read_b128 v[226:229], v2
	v_add_u32_e32 v0, 0x14800, v158
	v_lshl_add_u64 v[238:239], s[26:27], 0, v[134:135]
	v_add_u32_e32 v2, 0x14c00, v158
	ds_read_b128 v[230:233], v0
	ds_read_b128 v[234:237], v2
	global_load_lds_dwordx4 v[238:239], off
	v_lshl_add_u64 v[240:241], s[26:27], 0, v[132:133]
	s_mov_b32 m0, s39
	s_nop 0
	global_load_lds_dwordx4 v[240:241], off
	s_barrier
	s_waitcnt lgkmcnt(0)
	s_nop 0
	s_waitcnt lgkmcnt(0)
	v_mfma_f32_16x16x32_f16 v[120:123], v[222:225], v[178:181], v[120:123]
	v_mfma_f32_16x16x32_f16 v[116:119], v[230:233], v[178:181], v[116:119]
	v_mfma_f32_16x16x32_f16 v[104:107], v[222:225], v[186:189], v[104:107]
	v_mfma_f32_16x16x32_f16 v[100:103], v[230:233], v[186:189], v[100:103]
	v_mfma_f32_16x16x32_f16 v[88:91], v[222:225], v[206:209], v[88:91]
	v_mfma_f32_16x16x32_f16 v[84:87], v[230:233], v[206:209], v[84:87]
	v_mfma_f32_16x16x32_f16 v[72:75], v[222:225], v[214:217], v[72:75]
	v_mfma_f32_16x16x32_f16 v[68:71], v[230:233], v[214:217], v[68:71]
	v_mfma_f32_16x16x32_f16 v[120:123], v[226:229], v[182:185], v[120:123]
	v_mfma_f32_16x16x32_f16 v[116:119], v[234:237], v[182:185], v[116:119]
	v_mfma_f32_16x16x32_f16 v[104:107], v[226:229], v[202:205], v[104:107]
	v_mfma_f32_16x16x32_f16 v[100:103], v[234:237], v[202:205], v[100:103]
	v_mfma_f32_16x16x32_f16 v[88:91], v[226:229], v[210:213], v[88:91]
	v_mfma_f32_16x16x32_f16 v[84:87], v[234:237], v[210:213], v[84:87]
	v_mfma_f32_16x16x32_f16 v[72:75], v[226:229], v[218:221], v[72:75]
	v_mfma_f32_16x16x32_f16 v[68:71], v[234:237], v[218:221], v[68:71]
	s_nop 0
	s_mov_b32 m0, s37
	v_lshl_add_u64 v[242:243], s[28:29], 0, v[134:135]
	s_barrier
	ds_read_b128 v[178:181], v139 offset:16384
	ds_read_b128 v[182:185], v139 offset:17408
	ds_read_b128 v[186:189], v139 offset:18432
	ds_read_b128 v[202:205], v139 offset:19456
	ds_read_b128 v[206:209], v139 offset:20480
	ds_read_b128 v[210:213], v139 offset:21504
	ds_read_b128 v[214:217], v139 offset:22528
	ds_read_b128 v[218:221], v139 offset:23552
	global_load_lds_dwordx4 v[242:243], off
	v_lshl_add_u64 v[244:245], s[28:29], 0, v[132:133]
	s_mov_b32 m0, s40
	s_nop 0
	global_load_lds_dwordx4 v[244:245], off
	s_barrier
	s_waitcnt lgkmcnt(0)
	s_nop 0
	s_waitcnt lgkmcnt(0)
	v_mfma_f32_16x16x32_f16 v[64:67], v[162:165], v[178:181], v[64:67]
	v_mfma_f32_16x16x32_f16 v[60:63], v[170:173], v[178:181], v[60:63]
	v_mfma_f32_16x16x32_f16 v[48:51], v[162:165], v[186:189], v[48:51]
	v_mfma_f32_16x16x32_f16 v[44:47], v[170:173], v[186:189], v[44:47]
	v_mfma_f32_16x16x32_f16 v[32:35], v[162:165], v[206:209], v[32:35]
	v_mfma_f32_16x16x32_f16 v[28:31], v[170:173], v[206:209], v[28:31]
	v_mfma_f32_16x16x32_f16 v[16:19], v[162:165], v[214:217], v[16:19]
	v_mfma_f32_16x16x32_f16 v[12:15], v[170:173], v[214:217], v[12:15]
	v_mfma_f32_16x16x32_f16 v[64:67], v[166:169], v[182:185], v[64:67]
	v_mfma_f32_16x16x32_f16 v[60:63], v[174:177], v[182:185], v[60:63]
	v_mfma_f32_16x16x32_f16 v[48:51], v[166:169], v[202:205], v[48:51]
	v_mfma_f32_16x16x32_f16 v[44:47], v[174:177], v[202:205], v[44:47]
	v_mfma_f32_16x16x32_f16 v[32:35], v[166:169], v[210:213], v[32:35]
	v_mfma_f32_16x16x32_f16 v[28:31], v[174:177], v[210:213], v[28:31]
	v_mfma_f32_16x16x32_f16 v[16:19], v[166:169], v[218:221], v[16:19]
	v_mfma_f32_16x16x32_f16 v[12:15], v[174:177], v[218:221], v[12:15]
	s_nop 0
	s_barrier
; #define G8_STAGE(bufoff, gbase) do { _Pragma("unroll") for (int _i = 0; _i < 2; ++_i) \
;     __builtin_amdgcn_global_load_lds((const unsigned*)((const char*)(gbase) + voffA[_i]), (LAS unsigned*)(lds + (bufoff) + ldsw + _i * 8192), 16, 0, 0); } while (0)
; #define G8_LDA(dst, b, h) do { _Pragma("unroll") for (int m = 0; m < 4; ++m) _Pragma("unroll") for (int k = 0; k < 2; ++k) dst[m][k] = *(const LAS h16x8*)(lds + G8_SA(b, h) + aoff + m * 2048 + k * 1024); } while (0)
; #define G8_LDB(dst, b, h) do { _Pragma("unroll") for (int n = 0; n < 2; ++n) _Pragma("unroll") for (int k = 0; k < 2; ++k) dst[n][k] = *(const LAS h16x8*)(lds + G8_SB(b, h) + boff + n * 2048 + k * 1024); } while (0)
; #define G8_MMA(ai, bj, At, Bt_) do { __builtin_amdgcn_s_setprio(1); _Pragma("unroll") for (int m = 0; m < 4; ++m) _Pragma("unroll") for (int n = 0; n < 2; ++n) _Pragma("unroll") for (int k = 0; k < 2; ++k) \
;     acc[ai][bj][m][n] = __builtin_amdgcn_mfma_f32_16x16x32_f16(Bt_[n][k], At[m][k], acc[ai][bj][m][n], 0, 0, 0); __builtin_amdgcn_s_setprio(0); } while (0)
; #define G8_WAIT_V(n) asm volatile("s_waitcnt vmcnt(" #n ")" ::: "memory")
; #define G8_WAIT_L(n) asm volatile("s_waitcnt lgkmcnt(" #n ")" ::: "memory")
; #define G8_BAR __builtin_amdgcn_s_barrier()
; #define G8_SCHED __builtin_amdgcn_sched_barrier(0)
; template <class Epi>
; __device__ __forceinline__ void gemm_phase(LAS unsigned char* lds, const h16* A, const h16* Bt, int K, const Order& S, const Epi& E) {
;     ...
;       G8_LDA(At, 0, 1); G8_STAGE(G8_SA(0, 0), a2);
;       G8_BAR; G8_WAIT_L(0); G8_MMA(1, 0, At, B0); G8_BAR; G8_SCHED;
;       G8_STAGE(G8_SB(0, 1), b2 + hstep);
;       G8_WAIT_V(6); G8_BAR; G8_MMA(1, 1, At, B1); G8_BAR;
;       G8_LDB(B0, 1, 0); G8_SCHED; G8_LDA(At, 1, 0); G8_STAGE(G8_SA(0, 1), a2 + hstep);
;       G8_WAIT_L(8); G8_BAR; G8_WAIT_L(0); G8_MMA(0, 0, At, B0); G8_BAR; G8_SCHED;
;       G8_LDB(B1, 1, 1); G8_STAGE(G8_SB(1, 0), b3);
;       G8_BAR; G8_WAIT_L(0); G8_MMA(0, 1, At, B1); G8_BAR;
;       G8_LDA(At, 1, 1); G8_STAGE(G8_SA(1, 0), a3);
	s_add_u32 s56, s26, 0x40000
	s_addc_u32 s57, s27, 0
	s_mov_b32 m0, s41
	v_lshl_add_u64 v[2:3], s[56:57], 0, v[134:135]
	global_load_lds_dwordx4 v[2:3], off
	v_lshl_add_u64 v[2:3], s[56:57], 0, v[132:133]
	s_mov_b32 m0, s42
	s_nop 0
	global_load_lds_dwordx4 v[2:3], off
	s_waitcnt vmcnt(6)
	s_barrier
	s_nop 0
	v_mfma_f32_16x16x32_f16 v[56:59], v[222:225], v[178:181], v[56:59]
	v_mfma_f32_16x16x32_f16 v[52:55], v[230:233], v[178:181], v[52:55]
	v_mfma_f32_16x16x32_f16 v[40:43], v[222:225], v[186:189], v[40:43]
	v_mfma_f32_16x16x32_f16 v[36:39], v[230:233], v[186:189], v[36:39]
	v_mfma_f32_16x16x32_f16 v[24:27], v[222:225], v[206:209], v[24:27]
	v_mfma_f32_16x16x32_f16 v[20:23], v[230:233], v[206:209], v[20:23]
	v_mfma_f32_16x16x32_f16 v[8:11], v[222:225], v[214:217], v[8:11]
	v_mfma_f32_16x16x32_f16 v[2:5], v[230:233], v[214:217], v[4:7]
	v_mfma_f32_16x16x32_f16 v[56:59], v[226:229], v[182:185], v[56:59]
	v_mfma_f32_16x16x32_f16 v[52:55], v[234:237], v[182:185], v[52:55]
	v_mfma_f32_16x16x32_f16 v[40:43], v[226:229], v[202:205], v[40:43]
	v_mfma_f32_16x16x32_f16 v[36:39], v[234:237], v[202:205], v[36:39]
	v_mfma_f32_16x16x32_f16 v[24:27], v[226:229], v[210:213], v[24:27]
	v_mfma_f32_16x16x32_f16 v[20:23], v[234:237], v[210:213], v[20:23]
	v_mfma_f32_16x16x32_f16 v[8:11], v[226:229], v[218:221], v[8:11]
	v_mfma_f32_16x16x32_f16 v[2:5], v[234:237], v[218:221], v[2:5]
	s_nop 0
	v_or_b32_e32 v0, 0x18000, v158
	s_barrier
	v_add_u32_e32 v6, 0x18400, v158
	ds_read_b128 v[162:165], v0
	ds_read_b128 v[166:169], v6
	v_add_u32_e32 v0, 0x18800, v158
	v_add_u32_e32 v6, 0x18c00, v158
	ds_read_b128 v[170:173], v0
	ds_read_b128 v[174:177], v6
	s_add_u32 s28, s28, 0x40000
	s_addc_u32 s29, s29, 0
	s_mov_b32 m0, s43
	v_lshl_add_u64 v[6:7], s[28:29], 0, v[134:135]
	ds_read_b128 v[178:181], v139 offset:32768
	ds_read_b128 v[182:185], v139 offset:33792
	ds_read_b128 v[186:189], v139 offset:34816
	ds_read_b128 v[202:205], v139 offset:35840
	ds_read_b128 v[206:209], v139 offset:36864
	ds_read_b128 v[210:213], v139 offset:37888
	ds_read_b128 v[214:217], v139 offset:38912
	ds_read_b128 v[218:221], v139 offset:39936
	global_load_lds_dwordx4 v[6:7], off
	v_lshl_add_u64 v[6:7], s[28:29], 0, v[132:133]
	s_mov_b32 m0, s44
	s_nop 0
	global_load_lds_dwordx4 v[6:7], off
	s_waitcnt lgkmcnt(8)
	s_barrier
	s_waitcnt lgkmcnt(0)
	s_nop 0
	s_waitcnt lgkmcnt(0)
	v_mfma_f32_16x16x32_f16 v[128:131], v[162:165], v[178:181], v[128:131]
	v_mfma_f32_16x16x32_f16 v[124:127], v[170:173], v[178:181], v[124:127]
	v_mfma_f32_16x16x32_f16 v[112:115], v[162:165], v[186:189], v[112:115]
	v_mfma_f32_16x16x32_f16 v[108:111], v[170:173], v[186:189], v[108:111]
	v_mfma_f32_16x16x32_f16 v[96:99], v[162:165], v[206:209], v[96:99]
	v_mfma_f32_16x16x32_f16 v[92:95], v[170:173], v[206:209], v[92:95]
	v_mfma_f32_16x16x32_f16 v[80:83], v[162:165], v[214:217], v[80:83]
	v_mfma_f32_16x16x32_f16 v[76:79], v[170:173], v[214:217], v[76:79]
	v_mfma_f32_16x16x32_f16 v[128:131], v[166:169], v[182:185], v[128:131]
	v_mfma_f32_16x16x32_f16 v[124:127], v[174:177], v[182:185], v[124:127]
	v_mfma_f32_16x16x32_f16 v[112:115], v[166:169], v[202:205], v[112:115]
	v_mfma_f32_16x16x32_f16 v[108:111], v[174:177], v[202:205], v[108:111]
	v_mfma_f32_16x16x32_f16 v[96:99], v[166:169], v[210:213], v[96:99]
	v_mfma_f32_16x16x32_f16 v[92:95], v[174:177], v[210:213], v[92:95]
	v_mfma_f32_16x16x32_f16 v[80:83], v[166:169], v[218:221], v[80:83]
	v_mfma_f32_16x16x32_f16 v[76:79], v[174:177], v[218:221], v[76:79]
	s_nop 0
	s_barrier
	v_or_b32_e32 v0, 0x1c000, v158
	v_add_u32_e32 v6, 0x1c400, v158
	ds_read_b128 v[222:225], v0
	ds_read_b128 v[226:229], v6
	v_add_u32_e32 v0, 0x1c800, v158
	v_add_u32_e32 v6, 0x1cc00, v158
	s_mov_b32 m0, s46
	ds_read_b128 v[230:233], v0
	ds_read_b128 v[234:237], v6
	v_lshl_add_u64 v[6:7], v[238:239], 0, s[94:95]
	global_load_lds_dwordx4 v[6:7], off
	v_lshl_add_u64 v[6:7], v[240:241], 0, s[94:95]
	s_mov_b32 m0, s47
	s_nop 0
	global_load_lds_dwordx4 v[6:7], off
	s_barrier
; #define G8_STAGE(bufoff, gbase) do { _Pragma("unroll") for (int _i = 0; _i < 2; ++_i) \
;     __builtin_amdgcn_global_load_lds((const unsigned*)((const char*)(gbase) + voffA[_i]), (LAS unsigned*)(lds + (bufoff) + ldsw + _i * 8192), 16, 0, 0); } while (0)
; #define G8_LDA(dst, b, h) do { _Pragma("unroll") for (int m = 0; m < 4; ++m) _Pragma("unroll") for (int k = 0; k < 2; ++k) dst[m][k] = *(const LAS h16x8*)(lds + G8_SA(b, h) + aoff + m * 2048 + k * 1024); } while (0)
; #define G8_LDB(dst, b, h) do { _Pragma("unroll") for (int n = 0; n < 2; ++n) _Pragma("unroll") for (int k = 0; k < 2; ++k) dst[n][k] = *(const LAS h16x8*)(lds + G8_SB(b, h) + boff + n * 2048 + k * 1024); } while (0)
; #define G8_MMA(ai, bj, At, Bt_) do { __builtin_amdgcn_s_setprio(1); _Pragma("unroll") for (int m = 0; m < 4; ++m) _Pragma("unroll") for (int n = 0; n < 2; ++n) _Pragma("unroll") for (int k = 0; k < 2; ++k) \
;     acc[ai][bj][m][n] = __builtin_amdgcn_mfma_f32_16x16x32_f16(Bt_[n][k], At[m][k], acc[ai][bj][m][n], 0, 0, 0); __builtin_amdgcn_s_setprio(0); } while (0)
; #define G8_WAIT_V(n) asm volatile("s_waitcnt vmcnt(" #n ")" ::: "memory")
; #define G8_WAIT_L(n) asm volatile("s_waitcnt lgkmcnt(" #n ")" ::: "memory")
; #define G8_BAR __builtin_amdgcn_s_barrier()
; #define G8_SCHED __builtin_amdgcn_sched_barrier(0)
; template <class Epi>
; __device__ __forceinline__ void gemm_phase(LAS unsigned char* lds, const h16* A, const h16* Bt, int K, const Order& S, const Epi& E) {
;     ...
;       G8_LDB(B0, 1, 0); G8_SCHED; G8_LDA(At, 1, 0); G8_STAGE(G8_SA(0, 1), a2 + hstep);
;       G8_WAIT_L(8); G8_BAR; G8_WAIT_L(0); G8_MMA(0, 0, At, B0); G8_BAR; G8_SCHED;
;       G8_LDB(B1, 1, 1); G8_STAGE(G8_SB(1, 0), b3);
;       G8_BAR; G8_WAIT_L(0); G8_MMA(0, 1, At, B1); G8_BAR;
;       G8_LDA(At, 1, 1); G8_STAGE(G8_SA(1, 0), a3);
;       G8_BAR; G8_WAIT_L(0); G8_MMA(1, 0, At, B0); G8_BAR; G8_SCHED;
;       G8_STAGE(G8_SB(1, 1), b3 + hstep);
;       G8_WAIT_V(6); G8_BAR; G8_MMA(1, 1, At, B1); G8_BAR;
	s_waitcnt lgkmcnt(0)
	s_nop 0
	s_waitcnt lgkmcnt(0)
	v_mfma_f32_16x16x32_f16 v[120:123], v[222:225], v[178:181], v[120:123]
	v_mfma_f32_16x16x32_f16 v[116:119], v[230:233], v[178:181], v[116:119]
	v_mfma_f32_16x16x32_f16 v[104:107], v[222:225], v[186:189], v[104:107]
	v_mfma_f32_16x16x32_f16 v[100:103], v[230:233], v[186:189], v[100:103]
	v_mfma_f32_16x16x32_f16 v[88:91], v[222:225], v[206:209], v[88:91]
	v_mfma_f32_16x16x32_f16 v[84:87], v[230:233], v[206:209], v[84:87]
	v_mfma_f32_16x16x32_f16 v[72:75], v[222:225], v[214:217], v[72:75]
	v_mfma_f32_16x16x32_f16 v[68:71], v[230:233], v[214:217], v[68:71]
	v_mfma_f32_16x16x32_f16 v[120:123], v[226:229], v[182:185], v[120:123]
	v_mfma_f32_16x16x32_f16 v[116:119], v[234:237], v[182:185], v[116:119]
	v_mfma_f32_16x16x32_f16 v[104:107], v[226:229], v[202:205], v[104:107]
	v_mfma_f32_16x16x32_f16 v[100:103], v[234:237], v[202:205], v[100:103]
	v_mfma_f32_16x16x32_f16 v[88:91], v[226:229], v[210:213], v[88:91]
	v_mfma_f32_16x16x32_f16 v[84:87], v[234:237], v[210:213], v[84:87]
	v_mfma_f32_16x16x32_f16 v[72:75], v[226:229], v[218:221], v[72:75]
	v_mfma_f32_16x16x32_f16 v[68:71], v[234:237], v[218:221], v[68:71]
	s_nop 0
	s_mov_b32 m0, s48
	v_lshl_add_u64 v[6:7], v[242:243], 0, s[94:95]
	s_barrier
	ds_read_b128 v[178:181], v139 offset:49152
	ds_read_b128 v[182:185], v139 offset:50176
	ds_read_b128 v[186:189], v139 offset:51200
	ds_read_b128 v[202:205], v139 offset:52224
	ds_read_b128 v[206:209], v139 offset:53248
	ds_read_b128 v[210:213], v139 offset:54272
	ds_read_b128 v[214:217], v139 offset:55296
	ds_read_b128 v[218:221], v139 offset:56320
	global_load_lds_dwordx4 v[6:7], off
	v_lshl_add_u64 v[6:7], v[244:245], 0, s[94:95]
	s_mov_b32 m0, s49
	s_nop 0
	global_load_lds_dwordx4 v[6:7], off
	s_barrier
	s_waitcnt lgkmcnt(0)
	s_nop 0
	s_waitcnt lgkmcnt(0)
	v_mfma_f32_16x16x32_f16 v[64:67], v[162:165], v[178:181], v[64:67]
	v_mfma_f32_16x16x32_f16 v[60:63], v[170:173], v[178:181], v[60:63]
	v_mfma_f32_16x16x32_f16 v[48:51], v[162:165], v[186:189], v[48:51]
	v_mfma_f32_16x16x32_f16 v[44:47], v[170:173], v[186:189], v[44:47]
	v_mfma_f32_16x16x32_f16 v[32:35], v[162:165], v[206:209], v[32:35]
	v_mfma_f32_16x16x32_f16 v[28:31], v[170:173], v[206:209], v[28:31]
	v_mfma_f32_16x16x32_f16 v[16:19], v[162:165], v[214:217], v[16:19]
	v_mfma_f32_16x16x32_f16 v[12:15], v[170:173], v[214:217], v[12:15]
	v_mfma_f32_16x16x32_f16 v[64:67], v[166:169], v[182:185], v[64:67]
	v_mfma_f32_16x16x32_f16 v[60:63], v[174:177], v[182:185], v[60:63]
	v_mfma_f32_16x16x32_f16 v[48:51], v[166:169], v[202:205], v[48:51]
	v_mfma_f32_16x16x32_f16 v[44:47], v[174:177], v[202:205], v[44:47]
	v_mfma_f32_16x16x32_f16 v[32:35], v[166:169], v[210:213], v[32:35]
	v_mfma_f32_16x16x32_f16 v[28:31], v[174:177], v[210:213], v[28:31]
	v_mfma_f32_16x16x32_f16 v[16:19], v[166:169], v[218:221], v[16:19]
	v_mfma_f32_16x16x32_f16 v[12:15], v[174:177], v[218:221], v[12:15]
	s_nop 0
	s_barrier
	s_add_u32 s26, s26, 0x40080
	s_addc_u32 s27, s27, 0
	s_mov_b32 m0, s50
	v_lshl_add_u64 v[6:7], s[26:27], 0, v[134:135]
	global_load_lds_dwordx4 v[6:7], off
	v_lshl_add_u64 v[6:7], s[26:27], 0, v[132:133]
	s_mov_b32 m0, s51
	s_nop 0
	global_load_lds_dwordx4 v[6:7], off
	s_waitcnt vmcnt(6)
	s_barrier
	s_nop 0
	v_mfma_f32_16x16x32_f16 v[56:59], v[222:225], v[178:181], v[56:59]
	v_mfma_f32_16x16x32_f16 v[52:55], v[230:233], v[178:181], v[52:55]
	v_mfma_f32_16x16x32_f16 v[40:43], v[222:225], v[186:189], v[40:43]
	v_mfma_f32_16x16x32_f16 v[36:39], v[230:233], v[186:189], v[36:39]
	v_mfma_f32_16x16x32_f16 v[24:27], v[222:225], v[206:209], v[24:27]
	v_mfma_f32_16x16x32_f16 v[20:23], v[230:233], v[206:209], v[20:23]
	v_mfma_f32_16x16x32_f16 v[6:9], v[222:225], v[214:217], v[8:11]
	v_mfma_f32_16x16x32_f16 v[2:5], v[230:233], v[214:217], v[2:5]
	v_mfma_f32_16x16x32_f16 v[56:59], v[226:229], v[182:185], v[56:59]
	v_mfma_f32_16x16x32_f16 v[52:55], v[234:237], v[182:185], v[52:55]
	v_mfma_f32_16x16x32_f16 v[40:43], v[226:229], v[202:205], v[40:43]
	v_mfma_f32_16x16x32_f16 v[36:39], v[234:237], v[202:205], v[36:39]
	v_mfma_f32_16x16x32_f16 v[24:27], v[226:229], v[210:213], v[24:27]
	v_mfma_f32_16x16x32_f16 v[20:23], v[234:237], v[210:213], v[20:23]
	v_mfma_f32_16x16x32_f16 v[8:11], v[226:229], v[218:221], v[6:9]
	v_mfma_f32_16x16x32_f16 v[4:7], v[234:237], v[218:221], v[2:5]
	s_nop 0
	s_add_i32 s55, s55, 2
	s_add_u32 s24, s24, 0x100
	s_addc_u32 s25, s25, 0
	s_cmp_gt_u32 s55, 13
	s_barrier
	s_cbranch_scc1 .LBB0_2381

; #define G8_STAGE(bufoff, gbase) do { _Pragma("unroll") for (int _i = 0; _i < 2; ++_i) \
;     __builtin_amdgcn_global_load_lds((const unsigned*)((const char*)(gbase) + voffA[_i]), (LAS unsigned*)(lds + (bufoff) + ldsw + _i * 8192), 16, 0, 0); } while (0)
; #define G8_LDA(dst, b, h) do { _Pragma("unroll") for (int m = 0; m < 4; ++m) _Pragma("unroll") for (int k = 0; k < 2; ++k) dst[m][k] = *(const LAS h16x8*)(lds + G8_SA(b, h) + aoff + m * 2048 + k * 1024); } while (0)
; #define G8_LDB(dst, b, h) do { _Pragma("unroll") for (int n = 0; n < 2; ++n) _Pragma("unroll") for (int k = 0; k < 2; ++k) dst[n][k] = *(const LAS h16x8*)(lds + G8_SB(b, h) + boff + n * 2048 + k * 1024); } while (0)
; #define G8_MMA(ai, bj, At, Bt_) do { __builtin_amdgcn_s_setprio(1); _Pragma("unroll") for (int m = 0; m < 4; ++m) _Pragma("unroll") for (int n = 0; n < 2; ++n) _Pragma("unroll") for (int k = 0; k < 2; ++k) \
;     acc[ai][bj][m][n] = __builtin_amdgcn_mfma_f32_16x16x32_f16(Bt_[n][k], At[m][k], acc[ai][bj][m][n], 0, 0, 0); __builtin_amdgcn_s_setprio(0); } while (0)
; #define G8_WAIT_V(n) asm volatile("s_waitcnt vmcnt(" #n ")" ::: "memory")
; #define G8_WAIT_L(n) asm volatile("s_waitcnt lgkmcnt(" #n ")" ::: "memory")
; #define G8_BAR __builtin_amdgcn_s_barrier()
; #define G8_SCHED __builtin_amdgcn_sched_barrier(0)
; template <class Epi>
; __device__ __forceinline__ void gemm_phase(LAS unsigned char* lds, const h16* A, const h16* Bt, int K, const Order& S, const Epi& E) {
;     ...
;       G8_LDB(B0, 0, 0); G8_SCHED; G8_LDA(At, 0, 0); G8_STAGE(G8_SA(1, 1), a1 + hstep);
;       G8_WAIT_L(8); G8_BAR; G8_WAIT_L(0); G8_MMA(0, 0, At, B0); G8_BAR; G8_SCHED;
;       G8_LDB(B1, 0, 1); G8_STAGE(G8_SB(0, 0), b2);
;       G8_BAR; G8_WAIT_L(0); G8_MMA(0, 1, At, B1); G8_BAR;
;       G8_LDA(At, 0, 1); G8_STAGE(G8_SA(0, 0), a2);
;       G8_BAR; G8_WAIT_L(0); G8_MMA(1, 0, At, B0); G8_BAR; G8_SCHED;
;       G8_STAGE(G8_SB(0, 1), b2 + hstep);
;       G8_WAIT_V(6); G8_BAR; G8_MMA(1, 1, At, B1); G8_BAR;
.LBB0_2473:
	s_add_u32 s20, s18, 0xfffc0080
	s_addc_u32 s21, s19, -1
	s_cmp_eq_u32 s51, 12
	s_cselect_b32 s23, s13, s21
	s_cselect_b32 s22, s47, s20
	s_cselect_b32 s21, s11, s50
	s_cselect_b32 s20, s48, s49
	v_lshl_add_u64 v[188:189], s[18:19], 0, v[134:135]
	s_add_i32 m0, s27, 0xc000
	ds_read_b128 v[176:179], v139
	ds_read_b128 v[180:183], v139 offset:1024
	ds_read_b128 v[184:187], v139 offset:2048
	ds_read_b128 v[202:205], v139 offset:3072
	ds_read_b128 v[206:209], v139 offset:4096
	ds_read_b128 v[210:213], v139 offset:5120
	ds_read_b128 v[214:217], v139 offset:6144
	ds_read_b128 v[218:221], v139 offset:7168
	global_load_lds_dwordx4 v[188:189], off
	v_lshl_add_u64 v[188:189], s[18:19], 0, v[136:137]
	s_add_i32 m0, s27, 0xe000
	s_nop 0
	global_load_lds_dwordx4 v[188:189], off
	s_waitcnt lgkmcnt(8)
	s_barrier
	s_waitcnt lgkmcnt(0)
	s_nop 0
	s_waitcnt lgkmcnt(0)
	v_mfma_f32_16x16x32_f16 v[126:129], v[160:163], v[176:179], v[126:129]
	v_mfma_f32_16x16x32_f16 v[122:125], v[168:171], v[176:179], v[122:125]
	v_mfma_f32_16x16x32_f16 v[110:113], v[160:163], v[184:187], v[110:113]
	v_mfma_f32_16x16x32_f16 v[106:109], v[168:171], v[184:187], v[106:109]
	v_mfma_f32_16x16x32_f16 v[94:97], v[160:163], v[206:209], v[94:97]
	v_mfma_f32_16x16x32_f16 v[90:93], v[168:171], v[206:209], v[90:93]
	v_mfma_f32_16x16x32_f16 v[78:81], v[160:163], v[214:217], v[78:81]
	v_mfma_f32_16x16x32_f16 v[74:77], v[168:171], v[214:217], v[74:77]
	v_mfma_f32_16x16x32_f16 v[126:129], v[164:167], v[180:183], v[126:129]
	v_mfma_f32_16x16x32_f16 v[122:125], v[172:175], v[180:183], v[122:125]
	v_mfma_f32_16x16x32_f16 v[110:113], v[164:167], v[202:205], v[110:113]
	v_mfma_f32_16x16x32_f16 v[106:109], v[172:175], v[202:205], v[106:109]
	v_mfma_f32_16x16x32_f16 v[94:97], v[164:167], v[210:213], v[94:97]
	v_mfma_f32_16x16x32_f16 v[90:93], v[172:175], v[210:213], v[90:93]
	v_mfma_f32_16x16x32_f16 v[78:81], v[164:167], v[218:221], v[78:81]
	v_mfma_f32_16x16x32_f16 v[74:77], v[172:175], v[218:221], v[74:77]
	s_nop 0
	s_barrier
	v_or_b32_e32 v159, 0x14000, v140
	v_add_u32_e32 v188, 0x14400, v140
	ds_read_b128 v[222:225], v159
	ds_read_b128 v[226:229], v188
	v_add_u32_e32 v159, 0x14800, v140
	v_add_u32_e32 v188, 0x14c00, v140
	s_mov_b32 m0, s28
	ds_read_b128 v[230:233], v159
	ds_read_b128 v[234:237], v188
	v_lshl_add_u64 v[188:189], s[20:21], 0, v[132:133]
	global_load_lds_dwordx4 v[188:189], off
	v_lshl_add_u64 v[238:239], s[20:21], 0, v[130:131]
	s_mov_b32 m0, s29
	s_nop 0
	global_load_lds_dwordx4 v[238:239], off
	s_barrier
	s_waitcnt lgkmcnt(0)
	s_nop 0
	s_waitcnt lgkmcnt(0)
	v_mfma_f32_16x16x32_f16 v[118:121], v[222:225], v[176:179], v[118:121]
	v_mfma_f32_16x16x32_f16 v[114:117], v[230:233], v[176:179], v[114:117]
	v_mfma_f32_16x16x32_f16 v[102:105], v[222:225], v[184:187], v[102:105]
	v_mfma_f32_16x16x32_f16 v[98:101], v[230:233], v[184:187], v[98:101]
	v_mfma_f32_16x16x32_f16 v[86:89], v[222:225], v[206:209], v[86:89]
	v_mfma_f32_16x16x32_f16 v[82:85], v[230:233], v[206:209], v[82:85]
	v_mfma_f32_16x16x32_f16 v[70:73], v[222:225], v[214:217], v[70:73]
	v_mfma_f32_16x16x32_f16 v[66:69], v[230:233], v[214:217], v[66:69]
	v_mfma_f32_16x16x32_f16 v[118:121], v[226:229], v[180:183], v[118:121]
	v_mfma_f32_16x16x32_f16 v[114:117], v[234:237], v[180:183], v[114:117]
	v_mfma_f32_16x16x32_f16 v[102:105], v[226:229], v[202:205], v[102:105]
	v_mfma_f32_16x16x32_f16 v[98:101], v[234:237], v[202:205], v[98:101]
	v_mfma_f32_16x16x32_f16 v[86:89], v[226:229], v[210:213], v[86:89]
	v_mfma_f32_16x16x32_f16 v[82:85], v[234:237], v[210:213], v[82:85]
	v_mfma_f32_16x16x32_f16 v[70:73], v[226:229], v[218:221], v[70:73]
	v_mfma_f32_16x16x32_f16 v[66:69], v[234:237], v[218:221], v[66:69]
	s_nop 0
	s_mov_b32 m0, s27
	v_lshl_add_u64 v[240:241], s[22:23], 0, v[132:133]
	s_barrier
	ds_read_b128 v[176:179], v139 offset:16384
	ds_read_b128 v[180:183], v139 offset:17408
	ds_read_b128 v[184:187], v139 offset:18432
	ds_read_b128 v[202:205], v139 offset:19456
	ds_read_b128 v[206:209], v139 offset:20480
	ds_read_b128 v[210:213], v139 offset:21504
	ds_read_b128 v[214:217], v139 offset:22528
	ds_read_b128 v[218:221], v139 offset:23552
	global_load_lds_dwordx4 v[240:241], off
	v_lshl_add_u64 v[242:243], s[22:23], 0, v[130:131]
	s_mov_b32 m0, s30
	s_nop 0
	global_load_lds_dwordx4 v[242:243], off
	s_waitcnt vmcnt(10)
	s_barrier
	s_waitcnt lgkmcnt(0)
	s_nop 0
	s_waitcnt lgkmcnt(0)
	v_mfma_f32_16x16x32_f16 v[62:65], v[160:163], v[176:179], v[62:65]
	v_mfma_f32_16x16x32_f16 v[58:61], v[168:171], v[176:179], v[58:61]
	v_mfma_f32_16x16x32_f16 v[46:49], v[160:163], v[184:187], v[46:49]
	v_mfma_f32_16x16x32_f16 v[42:45], v[168:171], v[184:187], v[42:45]
	v_mfma_f32_16x16x32_f16 v[30:33], v[160:163], v[206:209], v[30:33]
	v_mfma_f32_16x16x32_f16 v[26:29], v[168:171], v[206:209], v[26:29]
	v_mfma_f32_16x16x32_f16 v[14:17], v[160:163], v[214:217], v[14:17]
	v_mfma_f32_16x16x32_f16 v[10:13], v[168:171], v[214:217], v[10:13]
	v_mfma_f32_16x16x32_f16 v[62:65], v[164:167], v[180:183], v[62:65]
	v_mfma_f32_16x16x32_f16 v[58:61], v[172:175], v[180:183], v[58:61]
	v_mfma_f32_16x16x32_f16 v[46:49], v[164:167], v[202:205], v[46:49]
	v_mfma_f32_16x16x32_f16 v[42:45], v[172:175], v[202:205], v[42:45]
	v_mfma_f32_16x16x32_f16 v[30:33], v[164:167], v[210:213], v[30:33]
	v_mfma_f32_16x16x32_f16 v[26:29], v[172:175], v[210:213], v[26:29]
	v_mfma_f32_16x16x32_f16 v[14:17], v[164:167], v[218:221], v[14:17]
	v_mfma_f32_16x16x32_f16 v[10:13], v[172:175], v[218:221], v[10:13]
	s_nop 0
	s_barrier
; #define G8_STAGE(bufoff, gbase) do { _Pragma("unroll") for (int _i = 0; _i < 2; ++_i) \
;     __builtin_amdgcn_global_load_lds((const unsigned*)((const char*)(gbase) + voffA[_i]), (LAS unsigned*)(lds + (bufoff) + ldsw + _i * 8192), 16, 0, 0); } while (0)
; #define G8_LDA(dst, b, h) do { _Pragma("unroll") for (int m = 0; m < 4; ++m) _Pragma("unroll") for (int k = 0; k < 2; ++k) dst[m][k] = *(const LAS h16x8*)(lds + G8_SA(b, h) + aoff + m * 2048 + k * 1024); } while (0)
; #define G8_LDB(dst, b, h) do { _Pragma("unroll") for (int n = 0; n < 2; ++n) _Pragma("unroll") for (int k = 0; k < 2; ++k) dst[n][k] = *(const LAS h16x8*)(lds + G8_SB(b, h) + boff + n * 2048 + k * 1024); } while (0)
; #define G8_MMA(ai, bj, At, Bt_) do { __builtin_amdgcn_s_setprio(1); _Pragma("unroll") for (int m = 0; m < 4; ++m) _Pragma("unroll") for (int n = 0; n < 2; ++n) _Pragma("unroll") for (int k = 0; k < 2; ++k) \
;     acc[ai][bj][m][n] = __builtin_amdgcn_mfma_f32_16x16x32_f16(Bt_[n][k], At[m][k], acc[ai][bj][m][n], 0, 0, 0); __builtin_amdgcn_s_setprio(0); } while (0)
; #define G8_WAIT_V(n) asm volatile("s_waitcnt vmcnt(" #n ")" ::: "memory")
; #define G8_WAIT_L(n) asm volatile("s_waitcnt lgkmcnt(" #n ")" ::: "memory")
; #define G8_BAR __builtin_amdgcn_s_barrier()
; #define G8_SCHED __builtin_amdgcn_sched_barrier(0)
; template <class Epi>
; __device__ __forceinline__ void gemm_phase(LAS unsigned char* lds, const h16* A, const h16* Bt, int K, const Order& S, const Epi& E) {
;     ...
;       G8_LDA(At, 0, 1); G8_STAGE(G8_SA(0, 0), a2);
;       G8_BAR; G8_WAIT_L(0); G8_MMA(1, 0, At, B0); G8_BAR; G8_SCHED;
;       G8_STAGE(G8_SB(0, 1), b2 + hstep);
;       G8_WAIT_V(6); G8_BAR; G8_MMA(1, 1, At, B1); G8_BAR;
;       G8_LDB(B0, 1, 0); G8_SCHED; G8_LDA(At, 1, 0); G8_STAGE(G8_SA(0, 1), a2 + hstep);
;       G8_WAIT_L(8); G8_BAR; G8_WAIT_L(0); G8_MMA(0, 0, At, B0); G8_BAR; G8_SCHED;
;       G8_LDB(B1, 1, 1); G8_STAGE(G8_SB(1, 0), b3);
;       G8_BAR; G8_WAIT_L(0); G8_MMA(0, 1, At, B1); G8_BAR;
;       G8_LDA(At, 1, 1); G8_STAGE(G8_SA(1, 0), a3);
;       G8_BAR; G8_WAIT_L(0); G8_MMA(1, 0, At, B0); G8_BAR; G8_SCHED;
	s_add_u32 s52, s20, 0x40000
	s_addc_u32 s53, s21, 0
	s_mov_b32 m0, s31
	v_lshl_add_u64 v[160:161], s[52:53], 0, v[132:133]
	global_load_lds_dwordx4 v[160:161], off
	v_lshl_add_u64 v[160:161], s[52:53], 0, v[130:131]
	s_mov_b32 m0, s34
	s_nop 0
	global_load_lds_dwordx4 v[160:161], off
	v_or_b32_e32 v159, 0x18000, v140
	v_add_u32_e32 v164, 0x18400, v140
	ds_read_b128 v[160:163], v159
	ds_read_b128 v[164:167], v164
	v_add_u32_e32 v159, 0x18800, v140
	v_add_u32_e32 v172, 0x18c00, v140
	ds_read_b128 v[168:171], v159
	ds_read_b128 v[172:175], v172
	s_waitcnt vmcnt(6)
	s_barrier
	s_nop 0
	v_mfma_f32_16x16x32_f16 v[54:57], v[222:225], v[176:179], v[54:57]
	v_mfma_f32_16x16x32_f16 v[50:53], v[230:233], v[176:179], v[50:53]
	v_mfma_f32_16x16x32_f16 v[38:41], v[222:225], v[184:187], v[38:41]
	v_mfma_f32_16x16x32_f16 v[34:37], v[230:233], v[184:187], v[34:37]
	v_mfma_f32_16x16x32_f16 v[22:25], v[222:225], v[206:209], v[22:25]
	v_mfma_f32_16x16x32_f16 v[18:21], v[230:233], v[206:209], v[18:21]
	v_mfma_f32_16x16x32_f16 v[6:9], v[222:225], v[214:217], v[6:9]
	v_mfma_f32_16x16x32_f16 v[2:5], v[230:233], v[214:217], v[2:5]
	v_mfma_f32_16x16x32_f16 v[54:57], v[226:229], v[180:183], v[54:57]
	v_mfma_f32_16x16x32_f16 v[50:53], v[234:237], v[180:183], v[50:53]
	v_mfma_f32_16x16x32_f16 v[38:41], v[226:229], v[202:205], v[38:41]
	v_mfma_f32_16x16x32_f16 v[34:37], v[234:237], v[202:205], v[34:37]
	v_mfma_f32_16x16x32_f16 v[22:25], v[226:229], v[210:213], v[22:25]
	v_mfma_f32_16x16x32_f16 v[18:21], v[234:237], v[210:213], v[18:21]
	v_mfma_f32_16x16x32_f16 v[6:9], v[226:229], v[218:221], v[6:9]
	v_mfma_f32_16x16x32_f16 v[2:5], v[234:237], v[218:221], v[2:5]
	s_nop 0
	s_barrier
	s_add_u32 s22, s22, 0x40000
	s_addc_u32 s23, s23, 0
	s_mov_b32 m0, s35
	v_lshl_add_u64 v[222:223], s[22:23], 0, v[132:133]
	ds_read_b128 v[176:179], v139 offset:32768
	ds_read_b128 v[180:183], v139 offset:33792
	ds_read_b128 v[184:187], v139 offset:34816
	ds_read_b128 v[202:205], v139 offset:35840
	ds_read_b128 v[206:209], v139 offset:36864
	ds_read_b128 v[210:213], v139 offset:37888
	ds_read_b128 v[214:217], v139 offset:38912
	ds_read_b128 v[218:221], v139 offset:39936
	global_load_lds_dwordx4 v[222:223], off
	v_lshl_add_u64 v[222:223], s[22:23], 0, v[130:131]
	s_mov_b32 m0, s36
	s_nop 0
	global_load_lds_dwordx4 v[222:223], off
	s_waitcnt lgkmcnt(8)
	s_barrier
	s_waitcnt lgkmcnt(0)
	s_nop 0
	s_waitcnt lgkmcnt(0)
	v_mfma_f32_16x16x32_f16 v[126:129], v[160:163], v[176:179], v[126:129]
	v_mfma_f32_16x16x32_f16 v[122:125], v[168:171], v[176:179], v[122:125]
	v_mfma_f32_16x16x32_f16 v[110:113], v[160:163], v[184:187], v[110:113]
	v_mfma_f32_16x16x32_f16 v[106:109], v[168:171], v[184:187], v[106:109]
	v_mfma_f32_16x16x32_f16 v[94:97], v[160:163], v[206:209], v[94:97]
	v_mfma_f32_16x16x32_f16 v[90:93], v[168:171], v[206:209], v[90:93]
	v_mfma_f32_16x16x32_f16 v[78:81], v[160:163], v[214:217], v[78:81]
	v_mfma_f32_16x16x32_f16 v[74:77], v[168:171], v[214:217], v[74:77]
	v_mfma_f32_16x16x32_f16 v[126:129], v[164:167], v[180:183], v[126:129]
	v_mfma_f32_16x16x32_f16 v[122:125], v[172:175], v[180:183], v[122:125]
	v_mfma_f32_16x16x32_f16 v[110:113], v[164:167], v[202:205], v[110:113]
	v_mfma_f32_16x16x32_f16 v[106:109], v[172:175], v[202:205], v[106:109]
	v_mfma_f32_16x16x32_f16 v[94:97], v[164:167], v[210:213], v[94:97]
	v_mfma_f32_16x16x32_f16 v[90:93], v[172:175], v[210:213], v[90:93]
	v_mfma_f32_16x16x32_f16 v[78:81], v[164:167], v[218:221], v[78:81]
	v_mfma_f32_16x16x32_f16 v[74:77], v[172:175], v[218:221], v[74:77]
	s_nop 0
	s_barrier
	v_or_b32_e32 v159, 0x1c000, v140
	s_mov_b32 m0, s37
	v_add_u32_e32 v195, 0x1c400, v140
	ds_read_b128 v[222:225], v159
	ds_read_b128 v[226:229], v195
	v_add_u32_e32 v159, 0x1c800, v140
	v_lshl_add_u64 v[188:189], v[188:189], 0, s[94:95]
	v_add_u32_e32 v195, 0x1cc00, v140
	ds_read_b128 v[230:233], v159
	ds_read_b128 v[234:237], v195
	global_load_lds_dwordx4 v[188:189], off
	v_lshl_add_u64 v[188:189], v[238:239], 0, s[94:95]
	s_mov_b32 m0, s38
	s_nop 0
	global_load_lds_dwordx4 v[188:189], off
	s_barrier
	s_waitcnt lgkmcnt(0)
	s_nop 0
	s_waitcnt lgkmcnt(0)
	v_mfma_f32_16x16x32_f16 v[118:121], v[222:225], v[176:179], v[118:121]
	v_mfma_f32_16x16x32_f16 v[114:117], v[230:233], v[176:179], v[114:117]
	v_mfma_f32_16x16x32_f16 v[102:105], v[222:225], v[184:187], v[102:105]
	v_mfma_f32_16x16x32_f16 v[98:101], v[230:233], v[184:187], v[98:101]
	v_mfma_f32_16x16x32_f16 v[86:89], v[222:225], v[206:209], v[86:89]
	v_mfma_f32_16x16x32_f16 v[82:85], v[230:233], v[206:209], v[82:85]
	v_mfma_f32_16x16x32_f16 v[70:73], v[222:225], v[214:217], v[70:73]
	v_mfma_f32_16x16x32_f16 v[66:69], v[230:233], v[214:217], v[66:69]
	v_mfma_f32_16x16x32_f16 v[118:121], v[226:229], v[180:183], v[118:121]
	v_mfma_f32_16x16x32_f16 v[114:117], v[234:237], v[180:183], v[114:117]
	v_mfma_f32_16x16x32_f16 v[102:105], v[226:229], v[202:205], v[102:105]
	v_mfma_f32_16x16x32_f16 v[98:101], v[234:237], v[202:205], v[98:101]
	v_mfma_f32_16x16x32_f16 v[86:89], v[226:229], v[210:213], v[86:89]
	v_mfma_f32_16x16x32_f16 v[82:85], v[234:237], v[210:213], v[82:85]
	v_mfma_f32_16x16x32_f16 v[70:73], v[226:229], v[218:221], v[70:73]
	v_mfma_f32_16x16x32_f16 v[66:69], v[234:237], v[218:221], v[66:69]
	s_nop 0
	s_mov_b32 m0, s39
	v_lshl_add_u64 v[188:189], v[240:241], 0, s[94:95]
	s_barrier
	ds_read_b128 v[176:179], v139 offset:49152
	ds_read_b128 v[180:183], v139 offset:50176
	ds_read_b128 v[184:187], v139 offset:51200
	ds_read_b128 v[202:205], v139 offset:52224
	ds_read_b128 v[206:209], v139 offset:53248
	ds_read_b128 v[210:213], v139 offset:54272
	ds_read_b128 v[214:217], v139 offset:55296
	ds_read_b128 v[218:221], v139 offset:56320
	global_load_lds_dwordx4 v[188:189], off
	v_lshl_add_u64 v[188:189], v[242:243], 0, s[94:95]
	s_mov_b32 m0, s40
	s_nop 0
	global_load_lds_dwordx4 v[188:189], off
	s_waitcnt vmcnt(10)
	s_barrier
; #define G8_STAGE(bufoff, gbase) do { _Pragma("unroll") for (int _i = 0; _i < 2; ++_i) \
;     __builtin_amdgcn_global_load_lds((const unsigned*)((const char*)(gbase) + voffA[_i]), (LAS unsigned*)(lds + (bufoff) + ldsw + _i * 8192), 16, 0, 0); } while (0)
; #define G8_LDA(dst, b, h) do { _Pragma("unroll") for (int m = 0; m < 4; ++m) _Pragma("unroll") for (int k = 0; k < 2; ++k) dst[m][k] = *(const LAS h16x8*)(lds + G8_SA(b, h) + aoff + m * 2048 + k * 1024); } while (0)
; #define G8_LDB(dst, b, h) do { _Pragma("unroll") for (int n = 0; n < 2; ++n) _Pragma("unroll") for (int k = 0; k < 2; ++k) dst[n][k] = *(const LAS h16x8*)(lds + G8_SB(b, h) + boff + n * 2048 + k * 1024); } while (0)
; #define G8_WAIT_V(n) asm volatile("s_waitcnt vmcnt(" #n ")" ::: "memory")
; #define G8_WAIT_L(n) asm volatile("s_waitcnt lgkmcnt(" #n ")" ::: "memory")
; #define G8_BAR __builtin_amdgcn_s_barrier()
; #define G8_SCHED __builtin_amdgcn_sched_barrier(0)
; template <class Epi>
; __device__ __forceinline__ void gemm_phase(LAS unsigned char* lds, const h16* A, const h16* Bt, int K, const Order& S, const Epi& E) {
;     ...
;       G8_LDB(B1, 1, 1); G8_STAGE(G8_SB(1, 0), b3);
;       G8_BAR; G8_WAIT_L(0); G8_MMA(0, 1, At, B1); G8_BAR;
;       G8_LDA(At, 1, 1); G8_STAGE(G8_SA(1, 0), a3);
;       G8_BAR; G8_WAIT_L(0); G8_MMA(1, 0, At, B0); G8_BAR; G8_SCHED;
;       G8_STAGE(G8_SB(1, 1), b3 + hstep);
;       G8_WAIT_V(6); G8_BAR; G8_MMA(1, 1, At, B1); G8_BAR;
;   __device__ __forceinline__ void operator()(const f32x4 (&acc)[2][2][4][2], const g8::Unit& u, int ui, int wr, int wc, int fr, int fq) const {
; #pragma unroll
;     for (int ai = 0; ai < 2; ++ai)
; #pragma unroll
;       for (int m = 0; m < 4; ++m) {
;         const int rl = 128 * ai + 64 * wr + 16 * m + fr;
;         const float r = rsl[ui * 256 + rl];
;         h16* rowp = hid + (size_t)(u.pm * 256 + rl) * DFF + 256 * u.pn + 32 * wc + 8 * fq;
; #pragma unroll
;         for (int bj = 0; bj < 2; ++bj) {
;           f32x4 v[2];
; #pragma unroll
;           for (int n = 0; n < 2; ++n) {
;             v[n] = acc[ai][bj][m][n] * r;
; #pragma unroll
;             for (int j = 0; j < 4; ++j) { const float t = fmaxf(v[n][j], 0.f); v[n][j] = t * t; }
;           }
;           __builtin_nontemporal_store(pack8(v[0], v[1]), (h16x8*)(rowp + 128 * bj));
;         }
;       }
	s_waitcnt lgkmcnt(0)
	s_nop 0
	s_waitcnt lgkmcnt(0)
	v_mfma_f32_16x16x32_f16 v[62:65], v[160:163], v[176:179], v[62:65]
	v_mfma_f32_16x16x32_f16 v[58:61], v[168:171], v[176:179], v[58:61]
	v_mfma_f32_16x16x32_f16 v[46:49], v[160:163], v[184:187], v[46:49]
	v_mfma_f32_16x16x32_f16 v[42:45], v[168:171], v[184:187], v[42:45]
	v_mfma_f32_16x16x32_f16 v[30:33], v[160:163], v[206:209], v[30:33]
	v_mfma_f32_16x16x32_f16 v[26:29], v[168:171], v[206:209], v[26:29]
	v_mfma_f32_16x16x32_f16 v[14:17], v[160:163], v[214:217], v[14:17]
	v_mfma_f32_16x16x32_f16 v[10:13], v[168:171], v[214:217], v[10:13]
	v_mfma_f32_16x16x32_f16 v[62:65], v[164:167], v[180:183], v[62:65]
	v_mfma_f32_16x16x32_f16 v[58:61], v[172:175], v[180:183], v[58:61]
	v_mfma_f32_16x16x32_f16 v[46:49], v[164:167], v[202:205], v[46:49]
	v_mfma_f32_16x16x32_f16 v[42:45], v[172:175], v[202:205], v[42:45]
	v_mfma_f32_16x16x32_f16 v[30:33], v[164:167], v[210:213], v[30:33]
	v_mfma_f32_16x16x32_f16 v[26:29], v[172:175], v[210:213], v[26:29]
	v_mfma_f32_16x16x32_f16 v[14:17], v[164:167], v[218:221], v[14:17]
	v_mfma_f32_16x16x32_f16 v[10:13], v[172:175], v[218:221], v[10:13]
	s_nop 0
	s_barrier
	s_add_u32 s20, s20, 0x40080
	s_addc_u32 s21, s21, 0
	s_mov_b32 m0, s41
	v_lshl_add_u64 v[160:161], s[20:21], 0, v[132:133]
	global_load_lds_dwordx4 v[160:161], off
	v_lshl_add_u64 v[160:161], s[20:21], 0, v[130:131]
	s_mov_b32 m0, s42
	s_nop 0
	global_load_lds_dwordx4 v[160:161], off
	v_or_b32_e32 v159, 0x10000, v140
	v_add_u32_e32 v164, 0x10400, v140
	ds_read_b128 v[160:163], v159
	ds_read_b128 v[164:167], v164
	v_add_u32_e32 v159, 0x10800, v140
	v_add_u32_e32 v172, 0x10c00, v140
	ds_read_b128 v[168:171], v159
	ds_read_b128 v[172:175], v172
	s_waitcnt vmcnt(6)
	s_barrier
	s_nop 0
	v_mfma_f32_16x16x32_f16 v[54:57], v[222:225], v[176:179], v[54:57]
	v_mfma_f32_16x16x32_f16 v[50:53], v[230:233], v[176:179], v[50:53]
	v_mfma_f32_16x16x32_f16 v[38:41], v[222:225], v[184:187], v[38:41]
	v_mfma_f32_16x16x32_f16 v[34:37], v[230:233], v[184:187], v[34:37]
	v_mfma_f32_16x16x32_f16 v[22:25], v[222:225], v[206:209], v[22:25]
	v_mfma_f32_16x16x32_f16 v[18:21], v[230:233], v[206:209], v[18:21]
	v_mfma_f32_16x16x32_f16 v[6:9], v[222:225], v[214:217], v[6:9]
	v_mfma_f32_16x16x32_f16 v[2:5], v[230:233], v[214:217], v[2:5]
	v_mfma_f32_16x16x32_f16 v[54:57], v[226:229], v[180:183], v[54:57]
	v_mfma_f32_16x16x32_f16 v[50:53], v[234:237], v[180:183], v[50:53]
	v_mfma_f32_16x16x32_f16 v[38:41], v[226:229], v[202:205], v[38:41]
	v_mfma_f32_16x16x32_f16 v[34:37], v[234:237], v[202:205], v[34:37]
	v_mfma_f32_16x16x32_f16 v[22:25], v[226:229], v[210:213], v[22:25]
	v_mfma_f32_16x16x32_f16 v[18:21], v[234:237], v[210:213], v[18:21]
	v_mfma_f32_16x16x32_f16 v[6:9], v[226:229], v[218:221], v[6:9]
	v_mfma_f32_16x16x32_f16 v[2:5], v[234:237], v[218:221], v[2:5]
	s_nop 0
	s_add_i32 s51, s51, 2
	s_add_u32 s18, s18, 0x100
	s_addc_u32 s19, s19, 0
	s_add_u32 s49, s49, 0x100
	s_addc_u32 s50, s50, 0
	s_cmp_gt_u32 s51, 13
	s_barrier
	s_cbranch_scc0 .LBB0_2473
	s_waitcnt lgkmcnt(0)
	v_lshl_add_u32 v159, s44, 10, v158
	s_waitcnt vmcnt(0)
	ds_read2_b32 v[160:161], v159 offset1:16
	s_lshl_b32 s11, s46, 8
	v_add_u32_e32 v162, s11, v138
	s_lshl_b32 s18, s45, 8
	v_ashrrev_i32_e32 v163, 31, v162
	s_waitcnt lgkmcnt(0)
	v_pk_mul_f32 v[128:129], v[128:129], v[160:161] op_sel_hi:[1,0]
	v_pk_mul_f32 v[126:127], v[126:127], v[160:161] op_sel_hi:[1,0]
	v_pk_mul_f32 v[122:123], v[122:123], v[160:161] op_sel_hi:[1,0]
	v_max_f32_e32 v166, 0, v126
	v_max_f32_e32 v126, 0, v127
	v_max_f32_e32 v127, 0, v128
	v_max_f32_e32 v128, 0, v129
	v_pk_mul_f32 v[124:125], v[124:125], v[160:161] op_sel_hi:[1,0]
	v_max_f32_e32 v129, 0, v122
	v_max_f32_e32 v164, 0, v123
	v_pk_mul_f32 v[122:123], v[126:127], v[126:127]
	v_max_f32_e32 v165, 0, v124
	v_fma_mixlo_f16 v124, v166, v166, 0
	v_cvt_pk_f16_f32 v123, v122, v123
	s_ashr_i32 s19, s18, 31
	v_lshlrev_b64 v[162:163], 13, v[162:163]
	v_max_f32_e32 v167, 0, v125
	v_pack_b32_f16 v122, v124, v123
	v_pk_mul_f32 v[124:125], v[128:129], v[128:129]
	v_lshl_add_u64 v[162:163], s[0:1], 0, v[162:163]
	s_lshl_b64 s[18:19], s[18:19], 1
	v_cvt_pk_f16_f32 v126, v124, v125
	v_pk_mul_f32 v[124:125], v[164:165], v[164:165]
	v_lshl_add_u64 v[162:163], v[162:163], 0, s[18:19]
	v_cvt_pk_f16_f32 v125, v124, v125
	v_lshl_add_u64 v[162:163], v[162:163], 0, s[92:93]
	v_alignbit_b32 v124, v125, v126, 16
	v_lshrrev_b32_e32 v125, 16, v125
	v_lshl_add_u64 v[162:163], v[162:163], 0, v[0:1]
	v_alignbit_b32 v123, v126, v123, 16
	v_fma_mixhi_f16 v125, v167, v167, 0
	v_pk_mul_f32 v[120:121], v[120:121], v[160:161] op_sel_hi:[1,0]
	v_pk_mul_f32 v[118:119], v[118:119], v[160:161] op_sel_hi:[1,0]
	global_store_dwordx4 v[162:163], v[122:125], off nt
	v_pk_mul_f32 v[114:115], v[114:115], v[160:161] op_sel_hi:[1,0]
	v_pk_mul_f32 v[116:117], v[116:117], v[160:161] op_sel_hi:[1,0]
	v_max_f32_e32 v124, 0, v118
	v_max_f32_e32 v118, 0, v119
	v_max_f32_e32 v119, 0, v120
	v_max_f32_e32 v120, 0, v121
	v_max_f32_e32 v121, 0, v114
	v_max_f32_e32 v122, 0, v115
	v_pk_mul_f32 v[114:115], v[118:119], v[118:119]
	v_max_f32_e32 v123, 0, v116
	v_fma_mixlo_f16 v116, v124, v124, 0
	v_cvt_pk_f16_f32 v115, v114, v115
	v_max_f32_e32 v125, 0, v117
	v_pack_b32_f16 v114, v116, v115
	v_pk_mul_f32 v[116:117], v[120:121], v[120:121]
	s_and_b64 vcc, exec, s[6:7]
	v_cvt_pk_f16_f32 v118, v116, v117
	v_pk_mul_f32 v[116:117], v[122:123], v[122:123]
	v_alignbit_b32 v115, v118, v115, 16
	v_cvt_pk_f16_f32 v117, v116, v117
	v_alignbit_b32 v116, v117, v118, 16
	v_lshrrev_b32_e32 v117, 16, v117
	v_fma_mixhi_f16 v117, v125, v125, 0
	global_store_dwordx4 v[162:163], v[114:117], off offset:256 nt
;   __device__ __forceinline__ void operator()(const f32x4 (&acc)[2][2][4][2], const g8::Unit& u, int ui, int wr, int wc, int fr, int fq) const {
; #pragma unroll
;     for (int ai = 0; ai < 2; ++ai)
; #pragma unroll
;       for (int m = 0; m < 4; ++m) {
;         const int rl = 128 * ai + 64 * wr + 16 * m + fr;
;         const float r = rsl[ui * 256 + rl];
;         h16* rowp = hid + (size_t)(u.pm * 256 + rl) * DFF + 256 * u.pn + 32 * wc + 8 * fq;
; #pragma unroll
;         for (int bj = 0; bj < 2; ++bj) {
;           f32x4 v[2];
; #pragma unroll
;           for (int n = 0; n < 2; ++n) {
;             v[n] = acc[ai][bj][m][n] * r;
; #pragma unroll
;             for (int j = 0; j < 4; ++j) { const float t = fmaxf(v[n][j], 0.f); v[n][j] = t * t; }
;           }
;           __builtin_nontemporal_store(pack8(v[0], v[1]), (h16x8*)(rowp + 128 * bj));
;         }
;       }
	s_mov_b32 s45, s10
	s_mov_b32 s46, s12
	v_mov_b32_e32 v116, v161
	v_pk_mul_f32 v[110:111], v[110:111], v[116:117] op_sel_hi:[1,0]
	v_pk_mul_f32 v[112:113], v[112:113], v[116:117] op_sel_hi:[1,0]
	v_max_f32_e32 v117, 0, v110
	v_max_f32_e32 v110, 0, v111
	v_max_f32_e32 v111, 0, v112
	v_pk_mul_f32 v[106:107], v[106:107], v[116:117] op_sel_hi:[1,0]
	v_add_u32_e32 v114, s11, v141
	v_max_f32_e32 v112, 0, v113
	v_pk_mul_f32 v[108:109], v[108:109], v[116:117] op_sel_hi:[1,0]
	v_max_f32_e32 v113, 0, v106
	v_max_f32_e32 v118, 0, v107
	v_pk_mul_f32 v[106:107], v[110:111], v[110:111]
	v_ashrrev_i32_e32 v115, 31, v114
	v_max_f32_e32 v119, 0, v108
	v_fma_mixlo_f16 v108, v117, v117, 0
	v_cvt_pk_f16_f32 v107, v106, v107
	v_lshlrev_b64 v[114:115], 13, v[114:115]
	v_max_f32_e32 v120, 0, v109
	v_pack_b32_f16 v106, v108, v107
	v_pk_mul_f32 v[108:109], v[112:113], v[112:113]
	v_lshl_add_u64 v[114:115], s[0:1], 0, v[114:115]
	v_cvt_pk_f16_f32 v110, v108, v109
	v_pk_mul_f32 v[108:109], v[118:119], v[118:119]
	v_lshl_add_u64 v[114:115], v[114:115], 0, s[18:19]
	v_cvt_pk_f16_f32 v109, v108, v109
	v_lshl_add_u64 v[114:115], v[114:115], 0, s[92:93]
	v_alignbit_b32 v108, v109, v110, 16
	v_lshrrev_b32_e32 v109, 16, v109
	v_lshl_add_u64 v[114:115], v[114:115], 0, v[0:1]
	v_alignbit_b32 v107, v110, v107, 16
	v_fma_mixhi_f16 v109, v120, v120, 0
	v_pk_mul_f32 v[104:105], v[104:105], v[116:117] op_sel_hi:[1,0]
	v_pk_mul_f32 v[102:103], v[102:103], v[116:117] op_sel_hi:[1,0]
	global_store_dwordx4 v[114:115], v[106:109], off nt
	v_pk_mul_f32 v[98:99], v[98:99], v[116:117] op_sel_hi:[1,0]
	v_pk_mul_f32 v[100:101], v[100:101], v[116:117] op_sel_hi:[1,0]
	v_max_f32_e32 v108, 0, v102
	v_max_f32_e32 v102, 0, v103
	v_max_f32_e32 v103, 0, v104
	v_max_f32_e32 v104, 0, v105
	v_max_f32_e32 v105, 0, v98
	v_max_f32_e32 v106, 0, v99
	v_pk_mul_f32 v[98:99], v[102:103], v[102:103]
	v_max_f32_e32 v107, 0, v100
	v_fma_mixlo_f16 v100, v108, v108, 0
	v_cvt_pk_f16_f32 v99, v98, v99
	v_max_f32_e32 v109, 0, v101
	v_pack_b32_f16 v98, v100, v99
	v_pk_mul_f32 v[100:101], v[104:105], v[104:105]
	s_mov_b64 s[20:21], s[16:17]
	v_cvt_pk_f16_f32 v102, v100, v101
	v_pk_mul_f32 v[100:101], v[106:107], v[106:107]
	v_alignbit_b32 v99, v102, v99, 16
	v_cvt_pk_f16_f32 v101, v100, v101
	v_alignbit_b32 v100, v101, v102, 16
	v_lshrrev_b32_e32 v101, 16, v101
	v_fma_mixhi_f16 v101, v109, v109, 0
	global_store_dwordx4 v[114:115], v[98:101], off offset:256 nt
	ds_read2_b32 v[98:99], v159 offset0:32 offset1:48
	s_mov_b32 s44, s43
	v_add_u32_e32 v100, s11, v152
	v_ashrrev_i32_e32 v101, 31, v100
	v_lshlrev_b64 v[100:101], 13, v[100:101]
	s_waitcnt lgkmcnt(0)
	v_pk_mul_f32 v[96:97], v[96:97], v[98:99] op_sel_hi:[1,0]
	v_pk_mul_f32 v[94:95], v[94:95], v[98:99] op_sel_hi:[1,0]
	v_pk_mul_f32 v[90:91], v[90:91], v[98:99] op_sel_hi:[1,0]
	v_max_f32_e32 v104, 0, v94
	v_max_f32_e32 v94, 0, v95
	v_max_f32_e32 v95, 0, v96
	v_max_f32_e32 v96, 0, v97
	v_pk_mul_f32 v[92:93], v[92:93], v[98:99] op_sel_hi:[1,0]
	v_max_f32_e32 v97, 0, v90
	v_max_f32_e32 v102, 0, v91
	v_pk_mul_f32 v[90:91], v[94:95], v[94:95]
	v_max_f32_e32 v103, 0, v92
	v_fma_mixlo_f16 v92, v104, v104, 0
	v_cvt_pk_f16_f32 v91, v90, v91
	v_max_f32_e32 v105, 0, v93
	v_pack_b32_f16 v90, v92, v91
	v_pk_mul_f32 v[92:93], v[96:97], v[96:97]
	v_lshl_add_u64 v[100:101], s[0:1], 0, v[100:101]
	v_cvt_pk_f16_f32 v94, v92, v93
	v_pk_mul_f32 v[92:93], v[102:103], v[102:103]
	v_lshl_add_u64 v[100:101], v[100:101], 0, s[18:19]
	v_cvt_pk_f16_f32 v93, v92, v93
	v_lshl_add_u64 v[100:101], v[100:101], 0, s[92:93]
	v_alignbit_b32 v92, v93, v94, 16
	v_lshrrev_b32_e32 v93, 16, v93
	v_lshl_add_u64 v[100:101], v[100:101], 0, v[0:1]
	v_alignbit_b32 v91, v94, v91, 16
	v_fma_mixhi_f16 v93, v105, v105, 0
	v_pk_mul_f32 v[88:89], v[88:89], v[98:99] op_sel_hi:[1,0]
	v_pk_mul_f32 v[86:87], v[86:87], v[98:99] op_sel_hi:[1,0]
	global_store_dwordx4 v[100:101], v[90:93], off nt
	v_pk_mul_f32 v[82:83], v[82:83], v[98:99] op_sel_hi:[1,0]
	v_pk_mul_f32 v[84:85], v[84:85], v[98:99] op_sel_hi:[1,0]
	v_max_f32_e32 v92, 0, v86
	v_max_f32_e32 v86, 0, v87
	v_max_f32_e32 v87, 0, v88
	v_max_f32_e32 v88, 0, v89
	v_max_f32_e32 v89, 0, v82
	v_max_f32_e32 v90, 0, v83
	v_pk_mul_f32 v[82:83], v[86:87], v[86:87]
	v_max_f32_e32 v91, 0, v84
	v_fma_mixlo_f16 v84, v92, v92, 0
	v_cvt_pk_f16_f32 v83, v82, v83
	v_max_f32_e32 v93, 0, v85
	v_pack_b32_f16 v82, v84, v83
	v_pk_mul_f32 v[84:85], v[88:89], v[88:89]
	s_nop 0
	v_cvt_pk_f16_f32 v86, v84, v85
	v_pk_mul_f32 v[84:85], v[90:91], v[90:91]
	v_alignbit_b32 v83, v86, v83, 16
	v_cvt_pk_f16_f32 v85, v84, v85
	v_alignbit_b32 v84, v85, v86, 16
	v_lshrrev_b32_e32 v85, 16, v85
	v_fma_mixhi_f16 v85, v93, v93, 0
	global_store_dwordx4 v[100:101], v[82:85], off offset:256 nt
	s_nop 1
	v_mov_b32_e32 v84, v99
	v_pk_mul_f32 v[78:79], v[78:79], v[84:85] op_sel_hi:[1,0]
	v_pk_mul_f32 v[80:81], v[80:81], v[84:85] op_sel_hi:[1,0]
	v_max_f32_e32 v85, 0, v78
	v_max_f32_e32 v78, 0, v79
	v_max_f32_e32 v79, 0, v80
	v_pk_mul_f32 v[74:75], v[74:75], v[84:85] op_sel_hi:[1,0]
	v_add_u32_e32 v82, s11, v153
	v_max_f32_e32 v80, 0, v81
	v_pk_mul_f32 v[76:77], v[76:77], v[84:85] op_sel_hi:[1,0]
	v_max_f32_e32 v81, 0, v74
	v_max_f32_e32 v86, 0, v75
	v_pk_mul_f32 v[74:75], v[78:79], v[78:79]
	v_ashrrev_i32_e32 v83, 31, v82
	v_max_f32_e32 v87, 0, v76
	v_fma_mixlo_f16 v76, v85, v85, 0
	v_cvt_pk_f16_f32 v75, v74, v75
	v_lshlrev_b64 v[82:83], 13, v[82:83]
	v_max_f32_e32 v88, 0, v77
	v_pack_b32_f16 v74, v76, v75
	v_pk_mul_f32 v[76:77], v[80:81], v[80:81]
	v_lshl_add_u64 v[82:83], s[0:1], 0, v[82:83]
	v_cvt_pk_f16_f32 v78, v76, v77
	v_pk_mul_f32 v[76:77], v[86:87], v[86:87]
	v_lshl_add_u64 v[82:83], v[82:83], 0, s[18:19]
	v_cvt_pk_f16_f32 v77, v76, v77
	v_lshl_add_u64 v[82:83], v[82:83], 0, s[92:93]
	v_alignbit_b32 v76, v77, v78, 16
	v_lshrrev_b32_e32 v77, 16, v77
	v_lshl_add_u64 v[82:83], v[82:83], 0, v[0:1]
	v_alignbit_b32 v75, v78, v75, 16
	v_fma_mixhi_f16 v77, v88, v88, 0
	v_pk_mul_f32 v[72:73], v[72:73], v[84:85] op_sel_hi:[1,0]
	v_pk_mul_f32 v[70:71], v[70:71], v[84:85] op_sel_hi:[1,0]
	global_store_dwordx4 v[82:83], v[74:77], off nt
	v_pk_mul_f32 v[66:67], v[66:67], v[84:85] op_sel_hi:[1,0]
	v_pk_mul_f32 v[68:69], v[68:69], v[84:85] op_sel_hi:[1,0]
	v_max_f32_e32 v76, 0, v70
	v_max_f32_e32 v70, 0, v71
	v_max_f32_e32 v71, 0, v72
	v_max_f32_e32 v72, 0, v73
	v_max_f32_e32 v73, 0, v66
	v_max_f32_e32 v74, 0, v67
	v_pk_mul_f32 v[66:67], v[70:71], v[70:71]
	v_max_f32_e32 v75, 0, v68
	v_fma_mixlo_f16 v68, v76, v76, 0
	v_cvt_pk_f16_f32 v67, v66, v67
	v_max_f32_e32 v77, 0, v69
	v_pack_b32_f16 v66, v68, v67
	v_pk_mul_f32 v[68:69], v[72:73], v[72:73]
	s_nop 0
	v_cvt_pk_f16_f32 v70, v68, v69
	v_pk_mul_f32 v[68:69], v[74:75], v[74:75]
	v_alignbit_b32 v67, v70, v67, 16
	v_cvt_pk_f16_f32 v69, v68, v69
	v_alignbit_b32 v68, v69, v70, 16
	v_lshrrev_b32_e32 v69, 16, v69
	v_fma_mixhi_f16 v69, v77, v77, 0
	global_store_dwordx4 v[82:83], v[66:69], off offset:256 nt
	ds_read2_b32 v[66:67], v159 offset0:128 offset1:144
	s_waitcnt lgkmcnt(0)
;   __device__ __forceinline__ void operator()(const f32x4 (&acc)[2][2][4][2], const g8::Unit& u, int ui, int wr, int wc, int fr, int fq) const {
; #pragma unroll
;     for (int ai = 0; ai < 2; ++ai)
; #pragma unroll
;       for (int m = 0; m < 4; ++m) {
;         const int rl = 128 * ai + 64 * wr + 16 * m + fr;
;         const float r = rsl[ui * 256 + rl];
;         h16* rowp = hid + (size_t)(u.pm * 256 + rl) * DFF + 256 * u.pn + 32 * wc + 8 * fq;
; #pragma unroll
;         for (int bj = 0; bj < 2; ++bj) {
;           f32x4 v[2];
; #pragma unroll
;           for (int n = 0; n < 2; ++n) {
;             v[n] = acc[ai][bj][m][n] * r;
; #pragma unroll
;             for (int j = 0; j < 4; ++j) { const float t = fmaxf(v[n][j], 0.f); v[n][j] = t * t; }
;           }
;           __builtin_nontemporal_store(pack8(v[0], v[1]), (h16x8*)(rowp + 128 * bj));
;         }
;       }
	v_pk_mul_f32 v[64:65], v[64:65], v[66:67] op_sel_hi:[1,0]
	v_pk_mul_f32 v[62:63], v[62:63], v[66:67] op_sel_hi:[1,0]
	v_pk_mul_f32 v[58:59], v[58:59], v[66:67] op_sel_hi:[1,0]
	v_max_f32_e32 v72, 0, v62
	v_max_f32_e32 v62, 0, v63
	v_max_f32_e32 v63, 0, v64
	v_add_u32_e32 v68, s11, v154
	v_max_f32_e32 v64, 0, v65
	v_pk_mul_f32 v[60:61], v[60:61], v[66:67] op_sel_hi:[1,0]
	v_max_f32_e32 v65, 0, v58
	v_max_f32_e32 v70, 0, v59
	v_pk_mul_f32 v[58:59], v[62:63], v[62:63]
	v_ashrrev_i32_e32 v69, 31, v68
	v_max_f32_e32 v71, 0, v60
	v_fma_mixlo_f16 v60, v72, v72, 0
	v_cvt_pk_f16_f32 v59, v58, v59
	v_lshlrev_b64 v[68:69], 13, v[68:69]
	v_max_f32_e32 v73, 0, v61
	v_pack_b32_f16 v58, v60, v59
	v_pk_mul_f32 v[60:61], v[64:65], v[64:65]
	v_lshl_add_u64 v[68:69], s[0:1], 0, v[68:69]
	v_cvt_pk_f16_f32 v62, v60, v61
	v_pk_mul_f32 v[60:61], v[70:71], v[70:71]
	v_lshl_add_u64 v[68:69], v[68:69], 0, s[18:19]
	v_cvt_pk_f16_f32 v61, v60, v61
	v_lshl_add_u64 v[68:69], v[68:69], 0, s[92:93]
	v_alignbit_b32 v60, v61, v62, 16
	v_lshrrev_b32_e32 v61, 16, v61
	v_lshl_add_u64 v[68:69], v[68:69], 0, v[0:1]
	v_alignbit_b32 v59, v62, v59, 16
	v_fma_mixhi_f16 v61, v73, v73, 0
	v_pk_mul_f32 v[56:57], v[56:57], v[66:67] op_sel_hi:[1,0]
	v_pk_mul_f32 v[54:55], v[54:55], v[66:67] op_sel_hi:[1,0]
	global_store_dwordx4 v[68:69], v[58:61], off nt
	v_pk_mul_f32 v[50:51], v[50:51], v[66:67] op_sel_hi:[1,0]
	v_pk_mul_f32 v[52:53], v[52:53], v[66:67] op_sel_hi:[1,0]
	v_max_f32_e32 v60, 0, v54
	v_max_f32_e32 v54, 0, v55
	v_max_f32_e32 v55, 0, v56
	v_max_f32_e32 v56, 0, v57
	v_max_f32_e32 v57, 0, v50
	v_max_f32_e32 v58, 0, v51
	v_pk_mul_f32 v[50:51], v[54:55], v[54:55]
	v_max_f32_e32 v59, 0, v52
	v_fma_mixlo_f16 v52, v60, v60, 0
	v_cvt_pk_f16_f32 v51, v50, v51
	v_max_f32_e32 v61, 0, v53
	v_pack_b32_f16 v50, v52, v51
	v_pk_mul_f32 v[52:53], v[56:57], v[56:57]
	s_nop 0
	v_cvt_pk_f16_f32 v54, v52, v53
	v_pk_mul_f32 v[52:53], v[58:59], v[58:59]
	v_alignbit_b32 v51, v54, v51, 16
	v_cvt_pk_f16_f32 v53, v52, v53
	v_alignbit_b32 v52, v53, v54, 16
	v_lshrrev_b32_e32 v53, 16, v53
	v_fma_mixhi_f16 v53, v61, v61, 0
	global_store_dwordx4 v[68:69], v[50:53], off offset:256 nt
	s_nop 1
	v_mov_b32_e32 v52, v67
	v_pk_mul_f32 v[46:47], v[46:47], v[52:53] op_sel_hi:[1,0]
	v_pk_mul_f32 v[48:49], v[48:49], v[52:53] op_sel_hi:[1,0]
	v_max_f32_e32 v53, 0, v46
	v_max_f32_e32 v46, 0, v47
	v_max_f32_e32 v47, 0, v48
	v_pk_mul_f32 v[42:43], v[42:43], v[52:53] op_sel_hi:[1,0]
	v_add_u32_e32 v50, s11, v155
	v_max_f32_e32 v48, 0, v49
	v_pk_mul_f32 v[44:45], v[44:45], v[52:53] op_sel_hi:[1,0]
	v_max_f32_e32 v49, 0, v42
	v_max_f32_e32 v54, 0, v43
	v_pk_mul_f32 v[42:43], v[46:47], v[46:47]
	v_ashrrev_i32_e32 v51, 31, v50
	v_max_f32_e32 v55, 0, v44
	v_fma_mixlo_f16 v44, v53, v53, 0
	v_cvt_pk_f16_f32 v43, v42, v43
	v_lshlrev_b64 v[50:51], 13, v[50:51]
	v_max_f32_e32 v56, 0, v45
	v_pack_b32_f16 v42, v44, v43
	v_pk_mul_f32 v[44:45], v[48:49], v[48:49]
	v_lshl_add_u64 v[50:51], s[0:1], 0, v[50:51]
	v_cvt_pk_f16_f32 v46, v44, v45
	v_pk_mul_f32 v[44:45], v[54:55], v[54:55]
	v_lshl_add_u64 v[50:51], v[50:51], 0, s[18:19]
	v_cvt_pk_f16_f32 v45, v44, v45
	v_lshl_add_u64 v[50:51], v[50:51], 0, s[92:93]
	v_alignbit_b32 v44, v45, v46, 16
	v_lshrrev_b32_e32 v45, 16, v45
	v_lshl_add_u64 v[50:51], v[50:51], 0, v[0:1]
	v_alignbit_b32 v43, v46, v43, 16
	v_fma_mixhi_f16 v45, v56, v56, 0
	v_pk_mul_f32 v[40:41], v[40:41], v[52:53] op_sel_hi:[1,0]
	v_pk_mul_f32 v[38:39], v[38:39], v[52:53] op_sel_hi:[1,0]
	global_store_dwordx4 v[50:51], v[42:45], off nt
	v_pk_mul_f32 v[34:35], v[34:35], v[52:53] op_sel_hi:[1,0]
	v_pk_mul_f32 v[36:37], v[36:37], v[52:53] op_sel_hi:[1,0]
	v_max_f32_e32 v44, 0, v38
	v_max_f32_e32 v38, 0, v39
	v_max_f32_e32 v39, 0, v40
	v_max_f32_e32 v40, 0, v41
	v_max_f32_e32 v41, 0, v34
	v_max_f32_e32 v42, 0, v35
	v_pk_mul_f32 v[34:35], v[38:39], v[38:39]
	v_max_f32_e32 v43, 0, v36
	v_fma_mixlo_f16 v36, v44, v44, 0
	v_cvt_pk_f16_f32 v35, v34, v35
	v_max_f32_e32 v45, 0, v37
	v_pack_b32_f16 v34, v36, v35
	v_pk_mul_f32 v[36:37], v[40:41], v[40:41]
	s_nop 0
	v_cvt_pk_f16_f32 v38, v36, v37
	v_pk_mul_f32 v[36:37], v[42:43], v[42:43]
	v_alignbit_b32 v35, v38, v35, 16
	v_cvt_pk_f16_f32 v37, v36, v37
	v_alignbit_b32 v36, v37, v38, 16
	v_lshrrev_b32_e32 v37, 16, v37
	v_fma_mixhi_f16 v37, v45, v45, 0
	global_store_dwordx4 v[50:51], v[34:37], off offset:256 nt
	ds_read2_b32 v[34:35], v159 offset0:160 offset1:176
	s_waitcnt lgkmcnt(0)
; #define G8_WAIT_V(n) asm volatile("s_waitcnt vmcnt(" #n ")" ::: "memory")
; #define G8_BAR __builtin_amdgcn_s_barrier()
; template <class Epi>
; __device__ __forceinline__ void gemm_phase(LAS unsigned char* lds, const h16* A, const h16* Bt, int K, const Order& S, const Epi& E) {
;     ...
;     E(acc, cur, ui, wr, wc, fr, fq);
;     if (!has_next) break;
; #pragma unroll
;     for (int a = 0; a < 2; ++a)
; #pragma unroll
;       for (int b = 0; b < 2; ++b)
; #pragma unroll
;         for (int m = 0; m < 4; ++m)
; #pragma unroll
;           for (int n = 0; n < 2; ++n) acc[a][b][m][n] = (f32x4){0.f, 0.f, 0.f, 0.f};
;     cur = nxt; cA = nA; cB = nB; ++ui;
;   }
;   G8_WAIT_V(0);
;   if (wr == 0) G8_BAR;
;   G8_BAR;
;   __device__ __forceinline__ void operator()(const f32x4 (&acc)[2][2][4][2], const g8::Unit& u, int ui, int wr, int wc, int fr, int fq) const {
; #pragma unroll
;     for (int ai = 0; ai < 2; ++ai)
; #pragma unroll
;       for (int m = 0; m < 4; ++m) {
;         const int rl = 128 * ai + 64 * wr + 16 * m + fr;
;         const float r = rsl[ui * 256 + rl];
;         h16* rowp = hid + (size_t)(u.pm * 256 + rl) * DFF + 256 * u.pn + 32 * wc + 8 * fq;
; #pragma unroll
;         for (int bj = 0; bj < 2; ++bj) {
;           f32x4 v[2];
; #pragma unroll
;           for (int n = 0; n < 2; ++n) {
;             v[n] = acc[ai][bj][m][n] * r;
; #pragma unroll
;             for (int j = 0; j < 4; ++j) { const float t = fmaxf(v[n][j], 0.f); v[n][j] = t * t; }
;           }
;           __builtin_nontemporal_store(pack8(v[0], v[1]), (h16x8*)(rowp + 128 * bj));
;         }
;       }
;   }
	v_pk_mul_f32 v[32:33], v[32:33], v[34:35] op_sel_hi:[1,0]
	v_pk_mul_f32 v[30:31], v[30:31], v[34:35] op_sel_hi:[1,0]
	v_pk_mul_f32 v[26:27], v[26:27], v[34:35] op_sel_hi:[1,0]
	v_max_f32_e32 v40, 0, v30
	v_max_f32_e32 v30, 0, v31
	v_max_f32_e32 v31, 0, v32
	v_add_u32_e32 v36, s11, v156
	v_max_f32_e32 v32, 0, v33
	v_pk_mul_f32 v[28:29], v[28:29], v[34:35] op_sel_hi:[1,0]
	v_max_f32_e32 v33, 0, v26
	v_max_f32_e32 v38, 0, v27
	v_pk_mul_f32 v[26:27], v[30:31], v[30:31]
	v_ashrrev_i32_e32 v37, 31, v36
	v_max_f32_e32 v39, 0, v28
	v_fma_mixlo_f16 v28, v40, v40, 0
	v_cvt_pk_f16_f32 v27, v26, v27
	v_lshlrev_b64 v[36:37], 13, v[36:37]
	v_max_f32_e32 v41, 0, v29
	v_pack_b32_f16 v26, v28, v27
	v_pk_mul_f32 v[28:29], v[32:33], v[32:33]
	v_lshl_add_u64 v[36:37], s[0:1], 0, v[36:37]
	v_cvt_pk_f16_f32 v30, v28, v29
	v_pk_mul_f32 v[28:29], v[38:39], v[38:39]
	v_lshl_add_u64 v[36:37], v[36:37], 0, s[18:19]
	v_cvt_pk_f16_f32 v29, v28, v29
	v_lshl_add_u64 v[36:37], v[36:37], 0, s[92:93]
	v_alignbit_b32 v28, v29, v30, 16
	v_lshrrev_b32_e32 v29, 16, v29
	v_lshl_add_u64 v[36:37], v[36:37], 0, v[0:1]
	v_alignbit_b32 v27, v30, v27, 16
	v_fma_mixhi_f16 v29, v41, v41, 0
	v_pk_mul_f32 v[24:25], v[24:25], v[34:35] op_sel_hi:[1,0]
	v_pk_mul_f32 v[22:23], v[22:23], v[34:35] op_sel_hi:[1,0]
	global_store_dwordx4 v[36:37], v[26:29], off nt
	v_pk_mul_f32 v[18:19], v[18:19], v[34:35] op_sel_hi:[1,0]
	v_pk_mul_f32 v[20:21], v[20:21], v[34:35] op_sel_hi:[1,0]
	v_max_f32_e32 v28, 0, v22
	v_max_f32_e32 v22, 0, v23
	v_max_f32_e32 v23, 0, v24
	v_max_f32_e32 v24, 0, v25
	v_max_f32_e32 v25, 0, v18
	v_max_f32_e32 v26, 0, v19
	v_pk_mul_f32 v[18:19], v[22:23], v[22:23]
	v_max_f32_e32 v27, 0, v20
	v_fma_mixlo_f16 v20, v28, v28, 0
	v_cvt_pk_f16_f32 v19, v18, v19
	v_max_f32_e32 v29, 0, v21
	v_pack_b32_f16 v18, v20, v19
	v_pk_mul_f32 v[20:21], v[24:25], v[24:25]
	s_nop 0
	v_cvt_pk_f16_f32 v22, v20, v21
	v_pk_mul_f32 v[20:21], v[26:27], v[26:27]
	v_alignbit_b32 v19, v22, v19, 16
	v_cvt_pk_f16_f32 v21, v20, v21
	v_alignbit_b32 v20, v21, v22, 16
	v_lshrrev_b32_e32 v21, 16, v21
	v_fma_mixhi_f16 v21, v29, v29, 0
	global_store_dwordx4 v[36:37], v[18:21], off offset:256 nt
	s_nop 1
	v_mov_b32_e32 v20, v35
	v_pk_mul_f32 v[14:15], v[14:15], v[20:21] op_sel_hi:[1,0]
	v_pk_mul_f32 v[16:17], v[16:17], v[20:21] op_sel_hi:[1,0]
	v_max_f32_e32 v21, 0, v14
	v_max_f32_e32 v14, 0, v15
	v_max_f32_e32 v15, 0, v16
	v_pk_mul_f32 v[10:11], v[10:11], v[20:21] op_sel_hi:[1,0]
	v_add_u32_e32 v18, s11, v157
	v_max_f32_e32 v16, 0, v17
	v_pk_mul_f32 v[12:13], v[12:13], v[20:21] op_sel_hi:[1,0]
	v_max_f32_e32 v17, 0, v10
	v_max_f32_e32 v22, 0, v11
	v_pk_mul_f32 v[10:11], v[14:15], v[14:15]
	v_ashrrev_i32_e32 v19, 31, v18
	v_max_f32_e32 v23, 0, v12
	v_fma_mixlo_f16 v12, v21, v21, 0
	v_cvt_pk_f16_f32 v11, v10, v11
	v_lshlrev_b64 v[18:19], 13, v[18:19]
	v_max_f32_e32 v24, 0, v13
	v_pack_b32_f16 v10, v12, v11
	v_pk_mul_f32 v[12:13], v[16:17], v[16:17]
	v_lshl_add_u64 v[18:19], s[0:1], 0, v[18:19]
	v_cvt_pk_f16_f32 v14, v12, v13
	v_pk_mul_f32 v[12:13], v[22:23], v[22:23]
	v_lshl_add_u64 v[18:19], v[18:19], 0, s[18:19]
	v_cvt_pk_f16_f32 v13, v12, v13
	v_lshl_add_u64 v[18:19], v[18:19], 0, s[92:93]
	v_alignbit_b32 v12, v13, v14, 16
	v_lshrrev_b32_e32 v13, 16, v13
	v_lshl_add_u64 v[18:19], v[18:19], 0, v[0:1]
	v_alignbit_b32 v11, v14, v11, 16
	v_fma_mixhi_f16 v13, v24, v24, 0
	v_pk_mul_f32 v[8:9], v[8:9], v[20:21] op_sel_hi:[1,0]
	v_pk_mul_f32 v[6:7], v[6:7], v[20:21] op_sel_hi:[1,0]
	global_store_dwordx4 v[18:19], v[10:13], off nt
	v_pk_mul_f32 v[2:3], v[2:3], v[20:21] op_sel_hi:[1,0]
	v_pk_mul_f32 v[4:5], v[4:5], v[20:21] op_sel_hi:[1,0]
	v_max_f32_e32 v12, 0, v6
	v_max_f32_e32 v6, 0, v7
	v_max_f32_e32 v7, 0, v8
	v_max_f32_e32 v8, 0, v9
	v_max_f32_e32 v9, 0, v2
	v_max_f32_e32 v10, 0, v3
	v_pk_mul_f32 v[2:3], v[6:7], v[6:7]
	v_max_f32_e32 v11, 0, v4
	v_fma_mixlo_f16 v4, v12, v12, 0
	v_cvt_pk_f16_f32 v3, v2, v3
	v_max_f32_e32 v13, 0, v5
	v_pack_b32_f16 v2, v4, v3
	v_pk_mul_f32 v[4:5], v[8:9], v[8:9]
	s_mov_b64 s[18:19], s[14:15]
	v_cvt_pk_f16_f32 v6, v4, v5
	v_pk_mul_f32 v[4:5], v[10:11], v[10:11]
	v_alignbit_b32 v3, v6, v3, 16
	v_cvt_pk_f16_f32 v5, v4, v5
	v_alignbit_b32 v4, v5, v6, 16
	v_lshrrev_b32_e32 v5, 16, v5
	v_fma_mixhi_f16 v5, v13, v13, 0
	global_store_dwordx4 v[18:19], v[2:5], off offset:256 nt
	s_cbranch_vccz .LBB0_2466
	s_waitcnt vmcnt(0)
	s_cmpk_gt_u32 s2, 0xff
	s_cbranch_scc1 .LBB0_2477
	s_barrier

; #define G8_STAGE(bufoff, gbase) do { _Pragma("unroll") for (int _i = 0; _i < 2; ++_i) \
;     __builtin_amdgcn_global_load_lds((const unsigned*)((const char*)(gbase) + voffA[_i]), (LAS unsigned*)(lds + (bufoff) + ldsw + _i * 8192), 16, 0, 0); } while (0)
; #define G8_LDA(dst, b, h) do { _Pragma("unroll") for (int m = 0; m < 4; ++m) _Pragma("unroll") for (int k = 0; k < 2; ++k) dst[m][k] = *(const LAS h16x8*)(lds + G8_SA(b, h) + aoff + m * 2048 + k * 1024); } while (0)
; #define G8_LDB(dst, b, h) do { _Pragma("unroll") for (int n = 0; n < 2; ++n) _Pragma("unroll") for (int k = 0; k < 2; ++k) dst[n][k] = *(const LAS h16x8*)(lds + G8_SB(b, h) + boff + n * 2048 + k * 1024); } while (0)
; #define G8_MMA(ai, bj, At, Bt_) do { __builtin_amdgcn_s_setprio(1); _Pragma("unroll") for (int m = 0; m < 4; ++m) _Pragma("unroll") for (int n = 0; n < 2; ++n) _Pragma("unroll") for (int k = 0; k < 2; ++k) \
;     acc[ai][bj][m][n] = __builtin_amdgcn_mfma_f32_16x16x32_f16(Bt_[n][k], At[m][k], acc[ai][bj][m][n], 0, 0, 0); __builtin_amdgcn_s_setprio(0); } while (0)
; #define G8_WAIT_L(n) asm volatile("s_waitcnt lgkmcnt(" #n ")" ::: "memory")
; #define G8_BAR __builtin_amdgcn_s_barrier()
; #define G8_SCHED __builtin_amdgcn_sched_barrier(0)
; template <class Epi>
; __device__ __forceinline__ void gemm_phase(LAS unsigned char* lds, const h16* A, const h16* Bt, int K, const Order& S, const Epi& E) {
;     ...
;       const bool last = (t == nt - 2);
;       const char* a1 = cA + (size_t)(t + 1) * kstep;
;       const char* a2 = last ? nA : cA + (size_t)(t + 2) * kstep;
;       const char* b2 = last ? nB : cB + (size_t)(t + 2) * kstep;
;       const char* a3 = a2 + kstep;
;       const char* b3 = b2 + kstep;
;       if (Epi::MID_T >= 0 && t == Epi::MID_T) E.mid(acc, ui, wr, fr);
;       G8_LDB(B0, 0, 0); G8_SCHED; G8_LDA(At, 0, 0); G8_STAGE(G8_SA(1, 1), a1 + hstep);
;       G8_WAIT_L(8); G8_BAR; G8_WAIT_L(0); G8_MMA(0, 0, At, B0); G8_BAR; G8_SCHED;
;       G8_LDB(B1, 0, 1); G8_STAGE(G8_SB(0, 0), b2);
;       G8_BAR; G8_WAIT_L(0); G8_MMA(0, 1, At, B1); G8_BAR;
;       G8_LDA(At, 0, 1); G8_STAGE(G8_SA(0, 0), a2);
;       G8_BAR; G8_WAIT_L(0); G8_MMA(1, 0, At, B0); G8_BAR; G8_SCHED;
.LBB0_2542:
	s_add_u32 s24, s22, 0xfff00080
	s_addc_u32 s25, s23, -1
	s_cmp_eq_u32 s53, 60
	s_cselect_b32 s27, s3, s25
	s_cselect_b32 s26, s9, s24
	s_cselect_b32 s25, s15, s52
	s_cselect_b32 s24, s17, s51
	v_lshl_add_u64 v[140:141], s[22:23], 0, v[136:137]
	s_add_i32 m0, s35, 0xc000
	ds_read_b128 v[172:175], v135
	ds_read_b128 v[176:179], v135 offset:1024
	ds_read_b128 v[180:183], v135 offset:2048
	ds_read_b128 v[184:187], v135 offset:3072
	ds_read_b128 v[202:205], v135 offset:4096
	ds_read_b128 v[206:209], v135 offset:5120
	ds_read_b128 v[210:213], v135 offset:6144
	ds_read_b128 v[214:217], v135 offset:7168
	global_load_lds_dwordx4 v[140:141], off
	v_lshl_add_u64 v[140:141], s[22:23], 0, v[138:139]
	s_add_i32 m0, s35, 0xe000
	s_nop 0
	global_load_lds_dwordx4 v[140:141], off
	s_waitcnt lgkmcnt(8)
	s_barrier
	s_waitcnt lgkmcnt(0)
	s_nop 0
	s_waitcnt lgkmcnt(0)
	v_mfma_f32_16x16x32_f16 v[126:129], v[152:155], v[172:175], v[126:129]
	v_mfma_f32_16x16x32_f16 v[122:125], v[164:167], v[172:175], v[122:125]
	v_mfma_f32_16x16x32_f16 v[110:113], v[152:155], v[180:183], v[110:113]
	v_mfma_f32_16x16x32_f16 v[106:109], v[164:167], v[180:183], v[106:109]
	v_mfma_f32_16x16x32_f16 v[94:97], v[152:155], v[202:205], v[94:97]
	v_mfma_f32_16x16x32_f16 v[90:93], v[164:167], v[202:205], v[90:93]
	v_mfma_f32_16x16x32_f16 v[78:81], v[152:155], v[210:213], v[78:81]
	v_mfma_f32_16x16x32_f16 v[74:77], v[164:167], v[210:213], v[74:77]
	v_mfma_f32_16x16x32_f16 v[126:129], v[160:163], v[176:179], v[126:129]
	v_mfma_f32_16x16x32_f16 v[122:125], v[168:171], v[176:179], v[122:125]
	v_mfma_f32_16x16x32_f16 v[110:113], v[160:163], v[184:187], v[110:113]
	v_mfma_f32_16x16x32_f16 v[106:109], v[168:171], v[184:187], v[106:109]
	v_mfma_f32_16x16x32_f16 v[94:97], v[160:163], v[206:209], v[94:97]
	v_mfma_f32_16x16x32_f16 v[90:93], v[168:171], v[206:209], v[90:93]
	v_mfma_f32_16x16x32_f16 v[78:81], v[160:163], v[214:217], v[78:81]
	v_mfma_f32_16x16x32_f16 v[74:77], v[168:171], v[214:217], v[74:77]
	s_nop 0
	s_barrier
	v_or_b32_e32 v140, 0x14000, v158
	v_add_u32_e32 v141, 0x14400, v158
	ds_read_b128 v[218:221], v140
	ds_read_b128 v[222:225], v141
	v_add_u32_e32 v140, 0x14800, v158
	v_add_u32_e32 v141, 0x14c00, v158
	s_mov_b32 m0, s36
	ds_read_b128 v[226:229], v140
	ds_read_b128 v[230:233], v141
	v_lshl_add_u64 v[140:141], s[24:25], 0, v[0:1]
	global_load_lds_dwordx4 v[140:141], off
	v_lshl_add_u64 v[156:157], s[24:25], 0, v[130:131]
	s_mov_b32 m0, s37
	s_nop 0
	global_load_lds_dwordx4 v[156:157], off
	s_barrier
	s_waitcnt lgkmcnt(0)
	s_nop 0
	s_waitcnt lgkmcnt(0)
	v_mfma_f32_16x16x32_f16 v[118:121], v[218:221], v[172:175], v[118:121]
	v_mfma_f32_16x16x32_f16 v[114:117], v[226:229], v[172:175], v[114:117]
	v_mfma_f32_16x16x32_f16 v[102:105], v[218:221], v[180:183], v[102:105]
	v_mfma_f32_16x16x32_f16 v[98:101], v[226:229], v[180:183], v[98:101]
	v_mfma_f32_16x16x32_f16 v[86:89], v[218:221], v[202:205], v[86:89]
	v_mfma_f32_16x16x32_f16 v[82:85], v[226:229], v[202:205], v[82:85]
	v_mfma_f32_16x16x32_f16 v[70:73], v[218:221], v[210:213], v[70:73]
	v_mfma_f32_16x16x32_f16 v[66:69], v[226:229], v[210:213], v[66:69]
	v_mfma_f32_16x16x32_f16 v[118:121], v[222:225], v[176:179], v[118:121]
	v_mfma_f32_16x16x32_f16 v[114:117], v[230:233], v[176:179], v[114:117]
	v_mfma_f32_16x16x32_f16 v[102:105], v[222:225], v[184:187], v[102:105]
	v_mfma_f32_16x16x32_f16 v[98:101], v[230:233], v[184:187], v[98:101]
	v_mfma_f32_16x16x32_f16 v[86:89], v[222:225], v[206:209], v[86:89]
	v_mfma_f32_16x16x32_f16 v[82:85], v[230:233], v[206:209], v[82:85]
	v_mfma_f32_16x16x32_f16 v[70:73], v[222:225], v[214:217], v[70:73]
	v_mfma_f32_16x16x32_f16 v[66:69], v[230:233], v[214:217], v[66:69]
	s_nop 0
	s_mov_b32 m0, s35
	v_lshl_add_u64 v[188:189], s[26:27], 0, v[0:1]
	s_barrier
	ds_read_b128 v[172:175], v135 offset:16384
	ds_read_b128 v[176:179], v135 offset:17408
	ds_read_b128 v[180:183], v135 offset:18432
	ds_read_b128 v[184:187], v135 offset:19456
	ds_read_b128 v[202:205], v135 offset:20480
	ds_read_b128 v[206:209], v135 offset:21504
	ds_read_b128 v[210:213], v135 offset:22528
	ds_read_b128 v[214:217], v135 offset:23552
	global_load_lds_dwordx4 v[188:189], off
	v_lshl_add_u64 v[234:235], s[26:27], 0, v[130:131]
	s_mov_b32 m0, s38
	s_nop 0
	global_load_lds_dwordx4 v[234:235], off
	s_waitcnt vmcnt(10)
	s_barrier
	s_waitcnt lgkmcnt(0)
	s_nop 0
	s_waitcnt lgkmcnt(0)
	v_mfma_f32_16x16x32_f16 v[62:65], v[152:155], v[172:175], v[62:65]
	v_mfma_f32_16x16x32_f16 v[58:61], v[164:167], v[172:175], v[58:61]
	v_mfma_f32_16x16x32_f16 v[46:49], v[152:155], v[180:183], v[46:49]
	v_mfma_f32_16x16x32_f16 v[42:45], v[164:167], v[180:183], v[42:45]
	v_mfma_f32_16x16x32_f16 v[30:33], v[152:155], v[202:205], v[30:33]
	v_mfma_f32_16x16x32_f16 v[26:29], v[164:167], v[202:205], v[26:29]
	v_mfma_f32_16x16x32_f16 v[14:17], v[152:155], v[210:213], v[14:17]
	v_mfma_f32_16x16x32_f16 v[10:13], v[164:167], v[210:213], v[10:13]
	v_mfma_f32_16x16x32_f16 v[62:65], v[160:163], v[176:179], v[62:65]
	v_mfma_f32_16x16x32_f16 v[58:61], v[168:171], v[176:179], v[58:61]
	v_mfma_f32_16x16x32_f16 v[46:49], v[160:163], v[184:187], v[46:49]
	v_mfma_f32_16x16x32_f16 v[42:45], v[168:171], v[184:187], v[42:45]
	v_mfma_f32_16x16x32_f16 v[30:33], v[160:163], v[206:209], v[30:33]
	v_mfma_f32_16x16x32_f16 v[26:29], v[168:171], v[206:209], v[26:29]
	v_mfma_f32_16x16x32_f16 v[14:17], v[160:163], v[214:217], v[14:17]
	v_mfma_f32_16x16x32_f16 v[10:13], v[168:171], v[214:217], v[10:13]
	s_nop 0
	s_barrier
; #define G8_STAGE(bufoff, gbase) do { _Pragma("unroll") for (int _i = 0; _i < 2; ++_i) \
;     __builtin_amdgcn_global_load_lds((const unsigned*)((const char*)(gbase) + voffA[_i]), (LAS unsigned*)(lds + (bufoff) + ldsw + _i * 8192), 16, 0, 0); } while (0)
; #define G8_LDA(dst, b, h) do { _Pragma("unroll") for (int m = 0; m < 4; ++m) _Pragma("unroll") for (int k = 0; k < 2; ++k) dst[m][k] = *(const LAS h16x8*)(lds + G8_SA(b, h) + aoff + m * 2048 + k * 1024); } while (0)
; #define G8_LDB(dst, b, h) do { _Pragma("unroll") for (int n = 0; n < 2; ++n) _Pragma("unroll") for (int k = 0; k < 2; ++k) dst[n][k] = *(const LAS h16x8*)(lds + G8_SB(b, h) + boff + n * 2048 + k * 1024); } while (0)
; #define G8_MMA(ai, bj, At, Bt_) do { __builtin_amdgcn_s_setprio(1); _Pragma("unroll") for (int m = 0; m < 4; ++m) _Pragma("unroll") for (int n = 0; n < 2; ++n) _Pragma("unroll") for (int k = 0; k < 2; ++k) \
;     acc[ai][bj][m][n] = __builtin_amdgcn_mfma_f32_16x16x32_f16(Bt_[n][k], At[m][k], acc[ai][bj][m][n], 0, 0, 0); __builtin_amdgcn_s_setprio(0); } while (0)
; #define G8_WAIT_V(n) asm volatile("s_waitcnt vmcnt(" #n ")" ::: "memory")
; #define G8_WAIT_L(n) asm volatile("s_waitcnt lgkmcnt(" #n ")" ::: "memory")
; #define G8_BAR __builtin_amdgcn_s_barrier()
; #define G8_SCHED __builtin_amdgcn_sched_barrier(0)
; template <class Epi>
; __device__ __forceinline__ void gemm_phase(LAS unsigned char* lds, const h16* A, const h16* Bt, int K, const Order& S, const Epi& E) {
;     ...
;       G8_STAGE(G8_SB(0, 1), b2 + hstep);
;       G8_WAIT_V(6); G8_BAR; G8_MMA(1, 1, At, B1); G8_BAR;
;       G8_LDB(B0, 1, 0); G8_SCHED; G8_LDA(At, 1, 0); G8_STAGE(G8_SA(0, 1), a2 + hstep);
;       G8_WAIT_L(8); G8_BAR; G8_WAIT_L(0); G8_MMA(0, 0, At, B0); G8_BAR; G8_SCHED;
;       G8_LDB(B1, 1, 1); G8_STAGE(G8_SB(1, 0), b3);
;       G8_BAR; G8_WAIT_L(0); G8_MMA(0, 1, At, B1); G8_BAR;
;       G8_LDA(At, 1, 1); G8_STAGE(G8_SA(1, 0), a3);
;       G8_BAR; G8_WAIT_L(0); G8_MMA(1, 0, At, B0); G8_BAR; G8_SCHED;
	s_add_u32 s54, s24, 0x100000
	s_addc_u32 s55, s25, 0
	s_mov_b32 m0, s39
	v_lshl_add_u64 v[152:153], s[54:55], 0, v[0:1]
	global_load_lds_dwordx4 v[152:153], off
	v_lshl_add_u64 v[152:153], s[54:55], 0, v[130:131]
	s_mov_b32 m0, s40
	s_nop 0
	global_load_lds_dwordx4 v[152:153], off
	v_or_b32_e32 v152, 0x18000, v158
	v_add_u32_e32 v159, 0x18400, v158
	ds_read_b128 v[152:155], v152
	ds_read_b128 v[160:163], v159
	v_add_u32_e32 v159, 0x18800, v158
	v_add_u32_e32 v168, 0x18c00, v158
	ds_read_b128 v[164:167], v159
	ds_read_b128 v[168:171], v168
	s_waitcnt vmcnt(6)
	s_barrier
	s_nop 0
	v_mfma_f32_16x16x32_f16 v[54:57], v[218:221], v[172:175], v[54:57]
	v_mfma_f32_16x16x32_f16 v[50:53], v[226:229], v[172:175], v[50:53]
	v_mfma_f32_16x16x32_f16 v[38:41], v[218:221], v[180:183], v[38:41]
	v_mfma_f32_16x16x32_f16 v[34:37], v[226:229], v[180:183], v[34:37]
	v_mfma_f32_16x16x32_f16 v[22:25], v[218:221], v[202:205], v[22:25]
	v_mfma_f32_16x16x32_f16 v[18:21], v[226:229], v[202:205], v[18:21]
	v_mfma_f32_16x16x32_f16 v[6:9], v[218:221], v[210:213], v[6:9]
	v_mfma_f32_16x16x32_f16 v[2:5], v[226:229], v[210:213], v[2:5]
	v_mfma_f32_16x16x32_f16 v[54:57], v[222:225], v[176:179], v[54:57]
	v_mfma_f32_16x16x32_f16 v[50:53], v[230:233], v[176:179], v[50:53]
	v_mfma_f32_16x16x32_f16 v[38:41], v[222:225], v[184:187], v[38:41]
	v_mfma_f32_16x16x32_f16 v[34:37], v[230:233], v[184:187], v[34:37]
	v_mfma_f32_16x16x32_f16 v[22:25], v[222:225], v[206:209], v[22:25]
	v_mfma_f32_16x16x32_f16 v[18:21], v[230:233], v[206:209], v[18:21]
	v_mfma_f32_16x16x32_f16 v[6:9], v[222:225], v[214:217], v[6:9]
	v_mfma_f32_16x16x32_f16 v[2:5], v[230:233], v[214:217], v[2:5]
	s_nop 0
	s_barrier
	s_add_u32 s26, s26, 0x100000
	s_addc_u32 s27, s27, 0
	s_mov_b32 m0, s41
	v_lshl_add_u64 v[218:219], s[26:27], 0, v[0:1]
	ds_read_b128 v[172:175], v135 offset:32768
	ds_read_b128 v[176:179], v135 offset:33792
	ds_read_b128 v[180:183], v135 offset:34816
	ds_read_b128 v[184:187], v135 offset:35840
	ds_read_b128 v[202:205], v135 offset:36864
	ds_read_b128 v[206:209], v135 offset:37888
	ds_read_b128 v[210:213], v135 offset:38912
	ds_read_b128 v[214:217], v135 offset:39936
	global_load_lds_dwordx4 v[218:219], off
	v_lshl_add_u64 v[218:219], s[26:27], 0, v[130:131]
	s_mov_b32 m0, s42
	s_nop 0
	global_load_lds_dwordx4 v[218:219], off
	s_waitcnt lgkmcnt(8)
	s_barrier
	s_waitcnt lgkmcnt(0)
	s_nop 0
	s_waitcnt lgkmcnt(0)
	v_mfma_f32_16x16x32_f16 v[126:129], v[152:155], v[172:175], v[126:129]
	v_mfma_f32_16x16x32_f16 v[122:125], v[164:167], v[172:175], v[122:125]
	v_mfma_f32_16x16x32_f16 v[110:113], v[152:155], v[180:183], v[110:113]
	v_mfma_f32_16x16x32_f16 v[106:109], v[164:167], v[180:183], v[106:109]
	v_mfma_f32_16x16x32_f16 v[94:97], v[152:155], v[202:205], v[94:97]
	v_mfma_f32_16x16x32_f16 v[90:93], v[164:167], v[202:205], v[90:93]
	v_mfma_f32_16x16x32_f16 v[78:81], v[152:155], v[210:213], v[78:81]
	v_mfma_f32_16x16x32_f16 v[74:77], v[164:167], v[210:213], v[74:77]
	v_mfma_f32_16x16x32_f16 v[126:129], v[160:163], v[176:179], v[126:129]
	v_mfma_f32_16x16x32_f16 v[122:125], v[168:171], v[176:179], v[122:125]
	v_mfma_f32_16x16x32_f16 v[110:113], v[160:163], v[184:187], v[110:113]
	v_mfma_f32_16x16x32_f16 v[106:109], v[168:171], v[184:187], v[106:109]
	v_mfma_f32_16x16x32_f16 v[94:97], v[160:163], v[206:209], v[94:97]
	v_mfma_f32_16x16x32_f16 v[90:93], v[168:171], v[206:209], v[90:93]
	v_mfma_f32_16x16x32_f16 v[78:81], v[160:163], v[214:217], v[78:81]
	v_mfma_f32_16x16x32_f16 v[74:77], v[168:171], v[214:217], v[74:77]
	s_nop 0
	s_barrier
	v_or_b32_e32 v159, 0x1c000, v158
	s_mov_b32 m0, s44
	v_add_u32_e32 v195, 0x1c400, v158
	ds_read_b128 v[218:221], v159
	ds_read_b128 v[222:225], v195
	v_add_u32_e32 v159, 0x1c800, v158
	v_lshl_add_u64 v[140:141], v[140:141], 0, s[94:95]
	v_add_u32_e32 v195, 0x1cc00, v158
	ds_read_b128 v[226:229], v159
	ds_read_b128 v[230:233], v195
	global_load_lds_dwordx4 v[140:141], off
	v_lshl_add_u64 v[140:141], v[156:157], 0, s[94:95]
	s_mov_b32 m0, s45
	s_nop 0
	global_load_lds_dwordx4 v[140:141], off
	s_barrier
	s_waitcnt lgkmcnt(0)
	s_nop 0
	s_waitcnt lgkmcnt(0)
	v_mfma_f32_16x16x32_f16 v[118:121], v[218:221], v[172:175], v[118:121]
	v_mfma_f32_16x16x32_f16 v[114:117], v[226:229], v[172:175], v[114:117]
	v_mfma_f32_16x16x32_f16 v[102:105], v[218:221], v[180:183], v[102:105]
	v_mfma_f32_16x16x32_f16 v[98:101], v[226:229], v[180:183], v[98:101]
	v_mfma_f32_16x16x32_f16 v[86:89], v[218:221], v[202:205], v[86:89]
	v_mfma_f32_16x16x32_f16 v[82:85], v[226:229], v[202:205], v[82:85]
	v_mfma_f32_16x16x32_f16 v[70:73], v[218:221], v[210:213], v[70:73]
	v_mfma_f32_16x16x32_f16 v[66:69], v[226:229], v[210:213], v[66:69]
	v_mfma_f32_16x16x32_f16 v[118:121], v[222:225], v[176:179], v[118:121]
	v_mfma_f32_16x16x32_f16 v[114:117], v[230:233], v[176:179], v[114:117]
	v_mfma_f32_16x16x32_f16 v[102:105], v[222:225], v[184:187], v[102:105]
	v_mfma_f32_16x16x32_f16 v[98:101], v[230:233], v[184:187], v[98:101]
	v_mfma_f32_16x16x32_f16 v[86:89], v[222:225], v[206:209], v[86:89]
	v_mfma_f32_16x16x32_f16 v[82:85], v[230:233], v[206:209], v[82:85]
	v_mfma_f32_16x16x32_f16 v[70:73], v[222:225], v[214:217], v[70:73]
	v_mfma_f32_16x16x32_f16 v[66:69], v[230:233], v[214:217], v[66:69]
	s_nop 0
	s_mov_b32 m0, s46
	v_lshl_add_u64 v[140:141], v[188:189], 0, s[94:95]
	s_barrier
	ds_read_b128 v[172:175], v135 offset:49152
	ds_read_b128 v[176:179], v135 offset:50176
	ds_read_b128 v[180:183], v135 offset:51200
	ds_read_b128 v[184:187], v135 offset:52224
	ds_read_b128 v[202:205], v135 offset:53248
	ds_read_b128 v[206:209], v135 offset:54272
	ds_read_b128 v[210:213], v135 offset:55296
	ds_read_b128 v[214:217], v135 offset:56320
	global_load_lds_dwordx4 v[140:141], off
	v_lshl_add_u64 v[140:141], v[234:235], 0, s[94:95]
	s_mov_b32 m0, s47
	s_nop 0
	global_load_lds_dwordx4 v[140:141], off
	s_waitcnt vmcnt(10)
	s_barrier
; #define G8_STAGE(bufoff, gbase) do { _Pragma("unroll") for (int _i = 0; _i < 2; ++_i) \
;     __builtin_amdgcn_global_load_lds((const unsigned*)((const char*)(gbase) + voffA[_i]), (LAS unsigned*)(lds + (bufoff) + ldsw + _i * 8192), 16, 0, 0); } while (0)
; #define G8_MMA(ai, bj, At, Bt_) do { __builtin_amdgcn_s_setprio(1); _Pragma("unroll") for (int m = 0; m < 4; ++m) _Pragma("unroll") for (int n = 0; n < 2; ++n) _Pragma("unroll") for (int k = 0; k < 2; ++k) \
;     acc[ai][bj][m][n] = __builtin_amdgcn_mfma_f32_16x16x32_f16(Bt_[n][k], At[m][k], acc[ai][bj][m][n], 0, 0, 0); __builtin_amdgcn_s_setprio(0); } while (0)
; #define G8_WAIT_V(n) asm volatile("s_waitcnt vmcnt(" #n ")" ::: "memory")
; #define G8_WAIT_L(n) asm volatile("s_waitcnt lgkmcnt(" #n ")" ::: "memory")
; #define G8_BAR __builtin_amdgcn_s_barrier()
; #define G8_SCHED __builtin_amdgcn_sched_barrier(0)
; template <class Epi>
; __device__ __forceinline__ void gemm_phase(LAS unsigned char* lds, const h16* A, const h16* Bt, int K, const Order& S, const Epi& E) {
;     ...
;       G8_BAR; G8_WAIT_L(0); G8_MMA(1, 0, At, B0); G8_BAR; G8_SCHED;
;       G8_STAGE(G8_SB(1, 1), b3 + hstep);
;       G8_WAIT_V(6); G8_BAR; G8_MMA(1, 1, At, B1); G8_BAR;
;     }
;   __device__ __forceinline__ void operator()(const f32x4 (&acc)[2][2][4][2], const g8::Unit& u, int ui, int wr, int wc, int fr, int fq) const {
; #pragma unroll
;     for (int ai = 0; ai < 2; ++ai)
; #pragma unroll
;       for (int m = 0; m < 4; ++m) {
;         const size_t row = (size_t)u.pm * 256 + 128 * ai + 64 * wr + 16 * m + fr;
;         const size_t base = row * DM + 256 * u.pn + 32 * wc + 8 * fq;
;         float ss = 0.f;
; #pragma unroll
;         for (int bj = 0; bj < 2; ++bj) {
;           const size_t idx = base + 128 * bj;
;           const h16x8 xv = *(const h16x8*)(xb + idx);
;           f32x4 x0 = acc[ai][bj][m][0], x1 = acc[ai][bj][m][1];
; #pragma unroll
;           for (int j = 0; j < 4; ++j) { x0[j] += (float)xv[j]; x1[j] += (float)xv[4 + j]; ss += x0[j] * x0[j] + x1[j] * x1[j]; }
;           if (final_out) {
;             __builtin_nontemporal_store(x0, (f32x4*)(xo + idx));
;             __builtin_nontemporal_store(x1, (f32x4*)(xo + idx + 4));
;           } else {
;             *(h16x8*)(xb + idx) = pack8(x0, x1);
	s_waitcnt lgkmcnt(0)
	s_nop 0
	s_waitcnt lgkmcnt(0)
	v_mfma_f32_16x16x32_f16 v[62:65], v[152:155], v[172:175], v[62:65]
	v_mfma_f32_16x16x32_f16 v[58:61], v[164:167], v[172:175], v[58:61]
	v_mfma_f32_16x16x32_f16 v[46:49], v[152:155], v[180:183], v[46:49]
	v_mfma_f32_16x16x32_f16 v[42:45], v[164:167], v[180:183], v[42:45]
	v_mfma_f32_16x16x32_f16 v[30:33], v[152:155], v[202:205], v[30:33]
	v_mfma_f32_16x16x32_f16 v[26:29], v[164:167], v[202:205], v[26:29]
	v_mfma_f32_16x16x32_f16 v[14:17], v[152:155], v[210:213], v[14:17]
	v_mfma_f32_16x16x32_f16 v[10:13], v[164:167], v[210:213], v[10:13]
	v_mfma_f32_16x16x32_f16 v[62:65], v[160:163], v[176:179], v[62:65]
	v_mfma_f32_16x16x32_f16 v[58:61], v[168:171], v[176:179], v[58:61]
	v_mfma_f32_16x16x32_f16 v[46:49], v[160:163], v[184:187], v[46:49]
	v_mfma_f32_16x16x32_f16 v[42:45], v[168:171], v[184:187], v[42:45]
	v_mfma_f32_16x16x32_f16 v[30:33], v[160:163], v[206:209], v[30:33]
	v_mfma_f32_16x16x32_f16 v[26:29], v[168:171], v[206:209], v[26:29]
	v_mfma_f32_16x16x32_f16 v[14:17], v[160:163], v[214:217], v[14:17]
	v_mfma_f32_16x16x32_f16 v[10:13], v[168:171], v[214:217], v[10:13]
	s_nop 0
	s_barrier
	s_add_u32 s24, s24, 0x100080
	s_addc_u32 s25, s25, 0
	s_mov_b32 m0, s48
	v_lshl_add_u64 v[140:141], s[24:25], 0, v[0:1]
	global_load_lds_dwordx4 v[140:141], off
	v_lshl_add_u64 v[140:141], s[24:25], 0, v[130:131]
	s_mov_b32 m0, s49
	s_nop 0
	global_load_lds_dwordx4 v[140:141], off
	v_or_b32_e32 v140, 0x10000, v158
	v_add_u32_e32 v141, 0x10400, v158
	ds_read_b128 v[152:155], v140
	ds_read_b128 v[160:163], v141
	v_add_u32_e32 v140, 0x10800, v158
	v_add_u32_e32 v141, 0x10c00, v158
	ds_read_b128 v[164:167], v140
	ds_read_b128 v[168:171], v141
	s_waitcnt vmcnt(6)
	s_barrier
	s_nop 0
	v_mfma_f32_16x16x32_f16 v[54:57], v[218:221], v[172:175], v[54:57]
	v_mfma_f32_16x16x32_f16 v[50:53], v[226:229], v[172:175], v[50:53]
	v_mfma_f32_16x16x32_f16 v[38:41], v[218:221], v[180:183], v[38:41]
	v_mfma_f32_16x16x32_f16 v[34:37], v[226:229], v[180:183], v[34:37]
	v_mfma_f32_16x16x32_f16 v[22:25], v[218:221], v[202:205], v[22:25]
	v_mfma_f32_16x16x32_f16 v[18:21], v[226:229], v[202:205], v[18:21]
	v_mfma_f32_16x16x32_f16 v[6:9], v[218:221], v[210:213], v[6:9]
	v_mfma_f32_16x16x32_f16 v[2:5], v[226:229], v[210:213], v[2:5]
	v_mfma_f32_16x16x32_f16 v[54:57], v[222:225], v[176:179], v[54:57]
	v_mfma_f32_16x16x32_f16 v[50:53], v[230:233], v[176:179], v[50:53]
	v_mfma_f32_16x16x32_f16 v[38:41], v[222:225], v[184:187], v[38:41]
	v_mfma_f32_16x16x32_f16 v[34:37], v[230:233], v[184:187], v[34:37]
	v_mfma_f32_16x16x32_f16 v[22:25], v[222:225], v[206:209], v[22:25]
	v_mfma_f32_16x16x32_f16 v[18:21], v[230:233], v[206:209], v[18:21]
	v_mfma_f32_16x16x32_f16 v[6:9], v[222:225], v[214:217], v[6:9]
	v_mfma_f32_16x16x32_f16 v[2:5], v[230:233], v[214:217], v[2:5]
	s_nop 0
	s_add_i32 s53, s53, 2
	s_add_u32 s22, s22, 0x100
	s_addc_u32 s23, s23, 0
	s_add_u32 s51, s51, 0x100
	s_addc_u32 s52, s52, 0
	s_cmp_gt_u32 s53, 61
	s_barrier
	s_cbranch_scc0 .LBB0_2542
	s_waitcnt lgkmcnt(0)
	s_ashr_i32 s9, s8, 31
	s_lshl_b64 s[8:9], s[8:9], 8
	s_lshl_b32 s3, s2, 8
	v_lshl_add_u64 v[140:141], s[8:9], 0, v[132:133]
	s_ashr_i32 s8, s3, 31
	v_mov_b32_e32 v153, s8
	v_or_b32_e32 v152, s3, v134
	v_lshlrev_b64 v[154:155], 10, v[140:141]
	v_lshl_add_u64 v[156:157], v[154:155], 0, v[152:153]
	v_lshl_add_u64 v[154:155], v[156:157], 1, s[10:11]
	global_load_dwordx4 v[166:169], v[154:155], off
	global_load_dwordx4 v[170:173], v[154:155], off offset:256
	s_mov_b32 s9, 0
	s_mov_b32 s8, 0x8000
	v_lshl_add_u64 v[234:235], v[154:155], 0, s[8:9]
	global_load_dwordx4 v[174:177], v[234:235], off
	global_load_dwordx4 v[178:181], v[234:235], off offset:256
	s_mov_b32 s8, 0x10000
	v_lshl_add_u64 v[234:235], v[154:155], 0, s[8:9]
	global_load_dwordx4 v[182:185], v[234:235], off
	global_load_dwordx4 v[186:189], v[234:235], off offset:256
	s_mov_b32 s8, 0x18000
	v_lshl_add_u64 v[234:235], v[154:155], 0, s[8:9]
	global_load_dwordx4 v[202:205], v[234:235], off
	global_load_dwordx4 v[206:209], v[234:235], off offset:256
	s_mov_b32 s8, 0x40000
	v_lshl_add_u64 v[234:235], v[154:155], 0, s[8:9]
	global_load_dwordx4 v[210:213], v[234:235], off
	global_load_dwordx4 v[214:217], v[234:235], off offset:256
	s_mov_b32 s8, 0x48000
	v_lshl_add_u64 v[234:235], v[154:155], 0, s[8:9]
	global_load_dwordx4 v[218:221], v[234:235], off
	global_load_dwordx4 v[222:225], v[234:235], off offset:256
	s_mov_b32 s8, 0x50000
	v_lshl_add_u64 v[234:235], v[154:155], 0, s[8:9]
	global_load_dwordx4 v[226:229], v[234:235], off
	global_load_dwordx4 v[230:233], v[234:235], off offset:256
	s_mov_b64 s[8:9], -1
	s_and_b64 vcc, exec, s[0:1]
	s_waitcnt vmcnt(13)
	v_cvt_f32_f16_e32 v164, v166
	v_cvt_f32_f16_sdwa v165, v166 dst_sel:DWORD dst_unused:UNUSED_PAD src0_sel:WORD_1
	v_cvt_f32_f16_e32 v160, v167
	v_cvt_f32_f16_sdwa v161, v167 dst_sel:DWORD dst_unused:UNUSED_PAD src0_sel:WORD_1
	v_pk_add_f32 v[126:127], v[126:127], v[164:165]
	v_cvt_f32_f16_e32 v164, v168
	v_cvt_f32_f16_sdwa v165, v168 dst_sel:DWORD dst_unused:UNUSED_PAD src0_sel:WORD_1
	v_pk_add_f32 v[128:129], v[128:129], v[160:161]
	v_cvt_f32_f16_e32 v160, v169
	v_cvt_f32_f16_sdwa v161, v169 dst_sel:DWORD dst_unused:UNUSED_PAD src0_sel:WORD_1
	v_pk_add_f32 v[122:123], v[122:123], v[164:165]
	v_pk_add_f32 v[124:125], v[124:125], v[160:161]
	s_cbranch_vccz .LBB0_2545
	v_cvt_pk_f16_f32 v163, v124, v125
	v_cvt_pk_f16_f32 v162, v122, v123
	v_cvt_pk_f16_f32 v161, v128, v129
	v_cvt_pk_f16_f32 v160, v126, v127
	global_store_dwordx4 v[154:155], v[160:163], off
	s_mov_b64 s[8:9], 0
